# removed the now-dead lgkmcnt waits in the DPP-converted P1/P6 epilogues (kept as s_nop where a VALU-SGPR/transcendental producer sits within 2 slots)
# speedup vs baseline: 1.0075x; 1.0075x over previous
; __device__ __forceinline__ unsigned cvt_pk_bf16(float lo, float hi) { unsigned r; asm volatile("v_cvt_pk_bf16_f32 %0, %1, %2" : "=v"(r) : "v"(lo), "v"(hi)); return r; }
;     __device__ __forceinline__ void operator()(EPI_ARGS) const {
;     ...
;                             for (int j = 0; j < 4; ++j) { r1[j] = __shfl(gv[j], s1); r2[j] = __shfl(gv[j], s2); r3[j] = __shfl(gv[j], s3); }
; #pragma unroll
;                             for (int j = 0; j < 4; ++j) { p1[j] = fr >= 1 ? r1[j] : q1[n][j]; p2[j] = fr >= 2 ? r2[j] : q2[n][j]; p3[j] = fr >= 3 ? r3[j] : q3[n][j]; }
;                             q1[n] = r1; q2[n] = r2; q3[n] = r3;
;                             o[n] = bb[n] + w0[n] * p3 + w1[n] * p2 + w2[n] * p1 + w3[n] * gv;
;                             if (m == 0 && fr < 3) *(f32x4*)(headu + ((size_t)blk * 3 + fr) * LW + c0 + 4 * n) = gv;
;                             if (m == 3 && fr >= 13) *(f32x4*)(tailu + ((size_t)blk * 3 + (fr - 13)) * LW + c0 + 4 * n) = gv;
;                         }
;                         if (!(m == 0 && fr < 3)) {
;                             u32x4 w; w.x = cvt_pk_bf16(o[0][0], o[0][1]); w.y = cvt_pk_bf16(o[0][2], o[0][3]); w.z = cvt_pk_bf16(o[1][0], o[1][1]); w.w = cvt_pk_bf16(o[1][2], o[1][3]);
;                             *(u32x4*)(vout + (size_t)row * LW + c0) = w;
.LBB0_138:
	s_or_b64 exec, exec, s[0:1]
	s_nop 1
	v_mov_b32_dpp v194, v120 row_ror:1 row_mask:0xf bank_mask:0xf
	v_mov_b32_dpp v198, v120 row_ror:2 row_mask:0xf bank_mask:0xf
	v_mov_b32_dpp v202, v120 row_ror:3 row_mask:0xf bank_mask:0xf
	v_mov_b32_dpp v195, v121 row_ror:1 row_mask:0xf bank_mask:0xf
	v_mov_b32_dpp v199, v121 row_ror:2 row_mask:0xf bank_mask:0xf
	v_mov_b32_dpp v203, v121 row_ror:3 row_mask:0xf bank_mask:0xf
	v_mov_b32_dpp v196, v122 row_ror:1 row_mask:0xf bank_mask:0xf
	v_mov_b32_dpp v200, v122 row_ror:2 row_mask:0xf bank_mask:0xf
	v_mov_b32_dpp v204, v122 row_ror:3 row_mask:0xf bank_mask:0xf
	v_mov_b32_dpp v197, v123 row_ror:1 row_mask:0xf bank_mask:0xf
	v_mov_b32_dpp v201, v123 row_ror:2 row_mask:0xf bank_mask:0xf
	v_mov_b32_dpp v205, v123 row_ror:3 row_mask:0xf bank_mask:0xf
	s_lshl_b32 s0, s12, 8
	s_add_i32 s0, s0, s24
	v_add_u32_e32 v186, s0, v182
	v_cmp_lt_i32_e32 vcc, 0, v182
	v_cmp_lt_i32_e64 s[0:1], 1, v182
	v_cmp_lt_i32_e64 s[4:5], 2, v182
	v_ashrrev_i32_e32 v187, 31, v186
	s_and_saveexec_b64 s[6:7], s[8:9]
	s_xor_b64 s[6:7], exec, s[6:7]
	s_cbranch_execz .LBB0_140
	v_cndmask_b32_e64 v236, 0, v221, s[4:5]
	v_cndmask_b32_e64 v237, 0, v224, s[4:5]
	v_cndmask_b32_e64 v234, 0, v220, s[0:1]
	v_cndmask_b32_e64 v235, 0, v223, s[0:1]
	v_cndmask_b32_e64 v242, 0, v227, s[4:5]
	v_cndmask_b32_e64 v243, 0, v230, s[4:5]
	s_waitcnt vmcnt(0)
	v_pk_fma_f32 v[236:237], v[140:141], v[236:237], v[144:145]
	v_cndmask_b32_e32 v232, 0, v219, vcc
	v_cndmask_b32_e32 v233, 0, v222, vcc
	v_cndmask_b32_e64 v240, 0, v226, s[0:1]
	v_cndmask_b32_e64 v241, 0, v229, s[0:1]
	v_pk_fma_f32 v[242:243], v[142:143], v[242:243], v[146:147]
	v_pk_fma_f32 v[234:235], v[136:137], v[234:235], v[236:237]
	v_cndmask_b32_e32 v238, 0, v225, vcc
	v_cndmask_b32_e32 v239, 0, v228, vcc
	v_pk_fma_f32 v[240:241], v[138:139], v[240:241], v[242:243]
	v_pk_fma_f32 v[232:233], v[132:133], v[232:233], v[234:235]
	v_pk_fma_f32 v[234:235], v[134:135], v[238:239], v[240:241]
	v_pk_fma_f32 v[124:125], v[124:125], v[128:129], v[232:233]
	v_pk_fma_f32 v[232:233], v[162:163], v[204:205], v[166:167]
	v_pk_fma_f32 v[126:127], v[126:127], v[130:131], v[234:235]
	v_pk_fma_f32 v[234:235], v[160:161], v[202:203], v[164:165]
	v_pk_fma_f32 v[232:233], v[158:159], v[200:201], v[232:233]
	v_pk_fma_f32 v[234:235], v[156:157], v[198:199], v[234:235]
	v_pk_fma_f32 v[232:233], v[154:155], v[196:197], v[232:233]
	v_pk_fma_f32 v[234:235], v[152:153], v[194:195], v[234:235]
	v_pk_fma_f32 v[232:233], v[122:123], v[150:151], v[232:233]
	v_pk_fma_f32 v[234:235], v[120:121], v[148:149], v[234:235]
	v_cvt_pk_bf16_f32 v124, v124, v125
	v_cvt_pk_bf16_f32 v125, v126, v127
	s_nop 0
	v_cvt_pk_bf16_f32 v126, v234, v235
	v_cvt_pk_bf16_f32 v127, v232, v233
	v_lshlrev_b64 v[232:233], 12, v[186:187]
	v_lshl_add_u64 v[232:233], s[54:55], 0, v[232:233]
	v_lshl_add_u64 v[232:233], v[184:185], 1, v[232:233]
	global_store_dwordx4 v[232:233], v[124:127], off

; __device__ __forceinline__ unsigned cvt_pk_bf16(float lo, float hi) { unsigned r; asm volatile("v_cvt_pk_bf16_f32 %0, %1, %2" : "=v"(r) : "v"(lo), "v"(hi)); return r; }
;     __device__ __forceinline__ void operator()(EPI_ARGS) const {
;     ...
;                             for (int j = 0; j < 4; ++j) { r1[j] = __shfl(gv[j], s1); r2[j] = __shfl(gv[j], s2); r3[j] = __shfl(gv[j], s3); }
; #pragma unroll
;                             for (int j = 0; j < 4; ++j) { p1[j] = fr >= 1 ? r1[j] : q1[n][j]; p2[j] = fr >= 2 ? r2[j] : q2[n][j]; p3[j] = fr >= 3 ? r3[j] : q3[n][j]; }
;                             q1[n] = r1; q2[n] = r2; q3[n] = r3;
;                             o[n] = bb[n] + w0[n] * p3 + w1[n] * p2 + w2[n] * p1 + w3[n] * gv;
;                             if (m == 0 && fr < 3) *(f32x4*)(headu + ((size_t)blk * 3 + fr) * LW + c0 + 4 * n) = gv;
;                             if (m == 3 && fr >= 13) *(f32x4*)(tailu + ((size_t)blk * 3 + (fr - 13)) * LW + c0 + 4 * n) = gv;
;                         }
;                         if (!(m == 0 && fr < 3)) {
;                             u32x4 w; w.x = cvt_pk_bf16(o[0][0], o[0][1]); w.y = cvt_pk_bf16(o[0][2], o[0][3]); w.z = cvt_pk_bf16(o[1][0], o[1][1]); w.w = cvt_pk_bf16(o[1][2], o[1][3]);
;                             *(u32x4*)(vout + (size_t)row * LW + c0) = w;
.LBB0_142:
	s_or_b64 exec, exec, s[6:7]
	s_nop 1
	v_mov_b32_dpp v232, v116 row_ror:2 row_mask:0xf bank_mask:0xf
	v_mov_b32_dpp v236, v117 row_ror:3 row_mask:0xf bank_mask:0xf
	v_mov_b32_dpp v237, v118 row_ror:1 row_mask:0xf bank_mask:0xf
	v_mov_b32_dpp v239, v118 row_ror:3 row_mask:0xf bank_mask:0xf
	v_mov_b32_dpp v242, v119 row_ror:3 row_mask:0xf bank_mask:0xf
	v_mov_b32_dpp v234, v117 row_ror:1 row_mask:0xf bank_mask:0xf
	v_mov_b32_dpp v235, v117 row_ror:2 row_mask:0xf bank_mask:0xf
	v_mov_b32_dpp v238, v118 row_ror:2 row_mask:0xf bank_mask:0xf
	v_mov_b32_dpp v241, v119 row_ror:2 row_mask:0xf bank_mask:0xf
	v_mov_b32_dpp v233, v116 row_ror:3 row_mask:0xf bank_mask:0xf
	v_mov_b32_dpp v240, v119 row_ror:1 row_mask:0xf bank_mask:0xf
	v_mov_b32_dpp v231, v116 row_ror:1 row_mask:0xf bank_mask:0xf
	v_cndmask_b32_e64 v124, v220, v232, s[0:1]
	v_cndmask_b32_e64 v127, v224, v236, s[4:5]
	v_cndmask_b32_e32 v220, v225, v237, vcc
	v_cndmask_b32_e64 v224, v227, v239, s[4:5]
	v_cndmask_b32_e64 v225, v230, v242, s[4:5]
	v_cndmask_b32_e32 v123, v222, v234, vcc
	v_cndmask_b32_e64 v125, v223, v235, s[0:1]
	v_cndmask_b32_e64 v222, v226, v238, s[0:1]
	v_cndmask_b32_e64 v223, v229, v241, s[0:1]
	s_waitcnt vmcnt(0)
	v_pk_fma_f32 v[224:225], v[142:143], v[224:225], v[146:147]
	s_nop 1
	v_mov_b32_dpp v226, v112 row_ror:3 row_mask:0xf bank_mask:0xf
	v_mov_b32_dpp v229, v113 row_ror:3 row_mask:0xf bank_mask:0xf
	v_cndmask_b32_e64 v126, v221, v233, s[4:5]
	v_cndmask_b32_e32 v221, v228, v240, vcc
	v_pk_fma_f32 v[222:223], v[138:139], v[222:223], v[224:225]
	s_nop 1
	v_mov_b32_dpp v225, v112 row_ror:2 row_mask:0xf bank_mask:0xf
	v_mov_b32_dpp v228, v113 row_ror:2 row_mask:0xf bank_mask:0xf
	v_mov_b32_dpp v244, v114 row_ror:3 row_mask:0xf bank_mask:0xf
	v_mov_b32_dpp v247, v115 row_ror:3 row_mask:0xf bank_mask:0xf
	v_mov_b32_dpp v224, v112 row_ror:1 row_mask:0xf bank_mask:0xf
	v_mov_b32_dpp v227, v113 row_ror:1 row_mask:0xf bank_mask:0xf
	v_mov_b32_dpp v230, v114 row_ror:1 row_mask:0xf bank_mask:0xf
	v_mov_b32_dpp v243, v114 row_ror:2 row_mask:0xf bank_mask:0xf
	v_mov_b32_dpp v245, v115 row_ror:1 row_mask:0xf bank_mask:0xf
	v_mov_b32_dpp v246, v115 row_ror:2 row_mask:0xf bank_mask:0xf
	v_pk_fma_f32 v[126:127], v[140:141], v[126:127], v[144:145]
	v_cndmask_b32_e32 v122, v219, v231, vcc
	v_pk_fma_f32 v[124:125], v[136:137], v[124:125], v[126:127]
	v_cndmask_b32_e64 v126, v202, v226, s[4:5]
	v_pk_fma_f32 v[122:123], v[132:133], v[122:123], v[124:125]
	v_pk_fma_f32 v[124:125], v[134:135], v[220:221], v[222:223]
	v_cndmask_b32_e64 v127, v203, v229, s[4:5]
	v_pk_fma_f32 v[118:119], v[118:119], v[130:131], v[124:125]
	v_cndmask_b32_e64 v124, v198, v225, s[0:1]
	v_cndmask_b32_e64 v125, v199, v228, s[0:1]
	v_cndmask_b32_e64 v198, v204, v244, s[4:5]
	v_cndmask_b32_e64 v199, v205, v247, s[4:5]
	v_pk_fma_f32 v[126:127], v[160:161], v[126:127], v[164:165]
	v_pk_fma_f32 v[116:117], v[116:117], v[128:129], v[122:123]
	v_cndmask_b32_e32 v122, v194, v224, vcc
	v_cndmask_b32_e32 v123, v195, v227, vcc
	v_cndmask_b32_e32 v194, v196, v230, vcc
	v_cndmask_b32_e64 v196, v200, v243, s[0:1]
	v_cndmask_b32_e32 v195, v197, v245, vcc
	v_cndmask_b32_e64 v197, v201, v246, s[0:1]
	v_pk_fma_f32 v[198:199], v[162:163], v[198:199], v[166:167]
	v_pk_fma_f32 v[124:125], v[156:157], v[124:125], v[126:127]
	v_pk_fma_f32 v[196:197], v[158:159], v[196:197], v[198:199]
	v_pk_fma_f32 v[122:123], v[152:153], v[122:123], v[124:125]
	v_add_u32_e32 v126, 16, v186
	v_pk_fma_f32 v[124:125], v[154:155], v[194:195], v[196:197]
	v_pk_fma_f32 v[112:113], v[112:113], v[148:149], v[122:123]
	v_ashrrev_i32_e32 v127, 31, v126
	v_pk_fma_f32 v[114:115], v[114:115], v[150:151], v[124:125]
	v_cvt_pk_bf16_f32 v122, v116, v117
	v_cvt_pk_bf16_f32 v123, v118, v119
	v_cvt_pk_bf16_f32 v124, v112, v113
	v_lshlrev_b64 v[112:113], 12, v[126:127]
	v_lshl_add_u64 v[112:113], s[54:55], 0, v[112:113]
	v_lshlrev_b64 v[116:117], 1, v[184:185]
	v_cvt_pk_bf16_f32 v125, v114, v115
	v_lshl_add_u64 v[112:113], v[112:113], 0, v[116:117]
	global_store_dwordx4 v[112:113], v[122:125], off
	s_nop 1
	v_mov_b32_dpp v122, v108 row_ror:3 row_mask:0xf bank_mask:0xf
	v_mov_b32_dpp v125, v109 row_ror:3 row_mask:0xf bank_mask:0xf
	v_mov_b32_dpp v194, v110 row_ror:3 row_mask:0xf bank_mask:0xf
	v_mov_b32_dpp v197, v111 row_ror:3 row_mask:0xf bank_mask:0xf
	v_mov_b32_dpp v119, v108 row_ror:2 row_mask:0xf bank_mask:0xf
	v_mov_b32_dpp v124, v109 row_ror:2 row_mask:0xf bank_mask:0xf
	v_mov_b32_dpp v127, v110 row_ror:2 row_mask:0xf bank_mask:0xf
	v_mov_b32_dpp v196, v111 row_ror:2 row_mask:0xf bank_mask:0xf
; __device__ __forceinline__ unsigned cvt_pk_bf16(float lo, float hi) { unsigned r; asm volatile("v_cvt_pk_bf16_f32 %0, %1, %2" : "=v"(r) : "v"(lo), "v"(hi)); return r; }
;     __device__ __forceinline__ void operator()(EPI_ARGS) const {
;     ...
;                             for (int j = 0; j < 4; ++j) { r1[j] = __shfl(gv[j], s1); r2[j] = __shfl(gv[j], s2); r3[j] = __shfl(gv[j], s3); }
; #pragma unroll
;                             for (int j = 0; j < 4; ++j) { p1[j] = fr >= 1 ? r1[j] : q1[n][j]; p2[j] = fr >= 2 ? r2[j] : q2[n][j]; p3[j] = fr >= 3 ? r3[j] : q3[n][j]; }
;                             q1[n] = r1; q2[n] = r2; q3[n] = r3;
;                             o[n] = bb[n] + w0[n] * p3 + w1[n] * p2 + w2[n] * p1 + w3[n] * gv;
;                             if (m == 0 && fr < 3) *(f32x4*)(headu + ((size_t)blk * 3 + fr) * LW + c0 + 4 * n) = gv;
;                             if (m == 3 && fr >= 13) *(f32x4*)(tailu + ((size_t)blk * 3 + (fr - 13)) * LW + c0 + 4 * n) = gv;
;                         }
;                         if (!(m == 0 && fr < 3)) {
;                             u32x4 w; w.x = cvt_pk_bf16(o[0][0], o[0][1]); w.y = cvt_pk_bf16(o[0][2], o[0][3]); w.z = cvt_pk_bf16(o[1][0], o[1][1]); w.w = cvt_pk_bf16(o[1][2], o[1][3]);
;                             *(u32x4*)(vout + (size_t)row * LW + c0) = w;
	v_mov_b32_dpp v118, v108 row_ror:1 row_mask:0xf bank_mask:0xf
	v_mov_b32_dpp v123, v109 row_ror:1 row_mask:0xf bank_mask:0xf
	v_mov_b32_dpp v126, v110 row_ror:1 row_mask:0xf bank_mask:0xf
	v_mov_b32_dpp v195, v111 row_ror:1 row_mask:0xf bank_mask:0xf
	v_cndmask_b32_e64 v200, v233, v122, s[4:5]
	v_cndmask_b32_e64 v201, v236, v125, s[4:5]
	v_cndmask_b32_e64 v220, v239, v194, s[4:5]
	v_cndmask_b32_e64 v221, v242, v197, s[4:5]
	v_cndmask_b32_e64 v198, v232, v119, s[0:1]
	v_cndmask_b32_e64 v199, v235, v124, s[0:1]
	v_cndmask_b32_e64 v204, v238, v127, s[0:1]
	v_cndmask_b32_e64 v205, v241, v196, s[0:1]
	v_pk_fma_f32 v[200:201], v[140:141], v[200:201], v[144:145]
	v_pk_fma_f32 v[220:221], v[142:143], v[220:221], v[146:147]
	v_cndmask_b32_e32 v114, v231, v118, vcc
	v_cndmask_b32_e32 v115, v234, v123, vcc
	v_cndmask_b32_e32 v202, v237, v126, vcc
	v_cndmask_b32_e32 v203, v240, v195, vcc
	v_pk_fma_f32 v[204:205], v[138:139], v[204:205], v[220:221]
	v_pk_fma_f32 v[198:199], v[136:137], v[198:199], v[200:201]
	s_nop 1
	v_mov_b32_dpp v201, v105 row_ror:3 row_mask:0xf bank_mask:0xf
	v_pk_fma_f32 v[114:115], v[132:133], v[114:115], v[198:199]
	v_pk_fma_f32 v[198:199], v[134:135], v[202:203], v[204:205]
	s_nop 1
	v_mov_b32_dpp v200, v105 row_ror:2 row_mask:0xf bank_mask:0xf
	v_pk_fma_f32 v[222:223], v[110:111], v[130:131], v[198:199]
	s_nop 1
	v_mov_b32_dpp v198, v104 row_ror:3 row_mask:0xf bank_mask:0xf
	v_mov_b32_dpp v199, v105 row_ror:1 row_mask:0xf bank_mask:0xf
	v_mov_b32_dpp v110, v104 row_ror:1 row_mask:0xf bank_mask:0xf
	v_mov_b32_dpp v111, v104 row_ror:2 row_mask:0xf bank_mask:0xf
	v_mov_b32_dpp v204, v106 row_ror:3 row_mask:0xf bank_mask:0xf
	v_mov_b32_dpp v220, v107 row_ror:3 row_mask:0xf bank_mask:0xf
	v_mov_b32_dpp v202, v106 row_ror:1 row_mask:0xf bank_mask:0xf
	v_mov_b32_dpp v203, v106 row_ror:2 row_mask:0xf bank_mask:0xf
	v_mov_b32_dpp v219, v107 row_ror:2 row_mask:0xf bank_mask:0xf
	v_mov_b32_dpp v205, v107 row_ror:1 row_mask:0xf bank_mask:0xf
	v_pk_fma_f32 v[108:109], v[108:109], v[128:129], v[114:115]
	v_cndmask_b32_e64 v226, v226, v198, s[4:5]
	v_cndmask_b32_e32 v115, v227, v199, vcc
	v_cndmask_b32_e64 v227, v229, v201, s[4:5]
	v_cndmask_b32_e32 v114, v224, v110, vcc
	v_cndmask_b32_e64 v224, v225, v111, s[0:1]
	v_cndmask_b32_e64 v225, v228, v200, s[0:1]
	v_pk_fma_f32 v[226:227], v[160:161], v[226:227], v[164:165]
	v_cndmask_b32_e64 v232, v244, v204, s[4:5]
	v_cndmask_b32_e64 v233, v247, v220, s[4:5]
	v_pk_fma_f32 v[224:225], v[156:157], v[224:225], v[226:227]
	v_cndmask_b32_e32 v228, v230, v202, vcc
	v_cndmask_b32_e64 v230, v243, v203, s[0:1]
	v_cndmask_b32_e64 v231, v246, v219, s[0:1]
	v_pk_fma_f32 v[232:233], v[162:163], v[232:233], v[166:167]
	v_pk_fma_f32 v[114:115], v[152:153], v[114:115], v[224:225]
	v_cndmask_b32_e32 v229, v245, v205, vcc
	v_pk_fma_f32 v[230:231], v[158:159], v[230:231], v[232:233]
	v_pk_fma_f32 v[104:105], v[104:105], v[148:149], v[114:115]
	v_add_u32_e32 v114, 32, v186
	v_pk_fma_f32 v[224:225], v[154:155], v[228:229], v[230:231]
	v_ashrrev_i32_e32 v115, 31, v114
	v_pk_fma_f32 v[106:107], v[106:107], v[150:151], v[224:225]
	v_cvt_pk_bf16_f32 v230, v108, v109
	v_cvt_pk_bf16_f32 v231, v222, v223
	v_cvt_pk_bf16_f32 v232, v104, v105
	v_lshlrev_b64 v[104:105], 12, v[114:115]
	s_mul_hi_i32 s13, s34, 3
	s_mul_i32 s12, s34, 3
	v_add_u32_e32 v176, -13, v182
	v_cvt_pk_bf16_f32 v233, v106, v107
	v_lshl_add_u64 v[108:109], s[54:55], 0, v[104:105]
	s_nop 1
	v_mov_b32_dpp v104, v96 row_ror:1 row_mask:0xf bank_mask:0xf
	v_mov_b32_dpp v105, v96 row_ror:2 row_mask:0xf bank_mask:0xf
	v_mov_b32_dpp v106, v96 row_ror:3 row_mask:0xf bank_mask:0xf
	v_mov_b32_dpp v107, v97 row_ror:1 row_mask:0xf bank_mask:0xf
	v_mov_b32_dpp v221, v97 row_ror:2 row_mask:0xf bank_mask:0xf
	v_mov_b32_dpp v222, v97 row_ror:3 row_mask:0xf bank_mask:0xf
	v_mov_b32_dpp v223, v98 row_ror:1 row_mask:0xf bank_mask:0xf
	v_mov_b32_dpp v224, v98 row_ror:2 row_mask:0xf bank_mask:0xf
	v_mov_b32_dpp v225, v98 row_ror:3 row_mask:0xf bank_mask:0xf
	v_mov_b32_dpp v226, v99 row_ror:1 row_mask:0xf bank_mask:0xf
	v_mov_b32_dpp v227, v99 row_ror:2 row_mask:0xf bank_mask:0xf
	v_mov_b32_dpp v228, v99 row_ror:3 row_mask:0xf bank_mask:0xf
	v_lshl_add_u64 v[120:121], s[12:13], 0, v[176:177]
	v_lshlrev_b64 v[120:121], 13, v[120:121]
	v_lshl_add_u64 v[114:115], v[108:109], 0, v[116:117]
	v_lshl_add_u64 v[108:109], s[74:75], 0, v[120:121]
	v_cmp_lt_i32_e64 s[6:7], 12, v182
	v_lshl_add_u64 v[108:109], v[184:185], 2, v[108:109]
	global_store_dwordx4 v[114:115], v[230:233], off
	s_and_saveexec_b64 s[12:13], s[6:7]
	s_cbranch_execz .LBB0_144
	global_store_dwordx4 v[108:109], v[96:99], off

; __device__ __forceinline__ unsigned cvt_pk_bf16(float lo, float hi) { unsigned r; asm volatile("v_cvt_pk_bf16_f32 %0, %1, %2" : "=v"(r) : "v"(lo), "v"(hi)); return r; }
;     __device__ __forceinline__ void operator()(EPI_ARGS) const {
;     ...
;                             for (int j = 0; j < 4; ++j) { r1[j] = __shfl(gv[j], s1); r2[j] = __shfl(gv[j], s2); r3[j] = __shfl(gv[j], s3); }
; #pragma unroll
;                             for (int j = 0; j < 4; ++j) { p1[j] = fr >= 1 ? r1[j] : q1[n][j]; p2[j] = fr >= 2 ? r2[j] : q2[n][j]; p3[j] = fr >= 3 ? r3[j] : q3[n][j]; }
;                             q1[n] = r1; q2[n] = r2; q3[n] = r3;
;                             o[n] = bb[n] + w0[n] * p3 + w1[n] * p2 + w2[n] * p1 + w3[n] * gv;
;                             if (m == 0 && fr < 3) *(f32x4*)(headu + ((size_t)blk * 3 + fr) * LW + c0 + 4 * n) = gv;
;                             if (m == 3 && fr >= 13) *(f32x4*)(tailu + ((size_t)blk * 3 + (fr - 13)) * LW + c0 + 4 * n) = gv;
;                         }
;                         if (!(m == 0 && fr < 3)) {
;                             u32x4 w; w.x = cvt_pk_bf16(o[0][0], o[0][1]); w.y = cvt_pk_bf16(o[0][2], o[0][3]); w.z = cvt_pk_bf16(o[1][0], o[1][1]); w.w = cvt_pk_bf16(o[1][2], o[1][3]);
;                             *(u32x4*)(vout + (size_t)row * LW + c0) = w;
.LBB0_146:
	s_or_b64 exec, exec, s[12:13]
	v_cndmask_b32_e32 v110, v110, v120, vcc
	v_cndmask_b32_e64 v120, v111, v121, s[0:1]
	v_cndmask_b32_e64 v198, v198, v229, s[4:5]
	v_cndmask_b32_e32 v111, v199, v230, vcc
	v_cndmask_b32_e64 v199, v201, v232, s[4:5]
	v_cndmask_b32_e64 v121, v200, v231, s[0:1]
	v_pk_fma_f32 v[198:199], v[160:161], v[198:199], v[164:165]
	v_cndmask_b32_e64 v204, v204, v235, s[4:5]
	v_cndmask_b32_e32 v201, v205, v236, vcc
	v_cndmask_b32_e64 v205, v220, v238, s[4:5]
	v_pk_fma_f32 v[120:121], v[156:157], v[120:121], v[198:199]
	v_cndmask_b32_e32 v200, v202, v233, vcc
	v_cndmask_b32_e64 v202, v203, v234, s[0:1]
	v_cndmask_b32_e64 v203, v219, v237, s[0:1]
	v_pk_fma_f32 v[204:205], v[162:163], v[204:205], v[166:167]
	v_pk_fma_f32 v[110:111], v[152:153], v[110:111], v[120:121]
	v_pk_fma_f32 v[202:203], v[158:159], v[202:203], v[204:205]
	v_pk_fma_f32 v[100:101], v[100:101], v[148:149], v[110:111]
	v_cndmask_b32_e64 v110, v119, v105, s[0:1]
	v_cndmask_b32_e64 v106, v122, v106, s[4:5]
	v_cndmask_b32_e32 v105, v123, v107, vcc
	v_cndmask_b32_e64 v107, v125, v222, s[4:5]
	v_pk_fma_f32 v[120:121], v[154:155], v[200:201], v[202:203]
	v_cndmask_b32_e64 v111, v124, v221, s[0:1]
	v_cndmask_b32_e64 v122, v194, v225, s[4:5]
	v_cndmask_b32_e64 v123, v197, v228, s[4:5]
	v_pk_fma_f32 v[106:107], v[140:141], v[106:107], v[144:145]
	v_pk_fma_f32 v[102:103], v[102:103], v[150:151], v[120:121]
	v_cndmask_b32_e32 v104, v118, v104, vcc
	v_cndmask_b32_e64 v120, v127, v224, s[0:1]
	v_cndmask_b32_e64 v121, v196, v227, s[0:1]
	v_pk_fma_f32 v[122:123], v[142:143], v[122:123], v[146:147]
	v_pk_fma_f32 v[106:107], v[136:137], v[110:111], v[106:107]
	v_cndmask_b32_e32 v118, v126, v223, vcc
	v_cndmask_b32_e32 v119, v195, v226, vcc
	v_pk_fma_f32 v[120:121], v[138:139], v[120:121], v[122:123]
	v_pk_fma_f32 v[104:105], v[132:133], v[104:105], v[106:107]
	v_pk_fma_f32 v[106:107], v[134:135], v[118:119], v[120:121]
	v_pk_fma_f32 v[96:97], v[96:97], v[128:129], v[104:105]
	v_add_u32_e32 v104, 48, v186
	v_pk_fma_f32 v[98:99], v[98:99], v[130:131], v[106:107]
	v_ashrrev_i32_e32 v105, 31, v104
	v_cvt_pk_bf16_f32 v96, v96, v97
	v_cvt_pk_bf16_f32 v97, v98, v99
	v_cvt_pk_bf16_f32 v98, v100, v101
	v_lshlrev_b64 v[100:101], 12, v[104:105]
	v_lshl_add_u64 v[100:101], s[54:55], 0, v[100:101]
	v_lshl_add_u64 v[110:111], v[184:185], 1, v[100:101]
	s_add_i32 s87, s34, 2
	s_nop 1
	v_mov_b32_dpp v122, v92 row_ror:1 row_mask:0xf bank_mask:0xf
	v_mov_b32_dpp v123, v92 row_ror:2 row_mask:0xf bank_mask:0xf
	v_mov_b32_dpp v124, v92 row_ror:3 row_mask:0xf bank_mask:0xf
	v_mov_b32_dpp v125, v93 row_ror:1 row_mask:0xf bank_mask:0xf
	v_mov_b32_dpp v126, v93 row_ror:2 row_mask:0xf bank_mask:0xf
	v_mov_b32_dpp v127, v93 row_ror:3 row_mask:0xf bank_mask:0xf
	v_mov_b32_dpp v194, v94 row_ror:1 row_mask:0xf bank_mask:0xf
	v_mov_b32_dpp v195, v94 row_ror:2 row_mask:0xf bank_mask:0xf
	v_mov_b32_dpp v196, v94 row_ror:3 row_mask:0xf bank_mask:0xf
	v_mov_b32_dpp v197, v95 row_ror:1 row_mask:0xf bank_mask:0xf
	v_mov_b32_dpp v198, v95 row_ror:2 row_mask:0xf bank_mask:0xf
	v_mov_b32_dpp v199, v95 row_ror:3 row_mask:0xf bank_mask:0xf
	v_cvt_pk_bf16_f32 v99, v102, v103
	global_store_dwordx4 v[110:111], v[96:99], off
	s_nop 1
	v_mad_i64_i32 v[96:97], s[12:13], s87, 3, v[182:183]
	v_lshlrev_b64 v[96:97], 13, v[96:97]
	v_lshl_add_u64 v[96:97], s[50:51], 0, v[96:97]
	v_lshl_add_u64 v[106:107], v[184:185], 2, v[96:97]
	s_and_saveexec_b64 s[12:13], s[10:11]
	s_cbranch_execz .LBB0_148
	global_store_dwordx4 v[106:107], v[92:95], off
.LBB0_148:
	s_or_b64 exec, exec, s[12:13]
	s_nop 1
	v_mov_b32_dpp v96, v88 row_ror:1 row_mask:0xf bank_mask:0xf
	v_mov_b32_dpp v100, v88 row_ror:2 row_mask:0xf bank_mask:0xf
	v_mov_b32_dpp v118, v88 row_ror:3 row_mask:0xf bank_mask:0xf
	v_mov_b32_dpp v97, v89 row_ror:1 row_mask:0xf bank_mask:0xf
	v_mov_b32_dpp v101, v89 row_ror:2 row_mask:0xf bank_mask:0xf
	v_mov_b32_dpp v119, v89 row_ror:3 row_mask:0xf bank_mask:0xf
	v_mov_b32_dpp v98, v90 row_ror:1 row_mask:0xf bank_mask:0xf
	v_mov_b32_dpp v102, v90 row_ror:2 row_mask:0xf bank_mask:0xf
	v_mov_b32_dpp v120, v90 row_ror:3 row_mask:0xf bank_mask:0xf
	v_mov_b32_dpp v99, v91 row_ror:1 row_mask:0xf bank_mask:0xf
	v_mov_b32_dpp v103, v91 row_ror:2 row_mask:0xf bank_mask:0xf
	v_mov_b32_dpp v121, v91 row_ror:3 row_mask:0xf bank_mask:0xf
	v_add_u32_e32 v104, 0x80, v186
	v_ashrrev_i32_e32 v105, 31, v104
	s_and_saveexec_b64 s[12:13], s[8:9]
	s_xor_b64 s[34:35], exec, s[12:13]
	s_cbranch_execz .LBB0_150
	v_cndmask_b32_e64 v202, 0, v124, s[4:5]
	v_cndmask_b32_e64 v203, 0, v127, s[4:5]
	v_cndmask_b32_e64 v200, 0, v123, s[0:1]
	v_cndmask_b32_e64 v201, 0, v126, s[0:1]
	v_cndmask_b32_e64 v222, 0, v196, s[4:5]
	v_cndmask_b32_e64 v223, 0, v199, s[4:5]
	v_pk_fma_f32 v[202:203], v[140:141], v[202:203], v[144:145]
	v_cndmask_b32_e32 v182, 0, v122, vcc
	v_cndmask_b32_e32 v183, 0, v125, vcc
	v_cndmask_b32_e64 v220, 0, v195, s[0:1]
	v_cndmask_b32_e64 v221, 0, v198, s[0:1]
	v_pk_fma_f32 v[222:223], v[142:143], v[222:223], v[146:147]
	v_pk_fma_f32 v[200:201], v[136:137], v[200:201], v[202:203]
	v_cndmask_b32_e32 v204, 0, v194, vcc
	v_cndmask_b32_e32 v205, 0, v197, vcc
	v_pk_fma_f32 v[220:221], v[138:139], v[220:221], v[222:223]
	v_pk_fma_f32 v[182:183], v[132:133], v[182:183], v[200:201]
	v_pk_fma_f32 v[200:201], v[134:135], v[204:205], v[220:221]
	v_pk_fma_f32 v[92:93], v[92:93], v[128:129], v[182:183]
	v_pk_fma_f32 v[182:183], v[162:163], v[120:121], v[166:167]
	v_pk_fma_f32 v[94:95], v[94:95], v[130:131], v[200:201]
	v_pk_fma_f32 v[200:201], v[160:161], v[118:119], v[164:165]
	v_pk_fma_f32 v[182:183], v[158:159], v[102:103], v[182:183]
	v_pk_fma_f32 v[200:201], v[156:157], v[100:101], v[200:201]
	v_pk_fma_f32 v[182:183], v[154:155], v[98:99], v[182:183]
	v_pk_fma_f32 v[200:201], v[152:153], v[96:97], v[200:201]
	v_pk_fma_f32 v[182:183], v[90:91], v[150:151], v[182:183]
	v_pk_fma_f32 v[200:201], v[88:89], v[148:149], v[200:201]
	v_cvt_pk_bf16_f32 v92, v92, v93
	v_cvt_pk_bf16_f32 v93, v94, v95
	s_nop 0
	v_cvt_pk_bf16_f32 v94, v200, v201
	v_cvt_pk_bf16_f32 v95, v182, v183
	v_lshlrev_b64 v[182:183], 12, v[104:105]
	v_lshl_add_u64 v[182:183], s[54:55], 0, v[182:183]
	v_lshl_add_u64 v[182:183], v[184:185], 1, v[182:183]
	global_store_dwordx4 v[182:183], v[92:95], off

; __device__ __forceinline__ unsigned cvt_pk_bf16(float lo, float hi) { unsigned r; asm volatile("v_cvt_pk_bf16_f32 %0, %1, %2" : "=v"(r) : "v"(lo), "v"(hi)); return r; }
;     __device__ __forceinline__ void operator()(EPI_ARGS) const {
;     ...
;                             for (int j = 0; j < 4; ++j) { r1[j] = __shfl(gv[j], s1); r2[j] = __shfl(gv[j], s2); r3[j] = __shfl(gv[j], s3); }
; #pragma unroll
;                             for (int j = 0; j < 4; ++j) { p1[j] = fr >= 1 ? r1[j] : q1[n][j]; p2[j] = fr >= 2 ? r2[j] : q2[n][j]; p3[j] = fr >= 3 ? r3[j] : q3[n][j]; }
;                             q1[n] = r1; q2[n] = r2; q3[n] = r3;
;                             o[n] = bb[n] + w0[n] * p3 + w1[n] * p2 + w2[n] * p1 + w3[n] * gv;
;                             if (m == 0 && fr < 3) *(f32x4*)(headu + ((size_t)blk * 3 + fr) * LW + c0 + 4 * n) = gv;
;                             if (m == 3 && fr >= 13) *(f32x4*)(tailu + ((size_t)blk * 3 + (fr - 13)) * LW + c0 + 4 * n) = gv;
;                         }
;                         if (!(m == 0 && fr < 3)) {
;                             u32x4 w; w.x = cvt_pk_bf16(o[0][0], o[0][1]); w.y = cvt_pk_bf16(o[0][2], o[0][3]); w.z = cvt_pk_bf16(o[1][0], o[1][1]); w.w = cvt_pk_bf16(o[1][2], o[1][3]);
;                             *(u32x4*)(vout + (size_t)row * LW + c0) = w;
.LBB0_152:
	s_or_b64 exec, exec, s[12:13]
	s_nop 1
	v_mov_b32_dpp v183, v84 row_ror:3 row_mask:0xf bank_mask:0xf
	v_mov_b32_dpp v201, v85 row_ror:2 row_mask:0xf bank_mask:0xf
	v_mov_b32_dpp v202, v85 row_ror:3 row_mask:0xf bank_mask:0xf
	v_mov_b32_dpp v205, v86 row_ror:3 row_mask:0xf bank_mask:0xf
	v_mov_b32_dpp v221, v87 row_ror:3 row_mask:0xf bank_mask:0xf
	s_mul_hi_i32 s13, s87, 3
	s_mul_i32 s12, s87, 3
	s_nop 1
	v_mov_b32_dpp v182, v84 row_ror:2 row_mask:0xf bank_mask:0xf
	v_mov_b32_dpp v200, v85 row_ror:1 row_mask:0xf bank_mask:0xf
	v_mov_b32_dpp v204, v86 row_ror:2 row_mask:0xf bank_mask:0xf
	v_mov_b32_dpp v220, v87 row_ror:2 row_mask:0xf bank_mask:0xf
	v_lshl_add_u64 v[88:89], s[12:13], 0, v[176:177]
	s_nop 1
	v_mov_b32_dpp v176, v84 row_ror:1 row_mask:0xf bank_mask:0xf
	v_mov_b32_dpp v203, v86 row_ror:1 row_mask:0xf bank_mask:0xf
	v_mov_b32_dpp v219, v87 row_ror:1 row_mask:0xf bank_mask:0xf
	v_cndmask_b32_e64 v94, v124, v183, s[4:5]
	v_cndmask_b32_e64 v93, v126, v201, s[0:1]
	v_cndmask_b32_e64 v95, v127, v202, s[4:5]
	v_cndmask_b32_e64 v126, v196, v205, s[4:5]
	v_cndmask_b32_e64 v127, v199, v221, s[4:5]
	v_cndmask_b32_e64 v92, v123, v182, s[0:1]
	v_cndmask_b32_e32 v91, v125, v200, vcc
	v_cndmask_b32_e64 v124, v195, v204, s[0:1]
	v_cndmask_b32_e64 v125, v198, v220, s[0:1]
	v_pk_fma_f32 v[94:95], v[140:141], v[94:95], v[144:145]
	v_pk_fma_f32 v[126:127], v[142:143], v[126:127], v[146:147]
	v_cndmask_b32_e32 v90, v122, v176, vcc
	v_cndmask_b32_e32 v122, v194, v203, vcc
	v_cndmask_b32_e32 v123, v197, v219, vcc
	v_pk_fma_f32 v[124:125], v[138:139], v[124:125], v[126:127]
	v_pk_fma_f32 v[92:93], v[136:137], v[92:93], v[94:95]
	s_nop 1
	v_mov_b32_dpp v194, v81 row_ror:2 row_mask:0xf bank_mask:0xf
	v_pk_fma_f32 v[90:91], v[132:133], v[90:91], v[92:93]
	v_pk_fma_f32 v[92:93], v[134:135], v[122:123], v[124:125]
	s_nop 1
	v_mov_b32_dpp v123, v80 row_ror:2 row_mask:0xf bank_mask:0xf
	v_mov_b32_dpp v125, v80 row_ror:3 row_mask:0xf bank_mask:0xf
	v_mov_b32_dpp v195, v81 row_ror:3 row_mask:0xf bank_mask:0xf
	v_mov_b32_dpp v198, v82 row_ror:3 row_mask:0xf bank_mask:0xf
	v_mov_b32_dpp v223, v83 row_ror:3 row_mask:0xf bank_mask:0xf
	v_mov_b32_dpp v122, v80 row_ror:1 row_mask:0xf bank_mask:0xf
	v_mov_b32_dpp v127, v81 row_ror:1 row_mask:0xf bank_mask:0xf
	v_mov_b32_dpp v196, v82 row_ror:1 row_mask:0xf bank_mask:0xf
	v_mov_b32_dpp v197, v82 row_ror:2 row_mask:0xf bank_mask:0xf
	v_mov_b32_dpp v199, v83 row_ror:1 row_mask:0xf bank_mask:0xf
	v_mov_b32_dpp v222, v83 row_ror:2 row_mask:0xf bank_mask:0xf
	v_pk_fma_f32 v[86:87], v[86:87], v[130:131], v[92:93]
	v_cndmask_b32_e64 v92, v100, v123, s[0:1]
	v_cndmask_b32_e64 v94, v118, v125, s[4:5]
	v_cndmask_b32_e64 v93, v101, v194, s[0:1]
	v_cndmask_b32_e64 v95, v119, v195, s[4:5]
	v_cndmask_b32_e64 v100, v120, v198, s[4:5]
	v_cndmask_b32_e64 v101, v121, v223, s[4:5]
	v_pk_fma_f32 v[84:85], v[84:85], v[128:129], v[90:91]
	v_cndmask_b32_e32 v90, v96, v122, vcc
	v_cndmask_b32_e32 v91, v97, v127, vcc
	v_cndmask_b32_e32 v96, v98, v196, vcc
	v_cndmask_b32_e64 v98, v102, v197, s[0:1]
	v_cndmask_b32_e32 v97, v99, v199, vcc
	v_cndmask_b32_e64 v99, v103, v222, s[0:1]
	v_pk_fma_f32 v[94:95], v[160:161], v[94:95], v[164:165]
	v_pk_fma_f32 v[100:101], v[162:163], v[100:101], v[166:167]
	v_pk_fma_f32 v[92:93], v[156:157], v[92:93], v[94:95]
	v_pk_fma_f32 v[98:99], v[158:159], v[98:99], v[100:101]
	v_pk_fma_f32 v[90:91], v[152:153], v[90:91], v[92:93]
	v_pk_fma_f32 v[92:93], v[154:155], v[96:97], v[98:99]
	v_lshlrev_b64 v[88:89], 13, v[88:89]
	v_pk_fma_f32 v[92:93], v[82:83], v[150:151], v[92:93]
	v_pk_fma_f32 v[82:83], v[80:81], v[148:149], v[90:91]
	v_add_u32_e32 v90, 0x90, v186
	v_ashrrev_i32_e32 v91, 31, v90
	v_cvt_pk_bf16_f32 v80, v84, v85
	v_lshlrev_b64 v[84:85], 12, v[90:91]
	v_lshl_add_u64 v[84:85], s[54:55], 0, v[84:85]
	v_cvt_pk_bf16_f32 v81, v86, v87
	v_cvt_pk_bf16_f32 v82, v82, v83
	v_lshl_add_u64 v[118:119], v[84:85], 0, v[116:117]
	v_cvt_pk_bf16_f32 v83, v92, v93
	global_store_dwordx4 v[118:119], v[80:83], off
	s_nop 1
	v_mov_b32_dpp v82, v76 row_ror:3 row_mask:0xf bank_mask:0xf
	v_mov_b32_dpp v85, v77 row_ror:3 row_mask:0xf bank_mask:0xf
	v_mov_b32_dpp v90, v78 row_ror:3 row_mask:0xf bank_mask:0xf
	v_mov_b32_dpp v93, v79 row_ror:3 row_mask:0xf bank_mask:0xf
	v_mov_b32_dpp v81, v76 row_ror:2 row_mask:0xf bank_mask:0xf
	v_mov_b32_dpp v84, v77 row_ror:2 row_mask:0xf bank_mask:0xf
; __device__ __forceinline__ unsigned cvt_pk_bf16(float lo, float hi) { unsigned r; asm volatile("v_cvt_pk_bf16_f32 %0, %1, %2" : "=v"(r) : "v"(lo), "v"(hi)); return r; }
;     __device__ __forceinline__ void operator()(EPI_ARGS) const {
;     ...
;                             for (int j = 0; j < 4; ++j) { r1[j] = __shfl(gv[j], s1); r2[j] = __shfl(gv[j], s2); r3[j] = __shfl(gv[j], s3); }
; #pragma unroll
;                             for (int j = 0; j < 4; ++j) { p1[j] = fr >= 1 ? r1[j] : q1[n][j]; p2[j] = fr >= 2 ? r2[j] : q2[n][j]; p3[j] = fr >= 3 ? r3[j] : q3[n][j]; }
;                             q1[n] = r1; q2[n] = r2; q3[n] = r3;
;                             o[n] = bb[n] + w0[n] * p3 + w1[n] * p2 + w2[n] * p1 + w3[n] * gv;
;                             if (m == 0 && fr < 3) *(f32x4*)(headu + ((size_t)blk * 3 + fr) * LW + c0 + 4 * n) = gv;
;                             if (m == 3 && fr >= 13) *(f32x4*)(tailu + ((size_t)blk * 3 + (fr - 13)) * LW + c0 + 4 * n) = gv;
;                         }
;                         if (!(m == 0 && fr < 3)) {
;                             u32x4 w; w.x = cvt_pk_bf16(o[0][0], o[0][1]); w.y = cvt_pk_bf16(o[0][2], o[0][3]); w.z = cvt_pk_bf16(o[1][0], o[1][1]); w.w = cvt_pk_bf16(o[1][2], o[1][3]);
;                             *(u32x4*)(vout + (size_t)row * LW + c0) = w;
	v_mov_b32_dpp v87, v78 row_ror:2 row_mask:0xf bank_mask:0xf
	v_mov_b32_dpp v92, v79 row_ror:2 row_mask:0xf bank_mask:0xf
	v_mov_b32_dpp v80, v76 row_ror:1 row_mask:0xf bank_mask:0xf
	v_mov_b32_dpp v83, v77 row_ror:1 row_mask:0xf bank_mask:0xf
	v_mov_b32_dpp v86, v78 row_ror:1 row_mask:0xf bank_mask:0xf
	v_mov_b32_dpp v91, v79 row_ror:1 row_mask:0xf bank_mask:0xf
	v_cndmask_b32_e64 v98, v183, v82, s[4:5]
	v_cndmask_b32_e64 v99, v202, v85, s[4:5]
	v_cndmask_b32_e64 v120, v205, v90, s[4:5]
	v_cndmask_b32_e64 v121, v221, v93, s[4:5]
	v_cndmask_b32_e64 v96, v182, v81, s[0:1]
	v_cndmask_b32_e64 v97, v201, v84, s[0:1]
	v_cndmask_b32_e64 v102, v204, v87, s[0:1]
	v_cndmask_b32_e64 v103, v220, v92, s[0:1]
	v_pk_fma_f32 v[98:99], v[140:141], v[98:99], v[144:145]
	v_pk_fma_f32 v[120:121], v[142:143], v[120:121], v[146:147]
	v_cndmask_b32_e32 v94, v176, v80, vcc
	v_cndmask_b32_e32 v95, v200, v83, vcc
	v_cndmask_b32_e32 v100, v203, v86, vcc
	v_cndmask_b32_e32 v101, v219, v91, vcc
	v_pk_fma_f32 v[102:103], v[138:139], v[102:103], v[120:121]
	v_pk_fma_f32 v[96:97], v[136:137], v[96:97], v[98:99]
	s_nop 1
	v_mov_b32_dpp v98, v74 row_ror:3 row_mask:0xf bank_mask:0xf
	v_pk_fma_f32 v[94:95], v[132:133], v[94:95], v[96:97]
	v_pk_fma_f32 v[96:97], v[134:135], v[100:101], v[102:103]
	v_pk_fma_f32 v[120:121], v[76:77], v[128:129], v[94:95]
	v_pk_fma_f32 v[102:103], v[78:79], v[130:131], v[96:97]
	s_nop 1
	v_mov_b32_dpp v77, v72 row_ror:2 row_mask:0xf bank_mask:0xf
	v_mov_b32_dpp v78, v72 row_ror:3 row_mask:0xf bank_mask:0xf
	v_mov_b32_dpp v79, v73 row_ror:1 row_mask:0xf bank_mask:0xf
	v_mov_b32_dpp v95, v73 row_ror:3 row_mask:0xf bank_mask:0xf
	v_mov_b32_dpp v94, v73 row_ror:2 row_mask:0xf bank_mask:0xf
	v_mov_b32_dpp v76, v72 row_ror:1 row_mask:0xf bank_mask:0xf
	v_mov_b32_dpp v96, v74 row_ror:1 row_mask:0xf bank_mask:0xf
	v_mov_b32_dpp v97, v74 row_ror:2 row_mask:0xf bank_mask:0xf
	v_mov_b32_dpp v101, v75 row_ror:3 row_mask:0xf bank_mask:0xf
	v_mov_b32_dpp v100, v75 row_ror:2 row_mask:0xf bank_mask:0xf
	v_mov_b32_dpp v99, v75 row_ror:1 row_mask:0xf bank_mask:0xf
	v_cndmask_b32_e64 v124, v123, v77, s[0:1]
	v_cndmask_b32_e64 v126, v125, v78, s[4:5]
	v_cndmask_b32_e32 v123, v127, v79, vcc
	v_cndmask_b32_e64 v127, v195, v95, s[4:5]
	v_cndmask_b32_e64 v125, v194, v94, s[0:1]
	v_pk_fma_f32 v[126:127], v[160:161], v[126:127], v[164:165]
	v_cndmask_b32_e32 v122, v122, v76, vcc
	v_cndmask_b32_e32 v182, v196, v96, vcc
	v_cndmask_b32_e64 v194, v197, v97, s[0:1]
	v_cndmask_b32_e64 v196, v198, v98, s[4:5]
	v_cndmask_b32_e64 v197, v223, v101, s[4:5]
	v_pk_fma_f32 v[124:125], v[156:157], v[124:125], v[126:127]
	v_cndmask_b32_e64 v195, v222, v100, s[0:1]
	v_pk_fma_f32 v[196:197], v[162:163], v[196:197], v[166:167]
	v_pk_fma_f32 v[122:123], v[152:153], v[122:123], v[124:125]
	v_cndmask_b32_e32 v183, v199, v99, vcc
	v_pk_fma_f32 v[194:195], v[158:159], v[194:195], v[196:197]
	v_pk_fma_f32 v[72:73], v[72:73], v[148:149], v[122:123]
	v_add_u32_e32 v122, 0xa0, v186
	v_pk_fma_f32 v[124:125], v[154:155], v[182:183], v[194:195]
	v_ashrrev_i32_e32 v123, 31, v122
	v_pk_fma_f32 v[74:75], v[74:75], v[150:151], v[124:125]
	v_cvt_pk_bf16_f32 v194, v120, v121
	v_cvt_pk_bf16_f32 v195, v102, v103
	v_cvt_pk_bf16_f32 v196, v72, v73
	v_lshlrev_b64 v[72:73], 12, v[122:123]
	v_cvt_pk_bf16_f32 v197, v74, v75
	v_lshl_add_u64 v[120:121], s[54:55], 0, v[72:73]
	s_nop 1
	v_mov_b32_dpp v72, v64 row_ror:1 row_mask:0xf bank_mask:0xf
	v_mov_b32_dpp v73, v64 row_ror:2 row_mask:0xf bank_mask:0xf
	v_mov_b32_dpp v74, v64 row_ror:3 row_mask:0xf bank_mask:0xf
	v_mov_b32_dpp v75, v65 row_ror:1 row_mask:0xf bank_mask:0xf
	v_mov_b32_dpp v102, v65 row_ror:2 row_mask:0xf bank_mask:0xf
	v_mov_b32_dpp v103, v65 row_ror:3 row_mask:0xf bank_mask:0xf
	v_mov_b32_dpp v122, v66 row_ror:1 row_mask:0xf bank_mask:0xf
	v_mov_b32_dpp v123, v66 row_ror:2 row_mask:0xf bank_mask:0xf
	v_mov_b32_dpp v124, v66 row_ror:3 row_mask:0xf bank_mask:0xf
	v_mov_b32_dpp v125, v67 row_ror:1 row_mask:0xf bank_mask:0xf
	v_mov_b32_dpp v126, v67 row_ror:2 row_mask:0xf bank_mask:0xf
	v_mov_b32_dpp v127, v67 row_ror:3 row_mask:0xf bank_mask:0xf
	v_lshl_add_u64 v[88:89], s[74:75], 0, v[88:89]
	v_lshl_add_u64 v[120:121], v[120:121], 0, v[116:117]
	v_lshl_add_u64 v[116:117], v[184:185], 2, v[88:89]
	global_store_dwordx4 v[120:121], v[194:197], off
	s_and_saveexec_b64 s[12:13], s[6:7]
	s_cbranch_execz .LBB0_154
	global_store_dwordx4 v[116:117], v[64:67], off

; __device__ __forceinline__ unsigned cvt_pk_bf16(float lo, float hi) { unsigned r; asm volatile("v_cvt_pk_bf16_f32 %0, %1, %2" : "=v"(r) : "v"(lo), "v"(hi)); return r; }
;     __device__ __forceinline__ void operator()(EPI_ARGS) const {
;     ...
;                 for (int n = 0; n < 2; ++n) { w0[n] = *(const f32x4*)(cw + c0 + 4 * n); w1[n] = *(const f32x4*)(cw + LW + c0 + 4 * n); w2[n] = *(const f32x4*)(cw + 2 * LW + c0 + 4 * n); w3[n] = *(const f32x4*)(cw + 3 * LW + c0 + 4 * n); bb[n] = *(const f32x4*)(cb + c0 + 4 * n); }
; #pragma unroll
;                 for (int ai = 0; ai < 2; ++ai) {
;                     const int blk = u.pm * 4 + ai * 2 + wr;
;                     f32x4 q1[2], q2[2], q3[2];
; #pragma unroll
;                     for (int n = 0; n < 2; ++n) { q1[n] = (f32x4){0.f, 0.f, 0.f, 0.f}; q2[n] = q1[n]; q3[n] = q1[n]; }
; #pragma unroll
;                     for (int m = 0; m < 4; ++m) {
;                         const int row = ROW_OF(ai, m);
;                         f32x4 o[2];
; #pragma unroll
;                         for (int n = 0; n < 2; ++n) {
;                             const f32x4 gv = acc[ai][bj][m][n];
;                             f32x4 r1, r2, r3, p1, p2, p3;
; #pragma unroll
;                             for (int j = 0; j < 4; ++j) { r1[j] = __shfl(gv[j], s1); r2[j] = __shfl(gv[j], s2); r3[j] = __shfl(gv[j], s3); }
; #pragma unroll
;                             for (int j = 0; j < 4; ++j) { p1[j] = fr >= 1 ? r1[j] : q1[n][j]; p2[j] = fr >= 2 ? r2[j] : q2[n][j]; p3[j] = fr >= 3 ? r3[j] : q3[n][j]; }
;                             q1[n] = r1; q2[n] = r2; q3[n] = r3;
;                             o[n] = bb[n] + w0[n] * p3 + w1[n] * p2 + w2[n] * p1 + w3[n] * gv;
;                             if (m == 0 && fr < 3) *(f32x4*)(headu + ((size_t)blk * 3 + fr) * LW + c0 + 4 * n) = gv;
;                             if (m == 3 && fr >= 13) *(f32x4*)(tailu + ((size_t)blk * 3 + (fr - 13)) * LW + c0 + 4 * n) = gv;
;                         }
;                         if (!(m == 0 && fr < 3)) {
;                             u32x4 w; w.x = cvt_pk_bf16(o[0][0], o[0][1]); w.y = cvt_pk_bf16(o[0][2], o[0][3]); w.z = cvt_pk_bf16(o[1][0], o[1][1]); w.w = cvt_pk_bf16(o[1][2], o[1][3]);
;                             *(u32x4*)(vout + (size_t)row * LW + c0) = w;
.LBB0_156:
	s_or_b64 exec, exec, s[12:13]
	v_cndmask_b32_e32 v76, v76, v88, vcc
	v_cndmask_b32_e64 v88, v77, v89, s[0:1]
	v_cndmask_b32_e64 v78, v78, v176, s[4:5]
	v_cndmask_b32_e32 v77, v79, v182, vcc
	v_cndmask_b32_e64 v79, v95, v194, s[4:5]
	v_cndmask_b32_e64 v89, v94, v183, s[0:1]
	v_pk_fma_f32 v[78:79], v[160:161], v[78:79], v[164:165]
	v_cndmask_b32_e64 v98, v98, v197, s[4:5]
	v_pk_fma_f32 v[78:79], v[156:157], v[88:89], v[78:79]
	v_cndmask_b32_e32 v95, v99, v198, vcc
	v_cndmask_b32_e64 v99, v101, v200, s[4:5]
	v_pk_fma_f32 v[76:77], v[152:153], v[76:77], v[78:79]
	v_cndmask_b32_e32 v94, v96, v195, vcc
	v_cndmask_b32_e64 v96, v97, v196, s[0:1]
	v_cndmask_b32_e64 v97, v100, v199, s[0:1]
	v_pk_fma_f32 v[98:99], v[162:163], v[98:99], v[166:167]
	v_pk_fma_f32 v[68:69], v[68:69], v[148:149], v[76:77]
	v_cndmask_b32_e64 v76, v81, v73, s[0:1]
	v_cndmask_b32_e64 v74, v82, v74, s[4:5]
	v_cndmask_b32_e32 v73, v83, v75, vcc
	v_cndmask_b32_e64 v75, v85, v103, s[4:5]
	v_pk_fma_f32 v[96:97], v[158:159], v[96:97], v[98:99]
	v_cndmask_b32_e64 v77, v84, v102, s[0:1]
	v_cndmask_b32_e64 v82, v90, v124, s[4:5]
	v_cndmask_b32_e64 v83, v93, v127, s[4:5]
	v_pk_fma_f32 v[74:75], v[140:141], v[74:75], v[144:145]
	v_pk_fma_f32 v[78:79], v[154:155], v[94:95], v[96:97]
	v_cndmask_b32_e32 v72, v80, v72, vcc
	v_cndmask_b32_e64 v80, v87, v123, s[0:1]
	v_cndmask_b32_e64 v81, v92, v126, s[0:1]
	v_pk_fma_f32 v[82:83], v[142:143], v[82:83], v[146:147]
	v_pk_fma_f32 v[74:75], v[136:137], v[76:77], v[74:75]
	v_pk_fma_f32 v[70:71], v[70:71], v[150:151], v[78:79]
	v_cndmask_b32_e32 v78, v86, v122, vcc
	v_cndmask_b32_e32 v79, v91, v125, vcc
	v_pk_fma_f32 v[80:81], v[138:139], v[80:81], v[82:83]
	v_pk_fma_f32 v[72:73], v[132:133], v[72:73], v[74:75]
	v_pk_fma_f32 v[74:75], v[134:135], v[78:79], v[80:81]
	v_pk_fma_f32 v[64:65], v[64:65], v[128:129], v[72:73]
	v_add_u32_e32 v72, 0xb0, v186
	v_pk_fma_f32 v[66:67], v[66:67], v[130:131], v[74:75]
	v_ashrrev_i32_e32 v73, 31, v72
	v_cvt_pk_bf16_f32 v64, v64, v65
	v_cvt_pk_bf16_f32 v65, v66, v67
	v_cvt_pk_bf16_f32 v66, v68, v69
	v_lshlrev_b64 v[68:69], 12, v[72:73]
	v_lshl_add_u64 v[68:69], s[54:55], 0, v[68:69]
	v_lshl_add_u64 v[122:123], v[184:185], 1, v[68:69]
	v_cvt_pk_bf16_f32 v67, v70, v71
	global_store_dwordx4 v[122:123], v[64:67], off
	s_nop 1
	v_mov_b32_dpp v136, v60 row_ror:1 row_mask:0xf bank_mask:0xf
	v_mov_b32_dpp v137, v60 row_ror:2 row_mask:0xf bank_mask:0xf
	v_add_u32_e32 v64, 0x80, v184
	v_ashrrev_i32_e32 v65, 31, v64
	v_lshlrev_b64 v[64:65], 2, v[64:65]
	v_lshl_add_u64 v[66:67], s[56:57], 0, v[64:65]
	v_lshl_add_u64 v[68:69], s[60:61], 0, v[64:65]
	v_lshl_add_u64 v[64:65], s[16:17], 0, v[64:65]
	global_load_dwordx4 v[96:99], v[192:193], off offset:528
	global_load_dwordx4 v[76:79], v[192:193], off offset:512
	global_load_dwordx4 v[92:95], v[66:67], off offset:16
	global_load_dwordx4 v[72:75], v[66:67], off
	global_load_dwordx4 v[88:91], v[68:69], off offset:16
	s_nop 0
	global_load_dwordx4 v[68:71], v[68:69], off
	s_nop 0
	global_load_dwordx4 v[84:87], v[64:65], off offset:16
	s_nop 0
	global_load_dwordx4 v[64:67], v[64:65], off
	s_nop 0
	global_load_dwordx4 v[100:103], v[190:191], off offset:528
	global_load_dwordx4 v[80:83], v[190:191], off offset:512
	s_nop 1
	v_mov_b32_dpp v138, v60 row_ror:3 row_mask:0xf bank_mask:0xf
	v_mov_b32_dpp v139, v61 row_ror:1 row_mask:0xf bank_mask:0xf
	v_mov_b32_dpp v140, v61 row_ror:2 row_mask:0xf bank_mask:0xf
	v_mov_b32_dpp v141, v61 row_ror:3 row_mask:0xf bank_mask:0xf
	v_mov_b32_dpp v142, v62 row_ror:1 row_mask:0xf bank_mask:0xf
	v_mov_b32_dpp v143, v62 row_ror:2 row_mask:0xf bank_mask:0xf
	v_mov_b32_dpp v144, v62 row_ror:3 row_mask:0xf bank_mask:0xf
	v_mov_b32_dpp v145, v63 row_ror:1 row_mask:0xf bank_mask:0xf
	v_mov_b32_dpp v146, v63 row_ror:2 row_mask:0xf bank_mask:0xf
	v_mov_b32_dpp v147, v63 row_ror:3 row_mask:0xf bank_mask:0xf
	s_and_saveexec_b64 s[12:13], s[10:11]
	s_cbranch_execz .LBB0_158
	global_store_dwordx4 v[188:189], v[60:63], off offset:512
.LBB0_158:
	s_or_b64 exec, exec, s[12:13]
	s_nop 1
	v_mov_b32_dpp v124, v56 row_ror:1 row_mask:0xf bank_mask:0xf
	v_mov_b32_dpp v128, v56 row_ror:2 row_mask:0xf bank_mask:0xf
	v_mov_b32_dpp v132, v56 row_ror:3 row_mask:0xf bank_mask:0xf
	v_mov_b32_dpp v125, v57 row_ror:1 row_mask:0xf bank_mask:0xf
	v_mov_b32_dpp v129, v57 row_ror:2 row_mask:0xf bank_mask:0xf
	v_mov_b32_dpp v133, v57 row_ror:3 row_mask:0xf bank_mask:0xf
	v_mov_b32_dpp v126, v58 row_ror:1 row_mask:0xf bank_mask:0xf
	v_mov_b32_dpp v130, v58 row_ror:2 row_mask:0xf bank_mask:0xf
	v_mov_b32_dpp v134, v58 row_ror:3 row_mask:0xf bank_mask:0xf
	v_mov_b32_dpp v127, v59 row_ror:1 row_mask:0xf bank_mask:0xf
	v_mov_b32_dpp v131, v59 row_ror:2 row_mask:0xf bank_mask:0xf
	v_mov_b32_dpp v135, v59 row_ror:3 row_mask:0xf bank_mask:0xf
	s_and_saveexec_b64 s[12:13], s[8:9]
	s_xor_b64 s[34:35], exec, s[12:13]
	s_cbranch_execz .LBB0_160
	v_cndmask_b32_e64 v152, 0, v138, s[4:5]
	v_cndmask_b32_e64 v153, 0, v141, s[4:5]
	v_cndmask_b32_e64 v150, 0, v137, s[0:1]
	v_cndmask_b32_e64 v151, 0, v140, s[0:1]
	v_cndmask_b32_e64 v158, 0, v144, s[4:5]
	v_cndmask_b32_e64 v159, 0, v147, s[4:5]
	s_waitcnt vmcnt(0)
	v_pk_fma_f32 v[152:153], v[76:77], v[152:153], v[80:81]
	v_cndmask_b32_e32 v148, 0, v136, vcc
	v_cndmask_b32_e32 v149, 0, v139, vcc
	v_cndmask_b32_e64 v156, 0, v143, s[0:1]
	v_cndmask_b32_e64 v157, 0, v146, s[0:1]
	v_pk_fma_f32 v[158:159], v[78:79], v[158:159], v[82:83]
	v_pk_fma_f32 v[150:151], v[72:73], v[150:151], v[152:153]
	v_cndmask_b32_e32 v154, 0, v142, vcc
	v_cndmask_b32_e32 v155, 0, v145, vcc
	v_pk_fma_f32 v[156:157], v[74:75], v[156:157], v[158:159]
	v_pk_fma_f32 v[148:149], v[68:69], v[148:149], v[150:151]
	v_pk_fma_f32 v[150:151], v[70:71], v[154:155], v[156:157]
	v_pk_fma_f32 v[60:61], v[60:61], v[64:65], v[148:149]
	v_pk_fma_f32 v[148:149], v[98:99], v[134:135], v[102:103]
	v_pk_fma_f32 v[62:63], v[62:63], v[66:67], v[150:151]
	v_pk_fma_f32 v[150:151], v[96:97], v[132:133], v[100:101]
	v_pk_fma_f32 v[148:149], v[94:95], v[130:131], v[148:149]
	v_pk_fma_f32 v[150:151], v[92:93], v[128:129], v[150:151]
	v_pk_fma_f32 v[148:149], v[90:91], v[126:127], v[148:149]
	v_pk_fma_f32 v[150:151], v[88:89], v[124:125], v[150:151]
	v_pk_fma_f32 v[148:149], v[58:59], v[86:87], v[148:149]
	v_pk_fma_f32 v[150:151], v[56:57], v[84:85], v[150:151]
	v_cvt_pk_bf16_f32 v60, v60, v61
	v_cvt_pk_bf16_f32 v61, v62, v63
	s_nop 0
	v_cvt_pk_bf16_f32 v62, v150, v151
	v_cvt_pk_bf16_f32 v63, v148, v149
	v_lshlrev_b64 v[148:149], 12, v[186:187]
	v_lshl_add_u64 v[148:149], s[54:55], 0, v[148:149]
	v_lshl_add_u64 v[148:149], v[184:185], 1, v[148:149]
	global_store_dwordx4 v[148:149], v[60:63], off offset:256

; __device__ __forceinline__ unsigned cvt_pk_bf16(float lo, float hi) { unsigned r; asm volatile("v_cvt_pk_bf16_f32 %0, %1, %2" : "=v"(r) : "v"(lo), "v"(hi)); return r; }
;     __device__ __forceinline__ void operator()(EPI_ARGS) const {
;     ...
;                             for (int j = 0; j < 4; ++j) { r1[j] = __shfl(gv[j], s1); r2[j] = __shfl(gv[j], s2); r3[j] = __shfl(gv[j], s3); }
; #pragma unroll
;                             for (int j = 0; j < 4; ++j) { p1[j] = fr >= 1 ? r1[j] : q1[n][j]; p2[j] = fr >= 2 ? r2[j] : q2[n][j]; p3[j] = fr >= 3 ? r3[j] : q3[n][j]; }
;                             q1[n] = r1; q2[n] = r2; q3[n] = r3;
;                             o[n] = bb[n] + w0[n] * p3 + w1[n] * p2 + w2[n] * p1 + w3[n] * gv;
;                             if (m == 0 && fr < 3) *(f32x4*)(headu + ((size_t)blk * 3 + fr) * LW + c0 + 4 * n) = gv;
;                             if (m == 3 && fr >= 13) *(f32x4*)(tailu + ((size_t)blk * 3 + (fr - 13)) * LW + c0 + 4 * n) = gv;
;                         }
;                         if (!(m == 0 && fr < 3)) {
;                             u32x4 w; w.x = cvt_pk_bf16(o[0][0], o[0][1]); w.y = cvt_pk_bf16(o[0][2], o[0][3]); w.z = cvt_pk_bf16(o[1][0], o[1][1]); w.w = cvt_pk_bf16(o[1][2], o[1][3]);
;                             *(u32x4*)(vout + (size_t)row * LW + c0) = w;
.LBB0_162:
	s_or_b64 exec, exec, s[12:13]
	s_nop 1
	v_mov_b32_dpp v150, v52 row_ror:3 row_mask:0xf bank_mask:0xf
	v_mov_b32_dpp v151, v53 row_ror:1 row_mask:0xf bank_mask:0xf
	v_mov_b32_dpp v156, v54 row_ror:3 row_mask:0xf bank_mask:0xf
	v_mov_b32_dpp v159, v55 row_ror:3 row_mask:0xf bank_mask:0xf
	v_mov_b32_dpp v148, v52 row_ror:1 row_mask:0xf bank_mask:0xf
	v_mov_b32_dpp v149, v52 row_ror:2 row_mask:0xf bank_mask:0xf
	v_mov_b32_dpp v152, v53 row_ror:2 row_mask:0xf bank_mask:0xf
	v_mov_b32_dpp v155, v54 row_ror:2 row_mask:0xf bank_mask:0xf
	v_mov_b32_dpp v158, v55 row_ror:2 row_mask:0xf bank_mask:0xf
	v_mov_b32_dpp v153, v53 row_ror:3 row_mask:0xf bank_mask:0xf
	v_mov_b32_dpp v154, v54 row_ror:1 row_mask:0xf bank_mask:0xf
	v_mov_b32_dpp v157, v55 row_ror:1 row_mask:0xf bank_mask:0xf
	v_cndmask_b32_e64 v60, v138, v150, s[4:5]
	v_cndmask_b32_e32 v57, v139, v151, vcc
	v_cndmask_b32_e64 v138, v144, v156, s[4:5]
	v_cndmask_b32_e64 v139, v147, v159, s[4:5]
	v_cndmask_b32_e32 v56, v136, v148, vcc
	v_cndmask_b32_e64 v58, v137, v149, s[0:1]
	v_cndmask_b32_e64 v59, v140, v152, s[0:1]
	v_cndmask_b32_e64 v136, v143, v155, s[0:1]
	v_cndmask_b32_e64 v137, v146, v158, s[0:1]
	s_waitcnt vmcnt(0)
; __device__ __forceinline__ unsigned cvt_pk_bf16(float lo, float hi) { unsigned r; asm volatile("v_cvt_pk_bf16_f32 %0, %1, %2" : "=v"(r) : "v"(lo), "v"(hi)); return r; }
;     __device__ __forceinline__ void operator()(EPI_ARGS) const {
;     ...
;                             for (int j = 0; j < 4; ++j) { r1[j] = __shfl(gv[j], s1); r2[j] = __shfl(gv[j], s2); r3[j] = __shfl(gv[j], s3); }
; #pragma unroll
;                             for (int j = 0; j < 4; ++j) { p1[j] = fr >= 1 ? r1[j] : q1[n][j]; p2[j] = fr >= 2 ? r2[j] : q2[n][j]; p3[j] = fr >= 3 ? r3[j] : q3[n][j]; }
;                             q1[n] = r1; q2[n] = r2; q3[n] = r3;
;                             o[n] = bb[n] + w0[n] * p3 + w1[n] * p2 + w2[n] * p1 + w3[n] * gv;
;                             if (m == 0 && fr < 3) *(f32x4*)(headu + ((size_t)blk * 3 + fr) * LW + c0 + 4 * n) = gv;
;                             if (m == 3 && fr >= 13) *(f32x4*)(tailu + ((size_t)blk * 3 + (fr - 13)) * LW + c0 + 4 * n) = gv;
;                         }
;                         if (!(m == 0 && fr < 3)) {
;                             u32x4 w; w.x = cvt_pk_bf16(o[0][0], o[0][1]); w.y = cvt_pk_bf16(o[0][2], o[0][3]); w.z = cvt_pk_bf16(o[1][0], o[1][1]); w.w = cvt_pk_bf16(o[1][2], o[1][3]);
;                             *(u32x4*)(vout + (size_t)row * LW + c0) = w;
	v_pk_fma_f32 v[138:139], v[78:79], v[138:139], v[82:83]
	s_nop 1
	v_mov_b32_dpp v140, v48 row_ror:3 row_mask:0xf bank_mask:0xf
	v_mov_b32_dpp v143, v49 row_ror:3 row_mask:0xf bank_mask:0xf
	v_mov_b32_dpp v144, v50 row_ror:1 row_mask:0xf bank_mask:0xf
	v_mov_b32_dpp v146, v50 row_ror:3 row_mask:0xf bank_mask:0xf
	v_mov_b32_dpp v147, v51 row_ror:1 row_mask:0xf bank_mask:0xf
	v_mov_b32_dpp v161, v51 row_ror:3 row_mask:0xf bank_mask:0xf
	v_cndmask_b32_e64 v61, v141, v153, s[4:5]
	v_cndmask_b32_e32 v62, v142, v154, vcc
	v_cndmask_b32_e32 v63, v145, v157, vcc
	v_pk_fma_f32 v[136:137], v[74:75], v[136:137], v[138:139]
	s_nop 1
	v_mov_b32_dpp v138, v48 row_ror:1 row_mask:0xf bank_mask:0xf
	v_mov_b32_dpp v139, v48 row_ror:2 row_mask:0xf bank_mask:0xf
	v_mov_b32_dpp v141, v49 row_ror:1 row_mask:0xf bank_mask:0xf
	v_mov_b32_dpp v142, v49 row_ror:2 row_mask:0xf bank_mask:0xf
	v_mov_b32_dpp v145, v50 row_ror:2 row_mask:0xf bank_mask:0xf
	v_mov_b32_dpp v160, v51 row_ror:2 row_mask:0xf bank_mask:0xf
	v_pk_fma_f32 v[60:61], v[76:77], v[60:61], v[80:81]
	s_nop 0
	v_pk_fma_f32 v[58:59], v[72:73], v[58:59], v[60:61]
	v_cndmask_b32_e64 v60, v132, v140, s[4:5]
	v_pk_fma_f32 v[56:57], v[68:69], v[56:57], v[58:59]
	v_pk_fma_f32 v[58:59], v[70:71], v[62:63], v[136:137]
	v_cndmask_b32_e64 v61, v133, v143, s[4:5]
	v_cndmask_b32_e32 v62, v126, v144, vcc
	v_cndmask_b32_e64 v126, v134, v146, s[4:5]
	v_cndmask_b32_e32 v63, v127, v147, vcc
	v_cndmask_b32_e64 v127, v135, v161, s[4:5]
	v_pk_fma_f32 v[54:55], v[54:55], v[66:67], v[58:59]
	v_pk_fma_f32 v[52:53], v[52:53], v[64:65], v[56:57]
	v_cndmask_b32_e32 v56, v124, v138, vcc
	v_cndmask_b32_e64 v58, v128, v139, s[0:1]
	v_cndmask_b32_e32 v57, v125, v141, vcc
	v_cndmask_b32_e64 v59, v129, v142, s[0:1]
	v_cndmask_b32_e64 v124, v130, v145, s[0:1]
	v_cndmask_b32_e64 v125, v131, v160, s[0:1]
	v_pk_fma_f32 v[60:61], v[96:97], v[60:61], v[100:101]
	v_pk_fma_f32 v[126:127], v[98:99], v[126:127], v[102:103]
	v_pk_fma_f32 v[58:59], v[92:93], v[58:59], v[60:61]
	v_pk_fma_f32 v[124:125], v[94:95], v[124:125], v[126:127]
	v_pk_fma_f32 v[56:57], v[88:89], v[56:57], v[58:59]
	v_pk_fma_f32 v[58:59], v[90:91], v[62:63], v[124:125]
	s_nop 0
	v_pk_fma_f32 v[58:59], v[50:51], v[86:87], v[58:59]
	v_pk_fma_f32 v[50:51], v[48:49], v[84:85], v[56:57]
	v_cvt_pk_bf16_f32 v48, v52, v53
	v_cvt_pk_bf16_f32 v49, v54, v55
	s_nop 1
	v_mov_b32_dpp v53, v45 row_ror:3 row_mask:0xf bank_mask:0xf
	v_cvt_pk_bf16_f32 v50, v50, v51
	v_cvt_pk_bf16_f32 v51, v58, v59
	global_store_dwordx4 v[112:113], v[48:51], off offset:256
	s_nop 1
	v_mov_b32_dpp v50, v44 row_ror:3 row_mask:0xf bank_mask:0xf
	v_mov_b32_dpp v56, v46 row_ror:3 row_mask:0xf bank_mask:0xf
	v_mov_b32_dpp v59, v47 row_ror:3 row_mask:0xf bank_mask:0xf
	v_mov_b32_dpp v49, v44 row_ror:2 row_mask:0xf bank_mask:0xf
	v_mov_b32_dpp v52, v45 row_ror:2 row_mask:0xf bank_mask:0xf
	v_mov_b32_dpp v55, v46 row_ror:2 row_mask:0xf bank_mask:0xf
	v_mov_b32_dpp v58, v47 row_ror:2 row_mask:0xf bank_mask:0xf
	v_mov_b32_dpp v48, v44 row_ror:1 row_mask:0xf bank_mask:0xf
	v_mov_b32_dpp v51, v45 row_ror:1 row_mask:0xf bank_mask:0xf
	v_mov_b32_dpp v54, v46 row_ror:1 row_mask:0xf bank_mask:0xf
	v_mov_b32_dpp v57, v47 row_ror:1 row_mask:0xf bank_mask:0xf
	v_cndmask_b32_e64 v112, v150, v50, s[4:5]
	v_cndmask_b32_e64 v113, v153, v53, s[4:5]
	v_cndmask_b32_e64 v128, v156, v56, s[4:5]
	v_cndmask_b32_e64 v129, v159, v59, s[4:5]
	v_cndmask_b32_e64 v62, v149, v49, s[0:1]
	v_cndmask_b32_e64 v63, v152, v52, s[0:1]
	v_cndmask_b32_e64 v126, v155, v55, s[0:1]
	v_cndmask_b32_e64 v127, v158, v58, s[0:1]
	v_pk_fma_f32 v[112:113], v[76:77], v[112:113], v[80:81]
	v_pk_fma_f32 v[128:129], v[78:79], v[128:129], v[82:83]
	v_cndmask_b32_e32 v60, v148, v48, vcc
	v_cndmask_b32_e32 v61, v151, v51, vcc
	v_cndmask_b32_e32 v124, v154, v54, vcc
	v_cndmask_b32_e32 v125, v157, v57, vcc
	v_pk_fma_f32 v[126:127], v[74:75], v[126:127], v[128:129]
	v_pk_fma_f32 v[62:63], v[72:73], v[62:63], v[112:113]
	s_nop 1
	v_mov_b32_dpp v112, v42 row_ror:3 row_mask:0xf bank_mask:0xf
	v_pk_fma_f32 v[60:61], v[68:69], v[60:61], v[62:63]
	v_pk_fma_f32 v[62:63], v[70:71], v[124:125], v[126:127]
	v_pk_fma_f32 v[126:127], v[44:45], v[64:65], v[60:61]
	v_pk_fma_f32 v[136:137], v[46:47], v[66:67], v[62:63]
	s_nop 1
	v_mov_b32_dpp v46, v40 row_ror:3 row_mask:0xf bank_mask:0xf
	v_mov_b32_dpp v47, v41 row_ror:1 row_mask:0xf bank_mask:0xf
	v_mov_b32_dpp v61, v41 row_ror:3 row_mask:0xf bank_mask:0xf
	v_mov_b32_dpp v125, v43 row_ror:3 row_mask:0xf bank_mask:0xf
	v_mov_b32_dpp v44, v40 row_ror:1 row_mask:0xf bank_mask:0xf
	v_mov_b32_dpp v45, v40 row_ror:2 row_mask:0xf bank_mask:0xf
	v_mov_b32_dpp v60, v41 row_ror:2 row_mask:0xf bank_mask:0xf
	v_mov_b32_dpp v63, v42 row_ror:2 row_mask:0xf bank_mask:0xf
	v_mov_b32_dpp v124, v43 row_ror:2 row_mask:0xf bank_mask:0xf
	v_mov_b32_dpp v62, v42 row_ror:1 row_mask:0xf bank_mask:0xf
	v_mov_b32_dpp v113, v43 row_ror:1 row_mask:0xf bank_mask:0xf
	v_cndmask_b32_e64 v132, v140, v46, s[4:5]
	v_cndmask_b32_e32 v129, v141, v47, vcc
	v_cndmask_b32_e64 v133, v143, v61, s[4:5]
	v_cndmask_b32_e64 v140, v146, v112, s[4:5]
	v_cndmask_b32_e64 v141, v161, v125, s[4:5]
	v_cndmask_b32_e32 v128, v138, v44, vcc
	v_cndmask_b32_e64 v130, v139, v45, s[0:1]
	v_cndmask_b32_e64 v131, v142, v60, s[0:1]
	v_cndmask_b32_e64 v138, v145, v63, s[0:1]
	v_cndmask_b32_e64 v139, v160, v124, s[0:1]
	v_pk_fma_f32 v[132:133], v[96:97], v[132:133], v[100:101]
	v_pk_fma_f32 v[140:141], v[98:99], v[140:141], v[102:103]
	v_cndmask_b32_e32 v134, v144, v62, vcc
	v_cndmask_b32_e32 v135, v147, v113, vcc
	v_pk_fma_f32 v[138:139], v[94:95], v[138:139], v[140:141]
	v_pk_fma_f32 v[130:131], v[92:93], v[130:131], v[132:133]
	s_nop 1
	v_mov_b32_dpp v132, v35 row_ror:2 row_mask:0xf bank_mask:0xf
	v_pk_fma_f32 v[128:129], v[88:89], v[128:129], v[130:131]
	v_pk_fma_f32 v[130:131], v[90:91], v[134:135], v[138:139]
	v_pk_fma_f32 v[140:141], v[40:41], v[84:85], v[128:129]
	v_pk_fma_f32 v[138:139], v[42:43], v[86:87], v[130:131]
	v_cvt_pk_bf16_f32 v134, v126, v127
	s_nop 1
	v_mov_b32_dpp v40, v32 row_ror:1 row_mask:0xf bank_mask:0xf
	v_mov_b32_dpp v41, v32 row_ror:2 row_mask:0xf bank_mask:0xf
	v_mov_b32_dpp v42, v32 row_ror:3 row_mask:0xf bank_mask:0xf
	v_mov_b32_dpp v43, v33 row_ror:1 row_mask:0xf bank_mask:0xf
	v_mov_b32_dpp v126, v33 row_ror:2 row_mask:0xf bank_mask:0xf
	v_mov_b32_dpp v127, v33 row_ror:3 row_mask:0xf bank_mask:0xf
	v_mov_b32_dpp v128, v34 row_ror:1 row_mask:0xf bank_mask:0xf
	v_mov_b32_dpp v129, v34 row_ror:2 row_mask:0xf bank_mask:0xf
	v_mov_b32_dpp v130, v34 row_ror:3 row_mask:0xf bank_mask:0xf
	v_mov_b32_dpp v131, v35 row_ror:1 row_mask:0xf bank_mask:0xf
	v_mov_b32_dpp v133, v35 row_ror:3 row_mask:0xf bank_mask:0xf
	v_cvt_pk_bf16_f32 v135, v136, v137
	v_cvt_pk_bf16_f32 v136, v140, v141
	v_cvt_pk_bf16_f32 v137, v138, v139
	global_store_dwordx4 v[114:115], v[134:137], off offset:256
	s_and_saveexec_b64 s[12:13], s[6:7]
	s_cbranch_execz .LBB0_164
	global_store_dwordx4 v[108:109], v[32:35], off offset:512

; __device__ __forceinline__ unsigned cvt_pk_bf16(float lo, float hi) { unsigned r; asm volatile("v_cvt_pk_bf16_f32 %0, %1, %2" : "=v"(r) : "v"(lo), "v"(hi)); return r; }
;     __device__ __forceinline__ void operator()(EPI_ARGS) const {
;     ...
;                             for (int j = 0; j < 4; ++j) { r1[j] = __shfl(gv[j], s1); r2[j] = __shfl(gv[j], s2); r3[j] = __shfl(gv[j], s3); }
; #pragma unroll
;                             for (int j = 0; j < 4; ++j) { p1[j] = fr >= 1 ? r1[j] : q1[n][j]; p2[j] = fr >= 2 ? r2[j] : q2[n][j]; p3[j] = fr >= 3 ? r3[j] : q3[n][j]; }
;                             q1[n] = r1; q2[n] = r2; q3[n] = r3;
;                             o[n] = bb[n] + w0[n] * p3 + w1[n] * p2 + w2[n] * p1 + w3[n] * gv;
;                             if (m == 0 && fr < 3) *(f32x4*)(headu + ((size_t)blk * 3 + fr) * LW + c0 + 4 * n) = gv;
;                             if (m == 3 && fr >= 13) *(f32x4*)(tailu + ((size_t)blk * 3 + (fr - 13)) * LW + c0 + 4 * n) = gv;
;                         }
;                         if (!(m == 0 && fr < 3)) {
;                             u32x4 w; w.x = cvt_pk_bf16(o[0][0], o[0][1]); w.y = cvt_pk_bf16(o[0][2], o[0][3]); w.z = cvt_pk_bf16(o[1][0], o[1][1]); w.w = cvt_pk_bf16(o[1][2], o[1][3]);
;                             *(u32x4*)(vout + (size_t)row * LW + c0) = w;
.LBB0_166:
	s_or_b64 exec, exec, s[12:13]
	v_cndmask_b32_e64 v108, v45, v115, s[0:1]
	v_cndmask_b32_e64 v46, v46, v134, s[4:5]
	v_cndmask_b32_e32 v45, v47, v135, vcc
	v_cndmask_b32_e64 v47, v61, v137, s[4:5]
	v_cndmask_b32_e64 v109, v60, v136, s[0:1]
	v_pk_fma_f32 v[46:47], v[96:97], v[46:47], v[100:101]
	v_cndmask_b32_e32 v44, v44, v114, vcc
	v_cndmask_b32_e64 v112, v112, v140, s[4:5]
	v_cndmask_b32_e32 v61, v113, v141, vcc
	v_cndmask_b32_e64 v113, v125, v143, s[4:5]
	v_pk_fma_f32 v[46:47], v[92:93], v[108:109], v[46:47]
	v_cndmask_b32_e32 v60, v62, v138, vcc
	v_cndmask_b32_e64 v62, v63, v139, s[0:1]
	v_cndmask_b32_e64 v63, v124, v142, s[0:1]
	v_pk_fma_f32 v[112:113], v[98:99], v[112:113], v[102:103]
	v_pk_fma_f32 v[44:45], v[88:89], v[44:45], v[46:47]
	v_pk_fma_f32 v[62:63], v[94:95], v[62:63], v[112:113]
	v_pk_fma_f32 v[36:37], v[36:37], v[84:85], v[44:45]
	v_cndmask_b32_e64 v44, v49, v41, s[0:1]
	v_cndmask_b32_e64 v42, v50, v42, s[4:5]
	v_cndmask_b32_e32 v41, v51, v43, vcc
	v_cndmask_b32_e64 v43, v53, v127, s[4:5]
	v_cndmask_b32_e64 v50, v56, v130, s[4:5]
	v_cndmask_b32_e64 v51, v59, v133, s[4:5]
	v_pk_fma_f32 v[46:47], v[90:91], v[60:61], v[62:63]
	v_cndmask_b32_e32 v40, v48, v40, vcc
	v_cndmask_b32_e64 v45, v52, v126, s[0:1]
	v_cndmask_b32_e64 v48, v55, v129, s[0:1]
	v_cndmask_b32_e64 v49, v58, v132, s[0:1]
	v_pk_fma_f32 v[42:43], v[76:77], v[42:43], v[80:81]
	v_pk_fma_f32 v[50:51], v[78:79], v[50:51], v[82:83]
	v_pk_fma_f32 v[38:39], v[38:39], v[86:87], v[46:47]
	v_cndmask_b32_e32 v46, v54, v128, vcc
	v_cndmask_b32_e32 v47, v57, v131, vcc
	v_pk_fma_f32 v[48:49], v[74:75], v[48:49], v[50:51]
	v_pk_fma_f32 v[42:43], v[72:73], v[44:45], v[42:43]
	s_nop 1
	v_mov_b32_dpp v44, v28 row_ror:1 row_mask:0xf bank_mask:0xf
	v_pk_fma_f32 v[40:41], v[68:69], v[40:41], v[42:43]
	v_pk_fma_f32 v[42:43], v[70:71], v[46:47], v[48:49]
	s_nop 1
	v_mov_b32_dpp v45, v28 row_ror:2 row_mask:0xf bank_mask:0xf
	v_mov_b32_dpp v46, v28 row_ror:3 row_mask:0xf bank_mask:0xf
	v_mov_b32_dpp v47, v29 row_ror:1 row_mask:0xf bank_mask:0xf
	v_mov_b32_dpp v48, v29 row_ror:2 row_mask:0xf bank_mask:0xf
	v_mov_b32_dpp v49, v29 row_ror:3 row_mask:0xf bank_mask:0xf
	v_mov_b32_dpp v50, v30 row_ror:1 row_mask:0xf bank_mask:0xf
	v_mov_b32_dpp v51, v30 row_ror:2 row_mask:0xf bank_mask:0xf
	v_mov_b32_dpp v52, v30 row_ror:3 row_mask:0xf bank_mask:0xf
	v_mov_b32_dpp v53, v31 row_ror:1 row_mask:0xf bank_mask:0xf
	v_mov_b32_dpp v54, v31 row_ror:2 row_mask:0xf bank_mask:0xf
	v_mov_b32_dpp v55, v31 row_ror:3 row_mask:0xf bank_mask:0xf
	v_pk_fma_f32 v[34:35], v[34:35], v[66:67], v[42:43]
	v_pk_fma_f32 v[32:33], v[32:33], v[64:65], v[40:41]
	s_nop 0
	v_cvt_pk_bf16_f32 v32, v32, v33
	v_cvt_pk_bf16_f32 v33, v34, v35
	v_cvt_pk_bf16_f32 v34, v36, v37
	v_cvt_pk_bf16_f32 v35, v38, v39
	global_store_dwordx4 v[110:111], v[32:35], off offset:256
	s_and_saveexec_b64 s[12:13], s[10:11]
	s_cbranch_execz .LBB0_168
	global_store_dwordx4 v[106:107], v[28:31], off offset:512
.LBB0_168:
	s_or_b64 exec, exec, s[12:13]
	s_nop 1
	v_mov_b32_dpp v32, v24 row_ror:1 row_mask:0xf bank_mask:0xf
	v_mov_b32_dpp v36, v24 row_ror:2 row_mask:0xf bank_mask:0xf
	v_mov_b32_dpp v40, v24 row_ror:3 row_mask:0xf bank_mask:0xf
	v_mov_b32_dpp v33, v25 row_ror:1 row_mask:0xf bank_mask:0xf
	v_mov_b32_dpp v37, v25 row_ror:2 row_mask:0xf bank_mask:0xf
	v_mov_b32_dpp v41, v25 row_ror:3 row_mask:0xf bank_mask:0xf
	v_mov_b32_dpp v34, v26 row_ror:1 row_mask:0xf bank_mask:0xf
	v_mov_b32_dpp v38, v26 row_ror:2 row_mask:0xf bank_mask:0xf
	v_mov_b32_dpp v42, v26 row_ror:3 row_mask:0xf bank_mask:0xf
	v_mov_b32_dpp v35, v27 row_ror:1 row_mask:0xf bank_mask:0xf
	v_mov_b32_dpp v39, v27 row_ror:2 row_mask:0xf bank_mask:0xf
	v_mov_b32_dpp v43, v27 row_ror:3 row_mask:0xf bank_mask:0xf
	s_and_saveexec_b64 s[10:11], s[8:9]
	s_xor_b64 s[8:9], exec, s[10:11]
	s_cbranch_execz .LBB0_170
	v_cndmask_b32_e64 v60, 0, v46, s[4:5]
	v_cndmask_b32_e64 v61, 0, v49, s[4:5]
	v_cndmask_b32_e64 v58, 0, v45, s[0:1]
	v_cndmask_b32_e64 v59, 0, v48, s[0:1]
	v_cndmask_b32_e64 v108, 0, v52, s[4:5]
	v_cndmask_b32_e64 v109, 0, v55, s[4:5]
	v_pk_fma_f32 v[60:61], v[76:77], v[60:61], v[80:81]
	v_cndmask_b32_e32 v56, 0, v44, vcc
	v_cndmask_b32_e32 v57, 0, v47, vcc
	v_cndmask_b32_e64 v106, 0, v51, s[0:1]
	v_cndmask_b32_e64 v107, 0, v54, s[0:1]
	v_pk_fma_f32 v[108:109], v[78:79], v[108:109], v[82:83]
	v_pk_fma_f32 v[58:59], v[72:73], v[58:59], v[60:61]
	v_cndmask_b32_e32 v62, 0, v50, vcc
	v_cndmask_b32_e32 v63, 0, v53, vcc
	v_pk_fma_f32 v[106:107], v[74:75], v[106:107], v[108:109]
	v_pk_fma_f32 v[56:57], v[68:69], v[56:57], v[58:59]
	v_pk_fma_f32 v[58:59], v[70:71], v[62:63], v[106:107]
	v_pk_fma_f32 v[28:29], v[28:29], v[64:65], v[56:57]
	v_pk_fma_f32 v[56:57], v[98:99], v[42:43], v[102:103]
	v_pk_fma_f32 v[30:31], v[30:31], v[66:67], v[58:59]
	v_pk_fma_f32 v[58:59], v[96:97], v[40:41], v[100:101]
	v_pk_fma_f32 v[56:57], v[94:95], v[38:39], v[56:57]
	v_pk_fma_f32 v[58:59], v[92:93], v[36:37], v[58:59]
	v_pk_fma_f32 v[56:57], v[90:91], v[34:35], v[56:57]
	v_pk_fma_f32 v[58:59], v[88:89], v[32:33], v[58:59]
	v_pk_fma_f32 v[56:57], v[26:27], v[86:87], v[56:57]
	v_pk_fma_f32 v[58:59], v[24:25], v[84:85], v[58:59]
	v_cvt_pk_bf16_f32 v28, v28, v29
	v_cvt_pk_bf16_f32 v29, v30, v31
	s_nop 0
	v_cvt_pk_bf16_f32 v30, v58, v59
	v_cvt_pk_bf16_f32 v31, v56, v57
	v_lshlrev_b64 v[56:57], 12, v[104:105]
	v_lshl_add_u64 v[56:57], s[54:55], 0, v[56:57]
	v_lshl_add_u64 v[56:57], v[184:185], 1, v[56:57]
	global_store_dwordx4 v[56:57], v[28:31], off offset:256

; __device__ __forceinline__ unsigned cvt_pk_bf16(float lo, float hi) { unsigned r; asm volatile("v_cvt_pk_bf16_f32 %0, %1, %2" : "=v"(r) : "v"(lo), "v"(hi)); return r; }
;     __device__ __forceinline__ void operator()(EPI_ARGS) const {
;     ...
;                             for (int j = 0; j < 4; ++j) { r1[j] = __shfl(gv[j], s1); r2[j] = __shfl(gv[j], s2); r3[j] = __shfl(gv[j], s3); }
; #pragma unroll
;                             for (int j = 0; j < 4; ++j) { p1[j] = fr >= 1 ? r1[j] : q1[n][j]; p2[j] = fr >= 2 ? r2[j] : q2[n][j]; p3[j] = fr >= 3 ? r3[j] : q3[n][j]; }
;                             q1[n] = r1; q2[n] = r2; q3[n] = r3;
;                             o[n] = bb[n] + w0[n] * p3 + w1[n] * p2 + w2[n] * p1 + w3[n] * gv;
;                             if (m == 0 && fr < 3) *(f32x4*)(headu + ((size_t)blk * 3 + fr) * LW + c0 + 4 * n) = gv;
;                             if (m == 3 && fr >= 13) *(f32x4*)(tailu + ((size_t)blk * 3 + (fr - 13)) * LW + c0 + 4 * n) = gv;
;                         }
;                         if (!(m == 0 && fr < 3)) {
;                             u32x4 w; w.x = cvt_pk_bf16(o[0][0], o[0][1]); w.y = cvt_pk_bf16(o[0][2], o[0][3]); w.z = cvt_pk_bf16(o[1][0], o[1][1]); w.w = cvt_pk_bf16(o[1][2], o[1][3]);
;                             *(u32x4*)(vout + (size_t)row * LW + c0) = w;
.LBB0_172:
	s_or_b64 exec, exec, s[8:9]
	s_nop 1
	v_mov_b32_dpp v58, v20 row_ror:3 row_mask:0xf bank_mask:0xf
	v_mov_b32_dpp v59, v21 row_ror:1 row_mask:0xf bank_mask:0xf
	v_mov_b32_dpp v61, v21 row_ror:3 row_mask:0xf bank_mask:0xf
	v_mov_b32_dpp v104, v22 row_ror:3 row_mask:0xf bank_mask:0xf
	v_mov_b32_dpp v107, v23 row_ror:3 row_mask:0xf bank_mask:0xf
	v_mov_b32_dpp v56, v20 row_ror:1 row_mask:0xf bank_mask:0xf
	v_mov_b32_dpp v57, v20 row_ror:2 row_mask:0xf bank_mask:0xf
	v_mov_b32_dpp v60, v21 row_ror:2 row_mask:0xf bank_mask:0xf
	v_mov_b32_dpp v63, v22 row_ror:2 row_mask:0xf bank_mask:0xf
	v_mov_b32_dpp v106, v23 row_ror:2 row_mask:0xf bank_mask:0xf
	v_mov_b32_dpp v62, v22 row_ror:1 row_mask:0xf bank_mask:0xf
	v_mov_b32_dpp v105, v23 row_ror:1 row_mask:0xf bank_mask:0xf
	v_cndmask_b32_e64 v28, v46, v58, s[4:5]
	v_cndmask_b32_e32 v25, v47, v59, vcc
	v_cndmask_b32_e64 v29, v49, v61, s[4:5]
	v_cndmask_b32_e64 v46, v52, v104, s[4:5]
	v_cndmask_b32_e64 v47, v55, v107, s[4:5]
	v_cndmask_b32_e32 v24, v44, v56, vcc
	v_cndmask_b32_e64 v26, v45, v57, s[0:1]
	v_cndmask_b32_e64 v27, v48, v60, s[0:1]
	v_cndmask_b32_e64 v44, v51, v63, s[0:1]
	v_cndmask_b32_e64 v45, v54, v106, s[0:1]
	v_pk_fma_f32 v[28:29], v[76:77], v[28:29], v[80:81]
	v_pk_fma_f32 v[46:47], v[78:79], v[46:47], v[82:83]
	v_cndmask_b32_e32 v30, v50, v62, vcc
	v_cndmask_b32_e32 v31, v53, v105, vcc
	v_pk_fma_f32 v[44:45], v[74:75], v[44:45], v[46:47]
	v_pk_fma_f32 v[26:27], v[72:73], v[26:27], v[28:29]
	s_nop 1
	v_mov_b32_dpp v48, v16 row_ror:3 row_mask:0xf bank_mask:0xf
	v_mov_b32_dpp v51, v17 row_ror:3 row_mask:0xf bank_mask:0xf
	v_mov_b32_dpp v52, v18 row_ror:1 row_mask:0xf bank_mask:0xf
	v_mov_b32_dpp v54, v18 row_ror:3 row_mask:0xf bank_mask:0xf
	v_mov_b32_dpp v55, v19 row_ror:1 row_mask:0xf bank_mask:0xf
	v_mov_b32_dpp v109, v19 row_ror:3 row_mask:0xf bank_mask:0xf
	v_pk_fma_f32 v[24:25], v[68:69], v[24:25], v[26:27]
	v_pk_fma_f32 v[26:27], v[70:71], v[30:31], v[44:45]
	s_nop 1
	v_mov_b32_dpp v44, v16 row_ror:1 row_mask:0xf bank_mask:0xf
	v_mov_b32_dpp v45, v16 row_ror:2 row_mask:0xf bank_mask:0xf
	v_mov_b32_dpp v49, v17 row_ror:1 row_mask:0xf bank_mask:0xf
	v_mov_b32_dpp v50, v17 row_ror:2 row_mask:0xf bank_mask:0xf
	v_mov_b32_dpp v53, v18 row_ror:2 row_mask:0xf bank_mask:0xf
	v_mov_b32_dpp v108, v19 row_ror:2 row_mask:0xf bank_mask:0xf
	v_cndmask_b32_e64 v28, v40, v48, s[4:5]
	v_cndmask_b32_e64 v29, v41, v51, s[4:5]
	v_cndmask_b32_e32 v30, v34, v52, vcc
	v_cndmask_b32_e64 v34, v42, v54, s[4:5]
	v_cndmask_b32_e32 v31, v35, v55, vcc
	v_cndmask_b32_e64 v35, v43, v109, s[4:5]
	v_pk_fma_f32 v[22:23], v[22:23], v[66:67], v[26:27]
	v_pk_fma_f32 v[20:21], v[20:21], v[64:65], v[24:25]
	v_cndmask_b32_e32 v24, v32, v44, vcc
	v_cndmask_b32_e64 v26, v36, v45, s[0:1]
	v_cndmask_b32_e32 v25, v33, v49, vcc
	v_cndmask_b32_e64 v27, v37, v50, s[0:1]
	v_cndmask_b32_e64 v32, v38, v53, s[0:1]
	v_cndmask_b32_e64 v33, v39, v108, s[0:1]
	v_pk_fma_f32 v[28:29], v[96:97], v[28:29], v[100:101]
	v_pk_fma_f32 v[34:35], v[98:99], v[34:35], v[102:103]
	v_pk_fma_f32 v[26:27], v[92:93], v[26:27], v[28:29]
	v_pk_fma_f32 v[32:33], v[94:95], v[32:33], v[34:35]
	v_pk_fma_f32 v[24:25], v[88:89], v[24:25], v[26:27]
	v_pk_fma_f32 v[26:27], v[90:91], v[30:31], v[32:33]
	s_nop 0
	v_pk_fma_f32 v[26:27], v[18:19], v[86:87], v[26:27]
	v_pk_fma_f32 v[18:19], v[16:17], v[84:85], v[24:25]
	v_cvt_pk_bf16_f32 v16, v20, v21
	v_cvt_pk_bf16_f32 v17, v22, v23
	s_nop 1
	v_mov_b32_dpp v21, v13 row_ror:3 row_mask:0xf bank_mask:0xf
	v_cvt_pk_bf16_f32 v18, v18, v19
	v_cvt_pk_bf16_f32 v19, v26, v27
	global_store_dwordx4 v[118:119], v[16:19], off offset:256
	s_nop 1
	v_mov_b32_dpp v18, v12 row_ror:3 row_mask:0xf bank_mask:0xf
	v_mov_b32_dpp v24, v14 row_ror:3 row_mask:0xf bank_mask:0xf
	v_mov_b32_dpp v27, v15 row_ror:3 row_mask:0xf bank_mask:0xf
	v_mov_b32_dpp v17, v12 row_ror:2 row_mask:0xf bank_mask:0xf
	v_mov_b32_dpp v20, v13 row_ror:2 row_mask:0xf bank_mask:0xf
;     __device__ __forceinline__ void operator()(EPI_ARGS) const {
;     ...
;             const int lane = fq * 16 + fr, s1 = (lane & 48) | ((fr - 1) & 15), s2 = (lane & 48) | ((fr - 2) & 15), s3 = (lane & 48) | ((fr - 3) & 15);
; #pragma unroll
;             for (int bj = 0; bj < 2; ++bj) {
;                 const int c0 = (pn - 4) * 256 + bj * 128 + wc * 32 + 8 * fq;
;                 f32x4 w0[2], w1[2], w2[2], w3[2], bb[2];
; #pragma unroll
;                 for (int n = 0; n < 2; ++n) { w0[n] = *(const f32x4*)(cw + c0 + 4 * n); w1[n] = *(const f32x4*)(cw + LW + c0 + 4 * n); w2[n] = *(const f32x4*)(cw + 2 * LW + c0 + 4 * n); w3[n] = *(const f32x4*)(cw + 3 * LW + c0 + 4 * n); bb[n] = *(const f32x4*)(cb + c0 + 4 * n); }
; #pragma unroll
;                 for (int ai = 0; ai < 2; ++ai) {
;                     const int blk = u.pm * 4 + ai * 2 + wr;
;                     f32x4 q1[2], q2[2], q3[2];
; #pragma unroll
;                     for (int n = 0; n < 2; ++n) { q1[n] = (f32x4){0.f, 0.f, 0.f, 0.f}; q2[n] = q1[n]; q3[n] = q1[n]; }
; #pragma unroll
;                     for (int m = 0; m < 4; ++m) {
;                         const int row = ROW_OF(ai, m);
;                         f32x4 o[2];
; #pragma unroll
;                         for (int n = 0; n < 2; ++n) {
;                             const f32x4 gv = acc[ai][bj][m][n];
;                             f32x4 r1, r2, r3, p1, p2, p3;
; #pragma unroll
;                             for (int j = 0; j < 4; ++j) { r1[j] = __shfl(gv[j], s1); r2[j] = __shfl(gv[j], s2); r3[j] = __shfl(gv[j], s3); }
; #pragma unroll
;                             for (int j = 0; j < 4; ++j) { p1[j] = fr >= 1 ? r1[j] : q1[n][j]; p2[j] = fr >= 2 ? r2[j] : q2[n][j]; p3[j] = fr >= 3 ? r3[j] : q3[n][j]; }
;                             q1[n] = r1; q2[n] = r2; q3[n] = r3;
;                             o[n] = bb[n] + w0[n] * p3 + w1[n] * p2 + w2[n] * p1 + w3[n] * gv;
;                             if (m == 0 && fr < 3) *(f32x4*)(headu + ((size_t)blk * 3 + fr) * LW + c0 + 4 * n) = gv;
;                             if (m == 3 && fr >= 13) *(f32x4*)(tailu + ((size_t)blk * 3 + (fr - 13)) * LW + c0 + 4 * n) = gv;
;                         }
;                         if (!(m == 0 && fr < 3)) {
	v_mov_b32_dpp v23, v14 row_ror:2 row_mask:0xf bank_mask:0xf
	v_mov_b32_dpp v26, v15 row_ror:2 row_mask:0xf bank_mask:0xf
	v_mov_b32_dpp v16, v12 row_ror:1 row_mask:0xf bank_mask:0xf
	v_mov_b32_dpp v19, v13 row_ror:1 row_mask:0xf bank_mask:0xf
	v_mov_b32_dpp v22, v14 row_ror:1 row_mask:0xf bank_mask:0xf
	v_mov_b32_dpp v25, v15 row_ror:1 row_mask:0xf bank_mask:0xf
	v_cndmask_b32_e64 v32, v58, v18, s[4:5]
	v_cndmask_b32_e64 v33, v61, v21, s[4:5]
	v_cndmask_b32_e64 v38, v104, v24, s[4:5]
	v_cndmask_b32_e64 v39, v107, v27, s[4:5]
	v_cndmask_b32_e64 v30, v57, v17, s[0:1]
	v_cndmask_b32_e64 v31, v60, v20, s[0:1]
	v_cndmask_b32_e64 v36, v63, v23, s[0:1]
	v_cndmask_b32_e64 v37, v106, v26, s[0:1]
	v_pk_fma_f32 v[32:33], v[76:77], v[32:33], v[80:81]
	v_pk_fma_f32 v[38:39], v[78:79], v[38:39], v[82:83]
	v_cndmask_b32_e32 v28, v56, v16, vcc
	v_cndmask_b32_e32 v29, v59, v19, vcc
	v_cndmask_b32_e32 v34, v62, v22, vcc
	v_cndmask_b32_e32 v35, v105, v25, vcc
	v_pk_fma_f32 v[36:37], v[74:75], v[36:37], v[38:39]
	v_pk_fma_f32 v[30:31], v[72:73], v[30:31], v[32:33]
	s_nop 1
	v_mov_b32_dpp v32, v10 row_ror:3 row_mask:0xf bank_mask:0xf
	v_pk_fma_f32 v[28:29], v[68:69], v[28:29], v[30:31]
	v_pk_fma_f32 v[30:31], v[70:71], v[34:35], v[36:37]
	v_pk_fma_f32 v[36:37], v[12:13], v[64:65], v[28:29]
	v_pk_fma_f32 v[46:47], v[14:15], v[66:67], v[30:31]
	s_nop 1
	v_mov_b32_dpp v14, v8 row_ror:3 row_mask:0xf bank_mask:0xf
	v_mov_b32_dpp v28, v9 row_ror:2 row_mask:0xf bank_mask:0xf
	v_mov_b32_dpp v29, v9 row_ror:3 row_mask:0xf bank_mask:0xf
	v_mov_b32_dpp v35, v11 row_ror:3 row_mask:0xf bank_mask:0xf
	v_mov_b32_dpp v13, v8 row_ror:2 row_mask:0xf bank_mask:0xf
	v_mov_b32_dpp v15, v9 row_ror:1 row_mask:0xf bank_mask:0xf
	v_mov_b32_dpp v31, v10 row_ror:2 row_mask:0xf bank_mask:0xf
	v_mov_b32_dpp v34, v11 row_ror:2 row_mask:0xf bank_mask:0xf
	v_mov_b32_dpp v12, v8 row_ror:1 row_mask:0xf bank_mask:0xf
	v_mov_b32_dpp v30, v10 row_ror:1 row_mask:0xf bank_mask:0xf
	v_mov_b32_dpp v33, v11 row_ror:1 row_mask:0xf bank_mask:0xf
	v_cndmask_b32_e64 v42, v48, v14, s[4:5]
	v_cndmask_b32_e64 v41, v50, v28, s[0:1]
	v_cndmask_b32_e64 v43, v51, v29, s[4:5]
	v_cndmask_b32_e64 v50, v54, v32, s[4:5]
	v_cndmask_b32_e64 v51, v109, v35, s[4:5]
	v_cndmask_b32_e64 v40, v45, v13, s[0:1]
	v_cndmask_b32_e32 v39, v49, v15, vcc
	v_cndmask_b32_e64 v48, v53, v31, s[0:1]
	v_cndmask_b32_e64 v49, v108, v34, s[0:1]
	v_pk_fma_f32 v[42:43], v[96:97], v[42:43], v[100:101]
	v_pk_fma_f32 v[50:51], v[98:99], v[50:51], v[102:103]
	v_cndmask_b32_e32 v38, v44, v12, vcc
	v_cndmask_b32_e32 v44, v52, v30, vcc
	v_cndmask_b32_e32 v45, v55, v33, vcc
	v_pk_fma_f32 v[48:49], v[94:95], v[48:49], v[50:51]
	v_pk_fma_f32 v[40:41], v[92:93], v[40:41], v[42:43]
	s_nop 1
	v_mov_b32_dpp v42, v3 row_ror:2 row_mask:0xf bank_mask:0xf
	v_pk_fma_f32 v[38:39], v[88:89], v[38:39], v[40:41]
	v_pk_fma_f32 v[40:41], v[90:91], v[44:45], v[48:49]
	v_pk_fma_f32 v[50:51], v[8:9], v[84:85], v[38:39]
	v_pk_fma_f32 v[48:49], v[10:11], v[86:87], v[40:41]
	v_cvt_pk_bf16_f32 v44, v36, v37
	s_nop 1
	v_mov_b32_dpp v8, v0 row_ror:1 row_mask:0xf bank_mask:0xf
	v_mov_b32_dpp v9, v0 row_ror:2 row_mask:0xf bank_mask:0xf
	v_mov_b32_dpp v10, v0 row_ror:3 row_mask:0xf bank_mask:0xf
	v_mov_b32_dpp v11, v1 row_ror:1 row_mask:0xf bank_mask:0xf
	v_mov_b32_dpp v36, v1 row_ror:2 row_mask:0xf bank_mask:0xf
	v_mov_b32_dpp v37, v1 row_ror:3 row_mask:0xf bank_mask:0xf
	v_mov_b32_dpp v38, v2 row_ror:1 row_mask:0xf bank_mask:0xf
	v_mov_b32_dpp v39, v2 row_ror:2 row_mask:0xf bank_mask:0xf
	v_mov_b32_dpp v40, v2 row_ror:3 row_mask:0xf bank_mask:0xf
	v_mov_b32_dpp v41, v3 row_ror:1 row_mask:0xf bank_mask:0xf
	v_mov_b32_dpp v43, v3 row_ror:3 row_mask:0xf bank_mask:0xf
	v_cvt_pk_bf16_f32 v45, v46, v47
	v_cvt_pk_bf16_f32 v46, v50, v51
	v_cvt_pk_bf16_f32 v47, v48, v49
	global_store_dwordx4 v[120:121], v[44:47], off offset:256
	s_and_saveexec_b64 s[8:9], s[6:7]
	s_cbranch_execz .LBB0_174
	global_store_dwordx4 v[116:117], v[0:3], off offset:512

; __device__ __forceinline__ unsigned cvt_pk_bf16(float lo, float hi) { unsigned r; asm volatile("v_cvt_pk_bf16_f32 %0, %1, %2" : "=v"(r) : "v"(lo), "v"(hi)); return r; }
;     __device__ __forceinline__ void operator()(EPI_ARGS) const {
;     ...
;                         for (int n = 0; n < 2; ++n) {
;                             const f32x4 gv = acc[ai][bj][m][n];
;                             f32x4 r1, r2, r3, p1, p2, p3;
; #pragma unroll
;                             for (int j = 0; j < 4; ++j) { r1[j] = __shfl(gv[j], s1); r2[j] = __shfl(gv[j], s2); r3[j] = __shfl(gv[j], s3); }
; #pragma unroll
;                             for (int j = 0; j < 4; ++j) { p1[j] = fr >= 1 ? r1[j] : q1[n][j]; p2[j] = fr >= 2 ? r2[j] : q2[n][j]; p3[j] = fr >= 3 ? r3[j] : q3[n][j]; }
;                             q1[n] = r1; q2[n] = r2; q3[n] = r3;
;                             o[n] = bb[n] + w0[n] * p3 + w1[n] * p2 + w2[n] * p1 + w3[n] * gv;
;                             if (m == 0 && fr < 3) *(f32x4*)(headu + ((size_t)blk * 3 + fr) * LW + c0 + 4 * n) = gv;
;                             if (m == 3 && fr >= 13) *(f32x4*)(tailu + ((size_t)blk * 3 + (fr - 13)) * LW + c0 + 4 * n) = gv;
;                         }
;                         if (!(m == 0 && fr < 3)) {
;                             u32x4 w; w.x = cvt_pk_bf16(o[0][0], o[0][1]); w.y = cvt_pk_bf16(o[0][2], o[0][3]); w.z = cvt_pk_bf16(o[1][0], o[1][1]); w.w = cvt_pk_bf16(o[1][2], o[1][3]);
;                             *(u32x4*)(vout + (size_t)row * LW + c0) = w;
.LBB0_176:
	s_or_b64 exec, exec, s[8:9]
	v_cndmask_b32_e32 v12, v12, v44, vcc
	v_cndmask_b32_e64 v44, v13, v45, s[0:1]
	v_cndmask_b32_e64 v14, v14, v46, s[4:5]
	v_cndmask_b32_e32 v13, v15, v47, vcc
	v_cndmask_b32_e64 v15, v29, v49, s[4:5]
	v_cndmask_b32_e64 v45, v28, v48, s[0:1]
	v_pk_fma_f32 v[14:15], v[96:97], v[14:15], v[100:101]
	v_cndmask_b32_e64 v32, v32, v52, s[4:5]
	v_cndmask_b32_e32 v29, v33, v53, vcc
	v_cndmask_b32_e64 v33, v35, v55, s[4:5]
	v_pk_fma_f32 v[14:15], v[92:93], v[44:45], v[14:15]
	v_cndmask_b32_e32 v28, v30, v50, vcc
	v_cndmask_b32_e64 v30, v31, v51, s[0:1]
	v_cndmask_b32_e64 v31, v34, v54, s[0:1]
	v_pk_fma_f32 v[32:33], v[98:99], v[32:33], v[102:103]
	v_pk_fma_f32 v[12:13], v[88:89], v[12:13], v[14:15]
	v_pk_fma_f32 v[30:31], v[94:95], v[30:31], v[32:33]
	v_pk_fma_f32 v[4:5], v[4:5], v[84:85], v[12:13]
	v_cndmask_b32_e64 v12, v17, v9, s[0:1]
	v_cndmask_b32_e64 v10, v18, v10, s[4:5]
	v_cndmask_b32_e32 v9, v19, v11, vcc
	v_cndmask_b32_e64 v11, v21, v37, s[4:5]
	v_cndmask_b32_e64 v18, v24, v40, s[4:5]
	v_cndmask_b32_e64 v19, v27, v43, s[4:5]
	v_pk_fma_f32 v[14:15], v[90:91], v[28:29], v[30:31]
	v_cndmask_b32_e32 v8, v16, v8, vcc
	v_cndmask_b32_e64 v13, v20, v36, s[0:1]
	v_cndmask_b32_e64 v16, v23, v39, s[0:1]
	v_cndmask_b32_e64 v17, v26, v42, s[0:1]
	v_pk_fma_f32 v[10:11], v[76:77], v[10:11], v[80:81]
	v_pk_fma_f32 v[18:19], v[78:79], v[18:19], v[82:83]
	v_pk_fma_f32 v[6:7], v[6:7], v[86:87], v[14:15]
	v_cndmask_b32_e32 v14, v22, v38, vcc
	v_cndmask_b32_e32 v15, v25, v41, vcc
	v_pk_fma_f32 v[16:17], v[74:75], v[16:17], v[18:19]
	v_pk_fma_f32 v[10:11], v[72:73], v[12:13], v[10:11]
	s_nop 0
	v_pk_fma_f32 v[8:9], v[68:69], v[8:9], v[10:11]
	v_pk_fma_f32 v[10:11], v[70:71], v[14:15], v[16:17]
	v_pk_fma_f32 v[0:1], v[0:1], v[64:65], v[8:9]
	v_pk_fma_f32 v[2:3], v[2:3], v[66:67], v[10:11]
	v_cvt_pk_bf16_f32 v0, v0, v1
	s_nop 0
	v_cvt_pk_bf16_f32 v1, v2, v3
	v_cvt_pk_bf16_f32 v2, v4, v5
	v_cvt_pk_bf16_f32 v3, v6, v7
	global_store_dwordx4 v[122:123], v[0:3], off offset:256
	s_andn2_b64 vcc, exec, s[90:91]
	s_mov_b64 s[0:1], -1
	s_cbranch_vccnz .LBB0_115
	s_branch .LBB0_340

; __device__ __forceinline__ unsigned cvt_pk_bf16(float lo, float hi) { unsigned r; asm volatile("v_cvt_pk_bf16_f32 %0, %1, %2" : "=v"(r) : "v"(lo), "v"(hi)); return r; }
;     __device__ __forceinline__ void operator()(EPI_ARGS) const {
;     ...
;         for (int ai = 0; ai < 2; ++ai) {
;             const int blk = u.pm * 4 + ai * 2 + wr;
;             f32x4 q1[2], q2[2];
; #pragma unroll
;             for (int n = 0; n < 2; ++n) { q1[n] = (f32x4){0.f, 0.f, 0.f, 0.f}; q2[n] = (f32x4){0.f, 0.f, 0.f, 0.f}; }
; #pragma unroll
;             for (int m = 0; m < 4; ++m) {
;                 const int row = ROW_OF(ai, m);
;                 const float rs = __builtin_amdgcn_rsqf(rsv[ai][m] * (1.0f / D) + EPS);
;                 f32x4 o[2];
; #pragma unroll
;                 for (int n = 0; n < 2; ++n) {
;                     const f32x4 gv = acc[ai][0][m][n] * rs, vv = acc[ai][1][m][n] * rs;
;                     f32x4 r1, r2;
; #pragma unroll
;                     for (int j = 0; j < 4; ++j) { r1[j] = __shfl(gv[j], src1); r2[j] = __shfl(gv[j], src2); }
;                     f32x4 p1, p2;
; #pragma unroll
;                     for (int j = 0; j < 4; ++j) { p1[j] = fr >= 1 ? r1[j] : q1[n][j]; p2[j] = fr >= 2 ? r2[j] : q2[n][j]; }
;                     q1[n] = r1; q2[n] = r2;
;                     const f32x4 cv = bb[n] + w0[n] * p2 + w1[n] * p1 + w2[n] * gv;
;                     o[n] = gelu4(cv) * vv;
;                     if (m == 0 && fr < 2) { const size_t so = ((size_t)blk * 2 + fr) * FF + f0 + 4 * n; *(f32x4*)(headg + so) = gv; *(f32x4*)(headv + so) = vv; }
;                     if (m == 3 && fr >= 14) { const size_t so = ((size_t)blk * 2 + (fr - 14)) * FF + f0 + 4 * n; *(f32x4*)(tailg + so) = gv; }
;                 }
;                 if (!(m == 0 && fr < 2)) {
;                     u32x4 w; w.x = cvt_pk_bf16(o[0][0], o[0][1]); w.y = cvt_pk_bf16(o[0][2], o[0][3]); w.z = cvt_pk_bf16(o[1][0], o[1][1]); w.w = cvt_pk_bf16(o[1][2], o[1][3]);
;                     *(u32x4*)(act + (size_t)row * FF + f0) = w;
.LBB0_928:
	s_or_b64 exec, exec, s[0:1]
	v_mov_b32_e32 v205, v204
	v_mov_b32_e32 v226, v204
	v_mov_b32_e32 v227, v204
	v_pk_mul_f32 v[150:151], v[150:151], v[226:227]
	v_pk_mul_f32 v[148:149], v[148:149], v[204:205]
	s_nop 1
	v_mov_b32_dpp v194, v148 row_ror:1 row_mask:0xf bank_mask:0xf
	v_mov_b32_dpp v198, v148 row_ror:2 row_mask:0xf bank_mask:0xf
	v_mov_b32_dpp v195, v149 row_ror:1 row_mask:0xf bank_mask:0xf
	v_mov_b32_dpp v199, v149 row_ror:2 row_mask:0xf bank_mask:0xf
	v_mov_b32_dpp v196, v150 row_ror:1 row_mask:0xf bank_mask:0xf
	v_mov_b32_dpp v200, v150 row_ror:2 row_mask:0xf bank_mask:0xf
	v_mov_b32_dpp v197, v151 row_ror:1 row_mask:0xf bank_mask:0xf
	v_mov_b32_dpp v201, v151 row_ror:2 row_mask:0xf bank_mask:0xf
	v_cmp_lt_i32_e32 vcc, 0, v184
	v_cmp_lt_i32_e64 s[0:1], 1, v184
	v_pk_mul_f32 v[146:147], v[146:147], v[226:227]
	v_pk_mul_f32 v[144:145], v[144:145], v[204:205]
	s_and_saveexec_b64 s[4:5], s[6:7]
	s_xor_b64 s[4:5], exec, s[4:5]
	s_cbranch_execz .LBB0_930
	v_cndmask_b32_e64 v204, 0, v219, s[0:1]
	v_cndmask_b32_e64 v205, 0, v221, s[0:1]
	v_cndmask_b32_e32 v202, 0, v218, vcc
	v_cndmask_b32_e32 v203, 0, v220, vcc
	v_cndmask_b32_e64 v228, 0, v223, s[0:1]
	v_cndmask_b32_e64 v229, 0, v225, s[0:1]
	v_pk_fma_f32 v[204:205], v[72:73], v[204:205], v[76:77]
	v_cndmask_b32_e32 v226, 0, v222, vcc
	v_cndmask_b32_e32 v227, 0, v224, vcc
	v_pk_fma_f32 v[228:229], v[74:75], v[228:229], v[78:79]
	v_pk_fma_f32 v[202:203], v[64:65], v[202:203], v[204:205]
	v_pk_fma_f32 v[226:227], v[66:67], v[226:227], v[228:229]
	v_pk_fma_f32 v[156:157], v[68:69], v[156:157], v[202:203]
	v_pk_fma_f32 v[158:159], v[70:71], v[158:159], v[226:227]
	v_pk_mul_f32 v[204:205], v[156:157], v[156:157]
	v_pk_mul_f32 v[202:203], v[158:159], v[158:159]
	v_fmamk_f32 v168, v204, 0xbdd2d3e8, v216
	v_mul_f32_e32 v168, v156, v168
	v_fmamk_f32 v204, v205, 0xbdd2d3e8, v216
	v_fmamk_f32 v202, v202, 0xbdd2d3e8, v216
	v_exp_f32_e32 v168, v168
	v_mul_f32_e32 v204, v157, v204
	v_mul_f32_e32 v202, v158, v202
	v_exp_f32_e32 v204, v204
	v_exp_f32_e32 v205, v202
	v_fmamk_f32 v202, v203, 0xbdd2d3e8, v216
	v_mul_f32_e32 v202, v159, v202
	v_exp_f32_e32 v226, v202
	v_add_f32_e32 v168, 1.0, v168
	v_rcp_f32_e32 v202, v168
	v_add_f32_e32 v168, 1.0, v204
	v_rcp_f32_e32 v203, v168
	v_add_f32_e32 v168, 1.0, v205
	v_rcp_f32_e32 v204, v168
	v_add_f32_e32 v168, 1.0, v226
	v_rcp_f32_e32 v205, v168
	v_pk_mul_f32 v[156:157], v[156:157], v[202:203]
	s_nop 0
	v_pk_fma_f32 v[202:203], v[94:95], v[200:201], v[98:99]
	v_pk_mul_f32 v[152:153], v[152:153], v[156:157]
	v_pk_mul_f32 v[158:159], v[158:159], v[204:205]
	v_pk_fma_f32 v[204:205], v[92:93], v[198:199], v[96:97]
	v_pk_fma_f32 v[202:203], v[86:87], v[196:197], v[202:203]
	v_pk_fma_f32 v[204:205], v[84:85], v[194:195], v[204:205]
	v_pk_fma_f32 v[150:151], v[90:91], v[150:151], v[202:203]
	v_pk_fma_f32 v[148:149], v[88:89], v[148:149], v[204:205]
	v_pk_mul_f32 v[202:203], v[150:151], v[150:151]
	v_pk_mul_f32 v[204:205], v[148:149], v[148:149]
	v_fmamk_f32 v202, v202, 0xbdd2d3e8, v216
	v_fmamk_f32 v168, v204, 0xbdd2d3e8, v216
	v_mul_f32_e32 v168, v148, v168
	v_exp_f32_e32 v168, v168
	v_fmamk_f32 v203, v203, 0xbdd2d3e8, v216
	v_mul_f32_e32 v202, v150, v202
	v_mul_f32_e32 v203, v151, v203
	v_add_f32_e32 v168, 1.0, v168
	v_rcp_f32_e32 v204, v168
	v_fmamk_f32 v168, v205, 0xbdd2d3e8, v216
	v_mul_f32_e32 v168, v149, v168
	v_exp_f32_e32 v168, v168
	v_exp_f32_e32 v202, v202
	v_exp_f32_e32 v203, v203
	v_pk_mul_f32 v[154:155], v[154:155], v[158:159]
	v_add_f32_e32 v168, 1.0, v168
	v_add_f32_e32 v202, 1.0, v202
	v_add_f32_e32 v203, 1.0, v203
	v_rcp_f32_e32 v202, v202
	v_rcp_f32_e32 v203, v203
	v_rcp_f32_e32 v205, v168
	v_pk_mul_f32 v[150:151], v[150:151], v[202:203]
	v_pk_mul_f32 v[148:149], v[148:149], v[204:205]
	v_pk_mul_f32 v[150:151], v[146:147], v[150:151]
	v_pk_mul_f32 v[146:147], v[144:145], v[148:149]
	v_mov_b64_e32 v[148:149], s[10:11]
	v_mad_i64_i32 v[148:149], s[12:13], v192, s66, v[148:149]
	v_cvt_pk_bf16_f32 v144, v152, v153
	v_cvt_pk_bf16_f32 v145, v154, v155
	v_cvt_pk_bf16_f32 v146, v146, v147
	v_cvt_pk_bf16_f32 v147, v150, v151
	v_lshl_add_u64 v[148:149], v[174:175], 1, v[148:149]
	global_store_dwordx4 v[148:149], v[144:147], off

; __device__ __forceinline__ unsigned cvt_pk_bf16(float lo, float hi) { unsigned r; asm volatile("v_cvt_pk_bf16_f32 %0, %1, %2" : "=v"(r) : "v"(lo), "v"(hi)); return r; }
;     __device__ __forceinline__ void operator()(EPI_ARGS) const {
;     ...
;             for (int m = 0; m < 4; ++m) {
;                 const int row = ROW_OF(ai, m);
;                 const float rs = __builtin_amdgcn_rsqf(rsv[ai][m] * (1.0f / D) + EPS);
;                 f32x4 o[2];
; #pragma unroll
;                 for (int n = 0; n < 2; ++n) {
;                     const f32x4 gv = acc[ai][0][m][n] * rs, vv = acc[ai][1][m][n] * rs;
;                     f32x4 r1, r2;
; #pragma unroll
;                     for (int j = 0; j < 4; ++j) { r1[j] = __shfl(gv[j], src1); r2[j] = __shfl(gv[j], src2); }
;                     f32x4 p1, p2;
; #pragma unroll
;                     for (int j = 0; j < 4; ++j) { p1[j] = fr >= 1 ? r1[j] : q1[n][j]; p2[j] = fr >= 2 ? r2[j] : q2[n][j]; }
;                     q1[n] = r1; q2[n] = r2;
;                     const f32x4 cv = bb[n] + w0[n] * p2 + w1[n] * p1 + w2[n] * gv;
;                     o[n] = gelu4(cv) * vv;
;                     if (m == 0 && fr < 2) { const size_t so = ((size_t)blk * 2 + fr) * FF + f0 + 4 * n; *(f32x4*)(headg + so) = gv; *(f32x4*)(headv + so) = vv; }
;                     if (m == 3 && fr >= 14) { const size_t so = ((size_t)blk * 2 + (fr - 14)) * FF + f0 + 4 * n; *(f32x4*)(tailg + so) = gv; }
;                 }
;                 if (!(m == 0 && fr < 2)) {
;                     u32x4 w; w.x = cvt_pk_bf16(o[0][0], o[0][1]); w.y = cvt_pk_bf16(o[0][2], o[0][3]); w.z = cvt_pk_bf16(o[1][0], o[1][1]); w.w = cvt_pk_bf16(o[1][2], o[1][3]);
;                     *(u32x4*)(act + (size_t)row * FF + f0) = w;
.LBB0_932:
	s_or_b64 exec, exec, s[4:5]
	s_nop 0
	v_fmamk_f32 v144, v217, 0x3a000000, v215
	v_rsq_f32_e32 v148, v144
	v_add_u32_e32 v168, -14, v184
	v_lshl_add_u64 v[146:147], s[62:63], 0, v[168:169]
	v_mad_u64_u32 v[144:145], s[12:13], v146, s30, 0
	v_pk_mul_f32 v[142:143], v[142:143], v[148:149] op_sel_hi:[1,0]
	v_pk_mul_f32 v[140:141], v[140:141], v[148:149] op_sel_hi:[1,0]
	s_nop 1
	v_mov_b32_dpp v192, v142 row_ror:2 row_mask:0xf bank_mask:0xf
	v_mov_b32_dpp v203, v143 row_ror:2 row_mask:0xf bank_mask:0xf
	v_mov_b32_dpp v156, v140 row_ror:2 row_mask:0xf bank_mask:0xf
	v_mov_b32_dpp v158, v141 row_ror:2 row_mask:0xf bank_mask:0xf
	v_mov_b32_dpp v159, v142 row_ror:1 row_mask:0xf bank_mask:0xf
	v_mov_b32_dpp v202, v143 row_ror:1 row_mask:0xf bank_mask:0xf
	v_mov_b32_dpp v149, v140 row_ror:1 row_mask:0xf bank_mask:0xf
	v_mov_b32_dpp v157, v141 row_ror:1 row_mask:0xf bank_mask:0xf
	v_cndmask_b32_e64 v154, v223, v192, s[0:1]
	v_cndmask_b32_e64 v155, v225, v203, s[0:1]
	v_cndmask_b32_e64 v150, v219, v156, s[0:1]
	v_cndmask_b32_e64 v151, v221, v158, s[0:1]
	v_cndmask_b32_e32 v152, v222, v159, vcc
	v_cndmask_b32_e32 v153, v224, v202, vcc
	v_pk_fma_f32 v[154:155], v[74:75], v[154:155], v[78:79]
	v_mad_i32_i24 v145, v147, s30, v145
	v_cndmask_b32_e32 v146, v218, v149, vcc
	v_cndmask_b32_e32 v147, v220, v157, vcc
	v_pk_fma_f32 v[150:151], v[72:73], v[150:151], v[76:77]
	v_pk_fma_f32 v[152:153], v[66:67], v[152:153], v[154:155]
	v_pk_fma_f32 v[146:147], v[64:65], v[146:147], v[150:151]
	v_pk_fma_f32 v[142:143], v[70:71], v[142:143], v[152:153]
	v_pk_fma_f32 v[140:141], v[68:69], v[140:141], v[146:147]
	v_pk_mul_f32 v[146:147], v[142:143], v[142:143]
	v_pk_mul_f32 v[150:151], v[140:141], v[140:141]
	v_fmamk_f32 v146, v146, 0xbdd2d3e8, v216
	v_mul_f32_e32 v146, v142, v146
	v_fmamk_f32 v150, v150, 0xbdd2d3e8, v216
	v_fmamk_f32 v151, v151, 0xbdd2d3e8, v216
	v_exp_f32_e32 v152, v146
	v_fmamk_f32 v146, v147, 0xbdd2d3e8, v216
	v_mul_f32_e32 v150, v140, v150
	v_mul_f32_e32 v151, v141, v151
	v_mul_f32_e32 v146, v143, v146
	v_exp_f32_e32 v150, v150
	v_exp_f32_e32 v151, v151
	v_exp_f32_e32 v153, v146
	v_pk_mul_f32 v[138:139], v[138:139], v[148:149] op_sel_hi:[1,0]
	v_add_f32_e32 v146, 1.0, v150
	v_add_f32_e32 v147, 1.0, v151
	v_add_f32_e32 v150, 1.0, v152
	v_add_f32_e32 v151, 1.0, v153
	v_pk_mul_f32 v[136:137], v[136:137], v[148:149] op_sel_hi:[1,0]
	s_nop 1
	v_mov_b32_dpp v205, v138 row_ror:2 row_mask:0xf bank_mask:0xf
	v_mov_b32_dpp v218, v139 row_ror:2 row_mask:0xf bank_mask:0xf
	v_rcp_f32_e32 v150, v150
	v_rcp_f32_e32 v151, v151
	s_nop 1
	v_mov_b32_dpp v153, v136 row_ror:2 row_mask:0xf bank_mask:0xf
	v_mov_b32_dpp v155, v137 row_ror:2 row_mask:0xf bank_mask:0xf
	v_mov_b32_dpp v204, v138 row_ror:1 row_mask:0xf bank_mask:0xf
	v_mov_b32_dpp v217, v139 row_ror:1 row_mask:0xf bank_mask:0xf
	v_rcp_f32_e32 v146, v146
	v_rcp_f32_e32 v147, v147
	s_nop 1
	v_mov_b32_dpp v152, v136 row_ror:1 row_mask:0xf bank_mask:0xf
	v_mov_b32_dpp v154, v137 row_ror:1 row_mask:0xf bank_mask:0xf
	v_pk_mul_f32 v[134:135], v[134:135], v[148:149] op_sel_hi:[1,0]
	v_pk_mul_f32 v[142:143], v[142:143], v[150:151]
	v_cndmask_b32_e64 v150, v200, v205, s[0:1]
	v_cndmask_b32_e64 v151, v201, v218, s[0:1]
	v_pk_mul_f32 v[132:133], v[132:133], v[148:149] op_sel_hi:[1,0]
	v_pk_mul_f32 v[140:141], v[140:141], v[146:147]
	v_pk_mul_f32 v[134:135], v[134:135], v[142:143]
	v_cndmask_b32_e64 v142, v198, v153, s[0:1]
	v_cndmask_b32_e64 v143, v199, v155, s[0:1]
	v_cndmask_b32_e32 v146, v196, v204, vcc
	v_cndmask_b32_e32 v147, v197, v217, vcc
	v_pk_fma_f32 v[150:151], v[94:95], v[150:151], v[98:99]
	v_pk_mul_f32 v[132:133], v[132:133], v[140:141]
	v_cndmask_b32_e32 v140, v194, v152, vcc
	v_cndmask_b32_e32 v141, v195, v154, vcc
	v_pk_fma_f32 v[142:143], v[92:93], v[142:143], v[96:97]
	v_pk_fma_f32 v[146:147], v[86:87], v[146:147], v[150:151]
	v_pk_fma_f32 v[140:141], v[84:85], v[140:141], v[142:143]
	v_pk_fma_f32 v[138:139], v[90:91], v[138:139], v[146:147]
	v_pk_fma_f32 v[136:137], v[88:89], v[136:137], v[140:141]
	v_pk_mul_f32 v[140:141], v[138:139], v[138:139]
	v_pk_mul_f32 v[142:143], v[136:137], v[136:137]
	v_fmamk_f32 v140, v140, 0xbdd2d3e8, v216
	v_fmamk_f32 v142, v142, 0xbdd2d3e8, v216
	v_fmamk_f32 v143, v143, 0xbdd2d3e8, v216
	v_mul_f32_e32 v140, v138, v140
	v_mul_f32_e32 v142, v136, v142
	v_mul_f32_e32 v143, v137, v143
	v_exp_f32_e32 v146, v140
	v_fmamk_f32 v140, v141, 0xbdd2d3e8, v216
	v_exp_f32_e32 v142, v142
	v_exp_f32_e32 v143, v143
	v_mul_f32_e32 v140, v139, v140
	v_exp_f32_e32 v147, v140
	v_add_f32_e32 v140, 1.0, v142
	v_add_f32_e32 v141, 1.0, v143
	v_rcp_f32_e32 v140, v140
	v_rcp_f32_e32 v141, v141
	v_add_f32_e32 v142, 1.0, v146
	v_add_f32_e32 v143, 1.0, v147
	v_rcp_f32_e32 v142, v142
	v_rcp_f32_e32 v143, v143
	v_pk_mul_f32 v[128:129], v[128:129], v[148:149] op_sel_hi:[1,0]
	v_pk_mul_f32 v[136:137], v[136:137], v[140:141]
	v_pk_mul_f32 v[130:131], v[130:131], v[148:149] op_sel_hi:[1,0]
	v_pk_mul_f32 v[138:139], v[138:139], v[142:143]
	v_pk_mul_f32 v[128:129], v[128:129], v[136:137]
	v_pk_mul_f32 v[138:139], v[130:131], v[138:139]
	v_cvt_pk_bf16_f32 v130, v132, v133
	v_cvt_pk_bf16_f32 v131, v134, v135
	v_cvt_pk_bf16_f32 v132, v128, v129
	v_fmamk_f32 v128, v193, 0x3a000000, v215
	v_cvt_pk_bf16_f32 v133, v138, v139
	v_rsq_f32_e32 v138, v128
	v_mov_b64_e32 v[136:137], s[10:11]
	v_mad_i64_i32 v[134:135], s[12:13], v190, s66, v[136:137]
	v_lshlrev_b64 v[128:129], 1, v[174:175]
	v_lshl_add_u64 v[134:135], v[134:135], 0, v[128:129]
	v_pk_mul_f32 v[140:141], v[124:125], v[138:139] op_sel_hi:[1,0]
	global_store_dwordx4 v[134:135], v[130:133], off
	v_pk_mul_f32 v[134:135], v[126:127], v[138:139] op_sel_hi:[1,0]
; __device__ __forceinline__ unsigned cvt_pk_bf16(float lo, float hi) { unsigned r; asm volatile("v_cvt_pk_bf16_f32 %0, %1, %2" : "=v"(r) : "v"(lo), "v"(hi)); return r; }
;     __device__ __forceinline__ void operator()(EPI_ARGS) const {
;     ...
;             for (int m = 0; m < 4; ++m) {
;                 const int row = ROW_OF(ai, m);
;                 const float rs = __builtin_amdgcn_rsqf(rsv[ai][m] * (1.0f / D) + EPS);
;                 f32x4 o[2];
; #pragma unroll
;                 for (int n = 0; n < 2; ++n) {
;                     const f32x4 gv = acc[ai][0][m][n] * rs, vv = acc[ai][1][m][n] * rs;
;                     f32x4 r1, r2;
; #pragma unroll
;                     for (int j = 0; j < 4; ++j) { r1[j] = __shfl(gv[j], src1); r2[j] = __shfl(gv[j], src2); }
;                     f32x4 p1, p2;
; #pragma unroll
;                     for (int j = 0; j < 4; ++j) { p1[j] = fr >= 1 ? r1[j] : q1[n][j]; p2[j] = fr >= 2 ? r2[j] : q2[n][j]; }
;                     q1[n] = r1; q2[n] = r2;
;                     const f32x4 cv = bb[n] + w0[n] * p2 + w1[n] * p1 + w2[n] * gv;
;                     o[n] = gelu4(cv) * vv;
;                     if (m == 0 && fr < 2) { const size_t so = ((size_t)blk * 2 + fr) * FF + f0 + 4 * n; *(f32x4*)(headg + so) = gv; *(f32x4*)(headv + so) = vv; }
;                     if (m == 3 && fr >= 14) { const size_t so = ((size_t)blk * 2 + (fr - 14)) * FF + f0 + 4 * n; *(f32x4*)(tailg + so) = gv; }
;                 }
;                 if (!(m == 0 && fr < 2)) {
;                     u32x4 w; w.x = cvt_pk_bf16(o[0][0], o[0][1]); w.y = cvt_pk_bf16(o[0][2], o[0][3]); w.z = cvt_pk_bf16(o[1][0], o[1][1]); w.w = cvt_pk_bf16(o[1][2], o[1][3]);
;                     *(u32x4*)(act + (size_t)row * FF + f0) = w;
	s_nop 1
	v_mov_b32_dpp v125, v140 row_ror:2 row_mask:0xf bank_mask:0xf
	v_mov_b32_dpp v127, v141 row_ror:2 row_mask:0xf bank_mask:0xf
	v_mov_b32_dpp v124, v140 row_ror:1 row_mask:0xf bank_mask:0xf
	v_mov_b32_dpp v126, v141 row_ror:1 row_mask:0xf bank_mask:0xf
	v_mov_b32_dpp v131, v134 row_ror:2 row_mask:0xf bank_mask:0xf
	v_mov_b32_dpp v133, v135 row_ror:2 row_mask:0xf bank_mask:0xf
	v_mov_b32_dpp v130, v134 row_ror:1 row_mask:0xf bank_mask:0xf
	v_mov_b32_dpp v132, v135 row_ror:1 row_mask:0xf bank_mask:0xf
	v_cndmask_b32_e64 v146, v156, v125, s[0:1]
	v_cndmask_b32_e64 v147, v158, v127, s[0:1]
	v_cndmask_b32_e32 v142, v149, v124, vcc
	v_cndmask_b32_e32 v143, v157, v126, vcc
	v_cndmask_b32_e64 v150, v192, v131, s[0:1]
	v_cndmask_b32_e64 v151, v203, v133, s[0:1]
	v_pk_fma_f32 v[146:147], v[72:73], v[146:147], v[76:77]
	v_cndmask_b32_e32 v148, v159, v130, vcc
	v_cndmask_b32_e32 v149, v202, v132, vcc
	v_pk_fma_f32 v[150:151], v[74:75], v[150:151], v[78:79]
	v_pk_fma_f32 v[142:143], v[64:65], v[142:143], v[146:147]
	v_pk_fma_f32 v[148:149], v[66:67], v[148:149], v[150:151]
	v_pk_fma_f32 v[140:141], v[68:69], v[140:141], v[142:143]
	v_pk_fma_f32 v[134:135], v[70:71], v[134:135], v[148:149]
	v_pk_mul_f32 v[146:147], v[140:141], v[140:141]
	v_pk_mul_f32 v[142:143], v[134:135], v[134:135]
	v_fmamk_f32 v139, v146, 0xbdd2d3e8, v216
	v_mul_f32_e32 v139, v140, v139
	v_fmamk_f32 v146, v147, 0xbdd2d3e8, v216
	v_fmamk_f32 v142, v142, 0xbdd2d3e8, v216
	v_exp_f32_e32 v139, v139
	v_mul_f32_e32 v146, v141, v146
	v_mul_f32_e32 v142, v134, v142
	v_exp_f32_e32 v146, v146
	v_exp_f32_e32 v147, v142
	v_fmamk_f32 v142, v143, 0xbdd2d3e8, v216
	v_mul_f32_e32 v142, v135, v142
	v_exp_f32_e32 v148, v142
	v_add_f32_e32 v139, 1.0, v139
	v_rcp_f32_e32 v142, v139
	v_add_f32_e32 v139, 1.0, v146
	v_rcp_f32_e32 v143, v139
	v_add_f32_e32 v139, 1.0, v147
	v_rcp_f32_e32 v146, v139
	v_add_f32_e32 v139, 1.0, v148
	v_rcp_f32_e32 v147, v139
	v_pk_mul_f32 v[116:117], v[116:117], v[138:139] op_sel_hi:[1,0]
	v_pk_mul_f32 v[118:119], v[118:119], v[138:139] op_sel_hi:[1,0]
	v_pk_mul_f32 v[140:141], v[140:141], v[142:143]
	v_pk_mul_f32 v[134:135], v[134:135], v[146:147]
	v_pk_mul_f32 v[146:147], v[120:121], v[138:139] op_sel_hi:[1,0]
	v_pk_mul_f32 v[142:143], v[118:119], v[134:135]
	v_pk_mul_f32 v[116:117], v[116:117], v[140:141]
	v_pk_mul_f32 v[140:141], v[122:123], v[138:139] op_sel_hi:[1,0]
	s_nop 1
	v_mov_b32_dpp v119, v146 row_ror:2 row_mask:0xf bank_mask:0xf
	v_mov_b32_dpp v121, v147 row_ror:2 row_mask:0xf bank_mask:0xf
	v_mov_b32_dpp v118, v146 row_ror:1 row_mask:0xf bank_mask:0xf
	v_mov_b32_dpp v120, v147 row_ror:1 row_mask:0xf bank_mask:0xf
	v_mov_b32_dpp v123, v140 row_ror:2 row_mask:0xf bank_mask:0xf
	v_mov_b32_dpp v135, v141 row_ror:2 row_mask:0xf bank_mask:0xf
	v_mov_b32_dpp v122, v140 row_ror:1 row_mask:0xf bank_mask:0xf
	v_mov_b32_dpp v134, v141 row_ror:1 row_mask:0xf bank_mask:0xf
	v_cndmask_b32_e64 v150, v153, v119, s[0:1]
	v_cndmask_b32_e64 v151, v155, v121, s[0:1]
	v_cndmask_b32_e32 v148, v152, v118, vcc
	v_cndmask_b32_e32 v149, v154, v120, vcc
	v_cndmask_b32_e64 v154, v205, v123, s[0:1]
	v_cndmask_b32_e64 v155, v218, v135, s[0:1]
	v_pk_fma_f32 v[150:151], v[92:93], v[150:151], v[96:97]
	v_cndmask_b32_e32 v152, v204, v122, vcc
	v_cndmask_b32_e32 v153, v217, v134, vcc
	v_pk_fma_f32 v[154:155], v[94:95], v[154:155], v[98:99]
	v_pk_fma_f32 v[148:149], v[84:85], v[148:149], v[150:151]
	v_pk_fma_f32 v[152:153], v[86:87], v[152:153], v[154:155]
	v_pk_fma_f32 v[146:147], v[88:89], v[146:147], v[148:149]
	v_pk_fma_f32 v[140:141], v[90:91], v[140:141], v[152:153]
	v_pk_mul_f32 v[150:151], v[146:147], v[146:147]
	v_pk_mul_f32 v[148:149], v[140:141], v[140:141]
	v_fmamk_f32 v139, v150, 0xbdd2d3e8, v216
	v_mul_f32_e32 v139, v146, v139
	v_fmamk_f32 v150, v151, 0xbdd2d3e8, v216
	v_fmamk_f32 v148, v148, 0xbdd2d3e8, v216
	v_exp_f32_e32 v139, v139
	v_mul_f32_e32 v150, v147, v150
	v_mul_f32_e32 v148, v140, v148
	v_exp_f32_e32 v150, v150
	v_exp_f32_e32 v151, v148
	v_fmamk_f32 v148, v149, 0xbdd2d3e8, v216
	v_mul_f32_e32 v148, v141, v148
	v_exp_f32_e32 v152, v148
	v_add_f32_e32 v139, 1.0, v139
	v_rcp_f32_e32 v148, v139
	v_add_f32_e32 v139, 1.0, v150
	v_rcp_f32_e32 v149, v139
	v_add_f32_e32 v139, 1.0, v151
	v_rcp_f32_e32 v150, v139
	v_add_f32_e32 v139, 1.0, v152
	v_rcp_f32_e32 v151, v139
	v_pk_mul_f32 v[112:113], v[112:113], v[138:139] op_sel_hi:[1,0]
	v_pk_mul_f32 v[114:115], v[114:115], v[138:139] op_sel_hi:[1,0]
	v_pk_mul_f32 v[138:139], v[146:147], v[148:149]
	v_pk_mul_f32 v[140:141], v[140:141], v[150:151]
	v_pk_mul_f32 v[112:113], v[112:113], v[138:139]
	v_pk_mul_f32 v[140:141], v[114:115], v[140:141]
	v_cvt_pk_bf16_f32 v114, v116, v117
	v_cvt_pk_bf16_f32 v115, v142, v143
	v_cvt_pk_bf16_f32 v116, v112, v113
	v_fmamk_f32 v112, v191, 0x3a000000, v215
	v_rsq_f32_e32 v112, v112
	v_cvt_pk_bf16_f32 v117, v140, v141
	v_mad_i64_i32 v[146:147], s[12:13], v188, s66, v[136:137]
	v_pk_mul_f32 v[110:111], v[110:111], v[112:113] op_sel_hi:[1,0]
	v_pk_mul_f32 v[108:109], v[108:109], v[112:113] op_sel_hi:[1,0]
	s_nop 1
	v_mov_b32_dpp v136, v108 row_ror:1 row_mask:0xf bank_mask:0xf
	v_mov_b32_dpp v137, v108 row_ror:2 row_mask:0xf bank_mask:0xf
	v_mov_b32_dpp v138, v109 row_ror:1 row_mask:0xf bank_mask:0xf
	v_mov_b32_dpp v139, v109 row_ror:2 row_mask:0xf bank_mask:0xf
	v_mov_b32_dpp v140, v110 row_ror:1 row_mask:0xf bank_mask:0xf
	v_mov_b32_dpp v141, v110 row_ror:2 row_mask:0xf bank_mask:0xf
	v_mov_b32_dpp v142, v111 row_ror:1 row_mask:0xf bank_mask:0xf
	v_mov_b32_dpp v143, v111 row_ror:2 row_mask:0xf bank_mask:0xf
	v_lshl_add_u64 v[146:147], v[146:147], 0, v[128:129]
	global_store_dwordx4 v[146:147], v[114:117], off
	v_cmp_lt_i32_e64 s[4:5], 13, v184
	s_nop 0
	v_lshl_add_u64 v[114:115], s[40:41], 0, v[144:145]
	v_lshl_add_u64 v[116:117], v[174:175], 2, v[114:115]
	s_and_saveexec_b64 s[12:13], s[4:5]
	s_cbranch_execz .LBB0_934
	global_store_dwordx4 v[116:117], v[108:111], off

; __device__ __forceinline__ unsigned cvt_pk_bf16(float lo, float hi) { unsigned r; asm volatile("v_cvt_pk_bf16_f32 %0, %1, %2" : "=v"(r) : "v"(lo), "v"(hi)); return r; }
;     __device__ __forceinline__ void operator()(EPI_ARGS) const {
;     ...
;         for (int ai = 0; ai < 2; ++ai) {
;             const int blk = u.pm * 4 + ai * 2 + wr;
;             f32x4 q1[2], q2[2];
; #pragma unroll
;             for (int n = 0; n < 2; ++n) { q1[n] = (f32x4){0.f, 0.f, 0.f, 0.f}; q2[n] = (f32x4){0.f, 0.f, 0.f, 0.f}; }
; #pragma unroll
;             for (int m = 0; m < 4; ++m) {
;                 const int row = ROW_OF(ai, m);
;                 const float rs = __builtin_amdgcn_rsqf(rsv[ai][m] * (1.0f / D) + EPS);
;                 f32x4 o[2];
; #pragma unroll
;                 for (int n = 0; n < 2; ++n) {
;                     const f32x4 gv = acc[ai][0][m][n] * rs, vv = acc[ai][1][m][n] * rs;
;                     f32x4 r1, r2;
; #pragma unroll
;                     for (int j = 0; j < 4; ++j) { r1[j] = __shfl(gv[j], src1); r2[j] = __shfl(gv[j], src2); }
;                     f32x4 p1, p2;
; #pragma unroll
;                     for (int j = 0; j < 4; ++j) { p1[j] = fr >= 1 ? r1[j] : q1[n][j]; p2[j] = fr >= 2 ? r2[j] : q2[n][j]; }
;                     q1[n] = r1; q2[n] = r2;
;                     const f32x4 cv = bb[n] + w0[n] * p2 + w1[n] * p1 + w2[n] * gv;
;                     o[n] = gelu4(cv) * vv;
;                     if (m == 0 && fr < 2) { const size_t so = ((size_t)blk * 2 + fr) * FF + f0 + 4 * n; *(f32x4*)(headg + so) = gv; *(f32x4*)(headv + so) = vv; }
;                     if (m == 3 && fr >= 14) { const size_t so = ((size_t)blk * 2 + (fr - 14)) * FF + f0 + 4 * n; *(f32x4*)(tailg + so) = gv; }
;                 }
;                 if (!(m == 0 && fr < 2)) {
;                     u32x4 w; w.x = cvt_pk_bf16(o[0][0], o[0][1]); w.y = cvt_pk_bf16(o[0][2], o[0][3]); w.z = cvt_pk_bf16(o[1][0], o[1][1]); w.w = cvt_pk_bf16(o[1][2], o[1][3]);
;                     *(u32x4*)(act + (size_t)row * FF + f0) = w;
.LBB0_936:
	s_or_b64 exec, exec, s[12:13]
	v_cndmask_b32_e32 v117, v120, v146, vcc
	v_cndmask_b32_e32 v120, v122, v148, vcc
	v_cndmask_b32_e64 v122, v123, v149, s[0:1]
	v_cndmask_b32_e64 v123, v135, v151, s[0:1]
	v_cndmask_b32_e32 v116, v118, v144, vcc
	v_cndmask_b32_e64 v118, v119, v145, s[0:1]
	v_cndmask_b32_e64 v119, v121, v147, s[0:1]
	v_cndmask_b32_e32 v121, v134, v150, vcc
	v_pk_fma_f32 v[122:123], v[94:95], v[122:123], v[98:99]
	v_pk_fma_f32 v[118:119], v[92:93], v[118:119], v[96:97]
	v_pk_fma_f32 v[120:121], v[86:87], v[120:121], v[122:123]
	v_pk_fma_f32 v[116:117], v[84:85], v[116:117], v[118:119]
	v_pk_fma_f32 v[106:107], v[90:91], v[106:107], v[120:121]
	v_pk_fma_f32 v[104:105], v[88:89], v[104:105], v[116:117]
	v_pk_mul_f32 v[116:117], v[106:107], v[106:107]
	v_pk_mul_f32 v[118:119], v[104:105], v[104:105]
	v_fmamk_f32 v116, v116, 0xbdd2d3e8, v216
	v_mul_f32_e32 v116, v106, v116
	v_fmamk_f32 v118, v118, 0xbdd2d3e8, v216
	v_fmamk_f32 v119, v119, 0xbdd2d3e8, v216
	v_exp_f32_e32 v120, v116
	v_fmamk_f32 v116, v117, 0xbdd2d3e8, v216
	v_mul_f32_e32 v118, v104, v118
	v_mul_f32_e32 v119, v105, v119
	v_mul_f32_e32 v116, v107, v116
	v_exp_f32_e32 v118, v118
	v_exp_f32_e32 v119, v119
	v_exp_f32_e32 v121, v116
	v_pk_mul_f32 v[102:103], v[102:103], v[114:115]
	v_add_f32_e32 v116, 1.0, v118
	v_add_f32_e32 v117, 1.0, v119
	v_add_f32_e32 v118, 1.0, v120
	v_add_f32_e32 v119, 1.0, v121
	v_rcp_f32_e32 v118, v118
	v_rcp_f32_e32 v119, v119
	v_rcp_f32_e32 v116, v116
	v_rcp_f32_e32 v117, v117
	v_pk_mul_f32 v[100:101], v[100:101], v[112:113]
	v_pk_mul_f32 v[106:107], v[106:107], v[118:119]
	v_cndmask_b32_e64 v118, v131, v141, s[0:1]
	v_cndmask_b32_e64 v119, v133, v143, s[0:1]
	v_pk_mul_f32 v[104:105], v[104:105], v[116:117]
	v_pk_mul_f32 v[102:103], v[102:103], v[106:107]
	v_cndmask_b32_e64 v106, v125, v137, s[0:1]
	v_cndmask_b32_e64 v107, v127, v139, s[0:1]
	v_cndmask_b32_e32 v116, v130, v140, vcc
	v_cndmask_b32_e32 v117, v132, v142, vcc
	v_pk_fma_f32 v[118:119], v[74:75], v[118:119], v[78:79]
	v_pk_mul_f32 v[100:101], v[100:101], v[104:105]
	v_cndmask_b32_e32 v104, v124, v136, vcc
	v_cndmask_b32_e32 v105, v126, v138, vcc
	v_pk_fma_f32 v[106:107], v[72:73], v[106:107], v[76:77]
	v_pk_fma_f32 v[116:117], v[66:67], v[116:117], v[118:119]
	v_pk_fma_f32 v[104:105], v[64:65], v[104:105], v[106:107]
	v_pk_fma_f32 v[106:107], v[70:71], v[110:111], v[116:117]
	v_pk_fma_f32 v[104:105], v[68:69], v[108:109], v[104:105]
	v_pk_mul_f32 v[108:109], v[106:107], v[106:107]
	v_pk_mul_f32 v[110:111], v[104:105], v[104:105]
	v_fmamk_f32 v108, v108, 0xbdd2d3e8, v216
	v_mul_f32_e32 v108, v106, v108
	v_fmamk_f32 v110, v110, 0xbdd2d3e8, v216
	v_fmamk_f32 v111, v111, 0xbdd2d3e8, v216
	v_exp_f32_e32 v116, v108
	v_fmamk_f32 v108, v109, 0xbdd2d3e8, v216
	v_mul_f32_e32 v110, v104, v110
	v_mul_f32_e32 v111, v105, v111
	v_mul_f32_e32 v108, v107, v108
	v_exp_f32_e32 v110, v110
	v_exp_f32_e32 v111, v111
	v_exp_f32_e32 v117, v108
	v_pk_mul_f32 v[82:83], v[82:83], v[114:115]
	v_add_f32_e32 v108, 1.0, v110
	v_add_f32_e32 v109, 1.0, v111
	v_add_f32_e32 v110, 1.0, v116
	v_add_f32_e32 v111, 1.0, v117
	v_rcp_f32_e32 v108, v108
	v_rcp_f32_e32 v109, v109
	v_rcp_f32_e32 v110, v110
	v_rcp_f32_e32 v111, v111
	v_pk_mul_f32 v[80:81], v[80:81], v[112:113]
	v_pk_mul_f32 v[104:105], v[104:105], v[108:109]
	v_pk_mul_f32 v[106:107], v[106:107], v[110:111]
	s_nop 0
	v_pk_mul_f32 v[82:83], v[82:83], v[106:107]
	v_pk_mul_f32 v[80:81], v[80:81], v[104:105]
	s_nop 0
	v_cvt_pk_bf16_f32 v80, v80, v81
	v_cvt_pk_bf16_f32 v81, v82, v83
	v_cvt_pk_bf16_f32 v82, v100, v101
	v_mov_b64_e32 v[100:101], s[10:11]
	v_mad_i64_i32 v[100:101], s[12:13], v186, s66, v[100:101]
	v_lshl_add_u64 v[100:101], v[174:175], 1, v[100:101]
	v_cvt_pk_bf16_f32 v83, v102, v103
	global_store_dwordx4 v[100:101], v[80:83], off
	s_add_i32 s12, s60, 2
	s_ashr_i32 s13, s12, 31
	v_fmamk_f32 v80, v189, 0x3a000000, v215
	v_rsq_f32_e32 v106, v80
	s_lshl_b64 s[60:61], s[12:13], 1
	v_lshl_add_u64 v[80:81], s[60:61], 0, v[184:185]
	v_mad_u64_u32 v[82:83], s[12:13], v80, s65, v[174:175]
	v_pk_mul_f32 v[62:63], v[62:63], v[106:107] op_sel_hi:[1,0]
	v_pk_mul_f32 v[60:61], v[60:61], v[106:107] op_sel_hi:[1,0]
	s_nop 1
	v_mov_b32_dpp v108, v60 row_ror:1 row_mask:0xf bank_mask:0xf
	v_mov_b32_dpp v109, v60 row_ror:2 row_mask:0xf bank_mask:0xf
	v_mov_b32_dpp v110, v61 row_ror:1 row_mask:0xf bank_mask:0xf
	v_mov_b32_dpp v111, v61 row_ror:2 row_mask:0xf bank_mask:0xf
	v_mov_b32_dpp v112, v62 row_ror:1 row_mask:0xf bank_mask:0xf
	v_mov_b32_dpp v113, v62 row_ror:2 row_mask:0xf bank_mask:0xf
	v_mov_b32_dpp v114, v63 row_ror:1 row_mask:0xf bank_mask:0xf
	v_mov_b32_dpp v115, v63 row_ror:2 row_mask:0xf bank_mask:0xf
	v_mad_i32_i24 v83, v81, s65, v83
	v_pk_mul_f32 v[54:55], v[54:55], v[106:107] op_sel_hi:[1,0]
	v_pk_mul_f32 v[52:53], v[52:53], v[106:107] op_sel_hi:[1,0]
	v_lshlrev_b64 v[104:105], 2, v[82:83]
	s_and_saveexec_b64 s[12:13], s[8:9]
	s_cbranch_execz .LBB0_938
	v_lshl_add_u64 v[82:83], s[24:25], 0, v[104:105]
	v_lshl_add_u64 v[80:81], s[38:39], 0, v[104:105]
	global_store_dwordx4 v[82:83], v[60:63], off
	global_store_dwordx4 v[80:81], v[52:55], off
; __device__ __forceinline__ unsigned cvt_pk_bf16(float lo, float hi) { unsigned r; asm volatile("v_cvt_pk_bf16_f32 %0, %1, %2" : "=v"(r) : "v"(lo), "v"(hi)); return r; }
;     __device__ __forceinline__ void operator()(EPI_ARGS) const {
;     ...
;         for (int ai = 0; ai < 2; ++ai) {
;             const int blk = u.pm * 4 + ai * 2 + wr;
;             f32x4 q1[2], q2[2];
; #pragma unroll
;             for (int n = 0; n < 2; ++n) { q1[n] = (f32x4){0.f, 0.f, 0.f, 0.f}; q2[n] = (f32x4){0.f, 0.f, 0.f, 0.f}; }
; #pragma unroll
;             for (int m = 0; m < 4; ++m) {
;                 const int row = ROW_OF(ai, m);
;                 const float rs = __builtin_amdgcn_rsqf(rsv[ai][m] * (1.0f / D) + EPS);
;                 f32x4 o[2];
; #pragma unroll
;                 for (int n = 0; n < 2; ++n) {
;                     const f32x4 gv = acc[ai][0][m][n] * rs, vv = acc[ai][1][m][n] * rs;
;                     f32x4 r1, r2;
; #pragma unroll
;                     for (int j = 0; j < 4; ++j) { r1[j] = __shfl(gv[j], src1); r2[j] = __shfl(gv[j], src2); }
;                     f32x4 p1, p2;
; #pragma unroll
;                     for (int j = 0; j < 4; ++j) { p1[j] = fr >= 1 ? r1[j] : q1[n][j]; p2[j] = fr >= 2 ? r2[j] : q2[n][j]; }
;                     q1[n] = r1; q2[n] = r2;
;                     const f32x4 cv = bb[n] + w0[n] * p2 + w1[n] * p1 + w2[n] * gv;
;                     o[n] = gelu4(cv) * vv;
;                     if (m == 0 && fr < 2) { const size_t so = ((size_t)blk * 2 + fr) * FF + f0 + 4 * n; *(f32x4*)(headg + so) = gv; *(f32x4*)(headv + so) = vv; }
;                     if (m == 3 && fr >= 14) { const size_t so = ((size_t)blk * 2 + (fr - 14)) * FF + f0 + 4 * n; *(f32x4*)(tailg + so) = gv; }
;                 }
;                 if (!(m == 0 && fr < 2)) {
;                     u32x4 w; w.x = cvt_pk_bf16(o[0][0], o[0][1]); w.y = cvt_pk_bf16(o[0][2], o[0][3]); w.z = cvt_pk_bf16(o[1][0], o[1][1]); w.w = cvt_pk_bf16(o[1][2], o[1][3]);
;                     *(u32x4*)(act + (size_t)row * FF + f0) = w;
.LBB0_938:
	s_or_b64 exec, exec, s[12:13]
	v_mov_b32_e32 v107, v106
	v_mov_b32_e32 v116, v106
	v_mov_b32_e32 v117, v106
	v_pk_mul_f32 v[58:59], v[58:59], v[116:117]
	v_pk_mul_f32 v[56:57], v[56:57], v[106:107]
	s_nop 1
	v_mov_b32_dpp v80, v56 row_ror:1 row_mask:0xf bank_mask:0xf
	v_mov_b32_dpp v100, v56 row_ror:2 row_mask:0xf bank_mask:0xf
	v_mov_b32_dpp v81, v57 row_ror:1 row_mask:0xf bank_mask:0xf
	v_mov_b32_dpp v101, v57 row_ror:2 row_mask:0xf bank_mask:0xf
	v_mov_b32_dpp v82, v58 row_ror:1 row_mask:0xf bank_mask:0xf
	v_mov_b32_dpp v102, v58 row_ror:2 row_mask:0xf bank_mask:0xf
	v_mov_b32_dpp v83, v59 row_ror:1 row_mask:0xf bank_mask:0xf
	v_mov_b32_dpp v103, v59 row_ror:2 row_mask:0xf bank_mask:0xf
	v_pk_mul_f32 v[50:51], v[50:51], v[116:117]
	v_pk_mul_f32 v[48:49], v[48:49], v[106:107]
	s_and_saveexec_b64 s[8:9], s[6:7]
	s_xor_b64 s[6:7], exec, s[8:9]
	s_cbranch_execz .LBB0_940
	v_cndmask_b32_e64 v118, 0, v113, s[0:1]
	v_cndmask_b32_e64 v119, 0, v115, s[0:1]
	v_cndmask_b32_e64 v106, 0, v109, s[0:1]
	v_cndmask_b32_e64 v107, 0, v111, s[0:1]
	v_cndmask_b32_e32 v116, 0, v112, vcc
	v_cndmask_b32_e32 v117, 0, v114, vcc
	v_pk_fma_f32 v[118:119], v[74:75], v[118:119], v[78:79]
	v_cndmask_b32_e32 v104, 0, v108, vcc
	v_cndmask_b32_e32 v105, 0, v110, vcc
	v_pk_fma_f32 v[106:107], v[72:73], v[106:107], v[76:77]
	v_pk_fma_f32 v[116:117], v[66:67], v[116:117], v[118:119]
	v_pk_fma_f32 v[104:105], v[64:65], v[104:105], v[106:107]
	v_pk_fma_f32 v[62:63], v[70:71], v[62:63], v[116:117]
	v_pk_fma_f32 v[60:61], v[68:69], v[60:61], v[104:105]
	v_pk_mul_f32 v[104:105], v[62:63], v[62:63]
	v_pk_mul_f32 v[106:107], v[60:61], v[60:61]
	v_fmamk_f32 v104, v104, 0xbdd2d3e8, v216
	v_mul_f32_e32 v104, v62, v104
	v_fmamk_f32 v106, v106, 0xbdd2d3e8, v216
	v_fmamk_f32 v107, v107, 0xbdd2d3e8, v216
	v_exp_f32_e32 v116, v104
	v_fmamk_f32 v104, v105, 0xbdd2d3e8, v216
	v_mul_f32_e32 v106, v60, v106
	v_mul_f32_e32 v107, v61, v107
	v_mul_f32_e32 v104, v63, v104
	v_exp_f32_e32 v106, v106
	v_exp_f32_e32 v107, v107
	v_exp_f32_e32 v117, v104
	v_add_f32_e32 v104, 1.0, v106
	v_add_f32_e32 v105, 1.0, v107
	v_add_f32_e32 v106, 1.0, v116
	v_add_f32_e32 v107, 1.0, v117
	v_rcp_f32_e32 v104, v104
	v_rcp_f32_e32 v105, v105
	v_rcp_f32_e32 v106, v106
	v_rcp_f32_e32 v107, v107
	v_pk_mul_f32 v[60:61], v[60:61], v[104:105]
	s_nop 0
	v_pk_fma_f32 v[104:105], v[94:95], v[102:103], v[98:99]
	v_pk_mul_f32 v[62:63], v[62:63], v[106:107]
	v_pk_fma_f32 v[106:107], v[92:93], v[100:101], v[96:97]
	v_pk_fma_f32 v[104:105], v[86:87], v[82:83], v[104:105]
	v_pk_fma_f32 v[106:107], v[84:85], v[80:81], v[106:107]
	v_pk_fma_f32 v[58:59], v[90:91], v[58:59], v[104:105]
	v_pk_fma_f32 v[56:57], v[88:89], v[56:57], v[106:107]
	v_pk_mul_f32 v[104:105], v[58:59], v[58:59]
	v_pk_mul_f32 v[106:107], v[56:57], v[56:57]
	v_fmamk_f32 v104, v104, 0xbdd2d3e8, v216
	v_fmamk_f32 v106, v106, 0xbdd2d3e8, v216
	v_fmamk_f32 v107, v107, 0xbdd2d3e8, v216
	v_fmamk_f32 v105, v105, 0xbdd2d3e8, v216
	v_mul_f32_e32 v106, v56, v106
	v_mul_f32_e32 v107, v57, v107
	v_mul_f32_e32 v104, v58, v104
	v_mul_f32_e32 v105, v59, v105
	v_exp_f32_e32 v106, v106
	v_exp_f32_e32 v107, v107
	v_exp_f32_e32 v104, v104
	v_exp_f32_e32 v105, v105
	v_add_f32_e32 v106, 1.0, v106
	v_add_f32_e32 v107, 1.0, v107
	v_add_f32_e32 v104, 1.0, v104
	v_add_f32_e32 v105, 1.0, v105
	v_rcp_f32_e32 v106, v106
	v_rcp_f32_e32 v104, v104
	v_rcp_f32_e32 v105, v105
	v_rcp_f32_e32 v107, v107
	v_pk_mul_f32 v[52:53], v[52:53], v[60:61]
	v_pk_mul_f32 v[54:55], v[54:55], v[62:63]
	v_pk_mul_f32 v[58:59], v[58:59], v[104:105]
	v_pk_mul_f32 v[56:57], v[56:57], v[106:107]
	v_pk_mul_f32 v[58:59], v[50:51], v[58:59]
	v_pk_mul_f32 v[50:51], v[48:49], v[56:57]
	v_cvt_pk_bf16_f32 v48, v52, v53
	v_mov_b64_e32 v[52:53], s[10:11]
	v_mad_i64_i32 v[52:53], s[8:9], v182, s66, v[52:53]
	v_cvt_pk_bf16_f32 v49, v54, v55
	v_cvt_pk_bf16_f32 v50, v50, v51
	v_cvt_pk_bf16_f32 v51, v58, v59
	v_lshl_add_u64 v[52:53], v[174:175], 1, v[52:53]
	global_store_dwordx4 v[52:53], v[48:51], off

; __device__ __forceinline__ unsigned cvt_pk_bf16(float lo, float hi) { unsigned r; asm volatile("v_cvt_pk_bf16_f32 %0, %1, %2" : "=v"(r) : "v"(lo), "v"(hi)); return r; }
;     __device__ __forceinline__ void operator()(EPI_ARGS) const {
;     ...
;             for (int m = 0; m < 4; ++m) {
;                 const int row = ROW_OF(ai, m);
;                 const float rs = __builtin_amdgcn_rsqf(rsv[ai][m] * (1.0f / D) + EPS);
;                 f32x4 o[2];
; #pragma unroll
;                 for (int n = 0; n < 2; ++n) {
;                     const f32x4 gv = acc[ai][0][m][n] * rs, vv = acc[ai][1][m][n] * rs;
;                     f32x4 r1, r2;
; #pragma unroll
;                     for (int j = 0; j < 4; ++j) { r1[j] = __shfl(gv[j], src1); r2[j] = __shfl(gv[j], src2); }
;                     f32x4 p1, p2;
; #pragma unroll
;                     for (int j = 0; j < 4; ++j) { p1[j] = fr >= 1 ? r1[j] : q1[n][j]; p2[j] = fr >= 2 ? r2[j] : q2[n][j]; }
;                     q1[n] = r1; q2[n] = r2;
;                     const f32x4 cv = bb[n] + w0[n] * p2 + w1[n] * p1 + w2[n] * gv;
;                     o[n] = gelu4(cv) * vv;
;                     if (m == 0 && fr < 2) { const size_t so = ((size_t)blk * 2 + fr) * FF + f0 + 4 * n; *(f32x4*)(headg + so) = gv; *(f32x4*)(headv + so) = vv; }
;                     if (m == 3 && fr >= 14) { const size_t so = ((size_t)blk * 2 + (fr - 14)) * FF + f0 + 4 * n; *(f32x4*)(tailg + so) = gv; }
;                 }
;                 if (!(m == 0 && fr < 2)) {
;                     u32x4 w; w.x = cvt_pk_bf16(o[0][0], o[0][1]); w.y = cvt_pk_bf16(o[0][2], o[0][3]); w.z = cvt_pk_bf16(o[1][0], o[1][1]); w.w = cvt_pk_bf16(o[1][2], o[1][3]);
;                     *(u32x4*)(act + (size_t)row * FF + f0) = w;
.LBB0_942:
	s_or_b64 exec, exec, s[6:7]
	s_nop 0
	v_fmamk_f32 v48, v187, 0x3a000000, v215
	v_rsq_f32_e32 v52, v48
	v_lshl_add_u64 v[50:51], s[60:61], 0, v[168:169]
	v_mad_u64_u32 v[48:49], s[6:7], v50, s30, 0
	v_pk_mul_f32 v[46:47], v[46:47], v[52:53] op_sel_hi:[1,0]
	v_pk_mul_f32 v[44:45], v[44:45], v[52:53] op_sel_hi:[1,0]
	s_nop 1
	v_mov_b32_dpp v104, v46 row_ror:2 row_mask:0xf bank_mask:0xf
	v_mov_b32_dpp v106, v47 row_ror:2 row_mask:0xf bank_mask:0xf
	v_mov_b32_dpp v60, v44 row_ror:2 row_mask:0xf bank_mask:0xf
	v_mov_b32_dpp v62, v45 row_ror:2 row_mask:0xf bank_mask:0xf
	v_mov_b32_dpp v63, v46 row_ror:1 row_mask:0xf bank_mask:0xf
	v_mov_b32_dpp v105, v47 row_ror:1 row_mask:0xf bank_mask:0xf
	v_mov_b32_dpp v53, v44 row_ror:1 row_mask:0xf bank_mask:0xf
	v_mov_b32_dpp v61, v45 row_ror:1 row_mask:0xf bank_mask:0xf
	v_cndmask_b32_e64 v58, v113, v104, s[0:1]
	v_cndmask_b32_e64 v59, v115, v106, s[0:1]
	v_cndmask_b32_e64 v54, v109, v60, s[0:1]
	v_cndmask_b32_e64 v55, v111, v62, s[0:1]
	v_cndmask_b32_e32 v56, v112, v63, vcc
	v_cndmask_b32_e32 v57, v114, v105, vcc
	v_pk_fma_f32 v[58:59], v[74:75], v[58:59], v[78:79]
	v_mad_i32_i24 v49, v51, s30, v49
	v_cndmask_b32_e32 v50, v108, v53, vcc
	v_cndmask_b32_e32 v51, v110, v61, vcc
	v_pk_fma_f32 v[54:55], v[72:73], v[54:55], v[76:77]
	v_pk_fma_f32 v[56:57], v[66:67], v[56:57], v[58:59]
	v_pk_fma_f32 v[50:51], v[64:65], v[50:51], v[54:55]
	v_pk_fma_f32 v[46:47], v[70:71], v[46:47], v[56:57]
	v_pk_fma_f32 v[44:45], v[68:69], v[44:45], v[50:51]
	v_pk_mul_f32 v[50:51], v[46:47], v[46:47]
	v_pk_mul_f32 v[54:55], v[44:45], v[44:45]
	v_fmamk_f32 v50, v50, 0xbdd2d3e8, v216
	v_mul_f32_e32 v50, v46, v50
	v_fmamk_f32 v54, v54, 0xbdd2d3e8, v216
	v_fmamk_f32 v55, v55, 0xbdd2d3e8, v216
	v_exp_f32_e32 v56, v50
	v_fmamk_f32 v50, v51, 0xbdd2d3e8, v216
	v_mul_f32_e32 v54, v44, v54
	v_mul_f32_e32 v55, v45, v55
	v_mul_f32_e32 v50, v47, v50
	v_exp_f32_e32 v54, v54
	v_exp_f32_e32 v55, v55
	v_exp_f32_e32 v57, v50
	v_pk_mul_f32 v[42:43], v[42:43], v[52:53] op_sel_hi:[1,0]
	v_add_f32_e32 v50, 1.0, v54
	v_add_f32_e32 v51, 1.0, v55
	v_add_f32_e32 v54, 1.0, v56
	v_add_f32_e32 v55, 1.0, v57
	v_pk_mul_f32 v[40:41], v[40:41], v[52:53] op_sel_hi:[1,0]
	s_nop 1
	v_mov_b32_dpp v108, v42 row_ror:2 row_mask:0xf bank_mask:0xf
	v_mov_b32_dpp v110, v43 row_ror:2 row_mask:0xf bank_mask:0xf
	v_rcp_f32_e32 v54, v54
	v_rcp_f32_e32 v55, v55
	s_nop 1
	v_mov_b32_dpp v57, v40 row_ror:2 row_mask:0xf bank_mask:0xf
	v_mov_b32_dpp v59, v41 row_ror:2 row_mask:0xf bank_mask:0xf
	v_mov_b32_dpp v107, v42 row_ror:1 row_mask:0xf bank_mask:0xf
	v_mov_b32_dpp v109, v43 row_ror:1 row_mask:0xf bank_mask:0xf
	v_rcp_f32_e32 v50, v50
	v_rcp_f32_e32 v51, v51
	s_nop 1
	v_mov_b32_dpp v56, v40 row_ror:1 row_mask:0xf bank_mask:0xf
	v_mov_b32_dpp v58, v41 row_ror:1 row_mask:0xf bank_mask:0xf
	v_pk_mul_f32 v[38:39], v[38:39], v[52:53] op_sel_hi:[1,0]
	v_pk_mul_f32 v[46:47], v[46:47], v[54:55]
	v_cndmask_b32_e64 v54, v102, v108, s[0:1]
	v_cndmask_b32_e64 v55, v103, v110, s[0:1]
	v_pk_mul_f32 v[36:37], v[36:37], v[52:53] op_sel_hi:[1,0]
	v_pk_mul_f32 v[44:45], v[44:45], v[50:51]
	v_pk_mul_f32 v[38:39], v[38:39], v[46:47]
	v_cndmask_b32_e64 v46, v100, v57, s[0:1]
	v_cndmask_b32_e64 v47, v101, v59, s[0:1]
	v_cndmask_b32_e32 v50, v82, v107, vcc
	v_cndmask_b32_e32 v51, v83, v109, vcc
	v_pk_fma_f32 v[54:55], v[94:95], v[54:55], v[98:99]
	v_pk_mul_f32 v[36:37], v[36:37], v[44:45]
	v_cndmask_b32_e32 v44, v80, v56, vcc
	v_cndmask_b32_e32 v45, v81, v58, vcc
	v_pk_fma_f32 v[46:47], v[92:93], v[46:47], v[96:97]
	v_pk_fma_f32 v[50:51], v[86:87], v[50:51], v[54:55]
	v_pk_fma_f32 v[44:45], v[84:85], v[44:45], v[46:47]
	v_pk_fma_f32 v[42:43], v[90:91], v[42:43], v[50:51]
	v_pk_fma_f32 v[40:41], v[88:89], v[40:41], v[44:45]
	v_pk_mul_f32 v[44:45], v[42:43], v[42:43]
	v_pk_mul_f32 v[46:47], v[40:41], v[40:41]
	v_fmamk_f32 v44, v44, 0xbdd2d3e8, v216
	v_mul_f32_e32 v44, v42, v44
	v_fmamk_f32 v46, v46, 0xbdd2d3e8, v216
	v_fmamk_f32 v47, v47, 0xbdd2d3e8, v216
	v_exp_f32_e32 v50, v44
	v_fmamk_f32 v44, v45, 0xbdd2d3e8, v216
	v_mul_f32_e32 v46, v40, v46
	v_mul_f32_e32 v47, v41, v47
	v_mul_f32_e32 v44, v43, v44
	v_exp_f32_e32 v46, v46
	v_exp_f32_e32 v47, v47
	v_exp_f32_e32 v51, v44
	v_pk_mul_f32 v[32:33], v[32:33], v[52:53] op_sel_hi:[1,0]
	v_add_f32_e32 v44, 1.0, v46
	v_add_f32_e32 v45, 1.0, v47
	v_add_f32_e32 v46, 1.0, v50
	v_add_f32_e32 v47, 1.0, v51
	v_rcp_f32_e32 v44, v44
	v_rcp_f32_e32 v45, v45
	v_rcp_f32_e32 v46, v46
	v_rcp_f32_e32 v47, v47
	v_pk_mul_f32 v[34:35], v[34:35], v[52:53] op_sel_hi:[1,0]
	v_pk_mul_f32 v[40:41], v[40:41], v[44:45]
	v_pk_mul_f32 v[42:43], v[42:43], v[46:47]
	s_nop 0
	v_pk_mul_f32 v[42:43], v[34:35], v[42:43]
	v_pk_mul_f32 v[34:35], v[32:33], v[40:41]
	v_cvt_pk_bf16_f32 v32, v36, v37
	v_fmamk_f32 v36, v183, 0x3a000000, v215
	v_rsq_f32_e32 v44, v36
	v_cvt_pk_bf16_f32 v33, v38, v39
	v_cvt_pk_bf16_f32 v34, v34, v35
	v_cvt_pk_bf16_f32 v35, v42, v43
	v_mov_b64_e32 v[42:43], s[10:11]
	v_mad_i64_i32 v[36:37], s[6:7], v180, s66, v[42:43]
	v_lshl_add_u64 v[36:37], v[36:37], 0, v[128:129]
	global_store_dwordx4 v[36:37], v[32:35], off
	v_pk_mul_f32 v[36:37], v[30:31], v[44:45] op_sel_hi:[1,0]
	v_pk_mul_f32 v[38:39], v[28:29], v[44:45] op_sel_hi:[1,0]
	s_nop 1
	v_mov_b32_dpp v28, v38 row_ror:1 row_mask:0xf bank_mask:0xf
	v_mov_b32_dpp v34, v36 row_ror:2 row_mask:0xf bank_mask:0xf
; __device__ __forceinline__ unsigned cvt_pk_bf16(float lo, float hi) { unsigned r; asm volatile("v_cvt_pk_bf16_f32 %0, %1, %2" : "=v"(r) : "v"(lo), "v"(hi)); return r; }
;     __device__ __forceinline__ void operator()(EPI_ARGS) const {
;     ...
;             for (int m = 0; m < 4; ++m) {
;                 const int row = ROW_OF(ai, m);
;                 const float rs = __builtin_amdgcn_rsqf(rsv[ai][m] * (1.0f / D) + EPS);
;                 f32x4 o[2];
; #pragma unroll
;                 for (int n = 0; n < 2; ++n) {
;                     const f32x4 gv = acc[ai][0][m][n] * rs, vv = acc[ai][1][m][n] * rs;
;                     f32x4 r1, r2;
; #pragma unroll
;                     for (int j = 0; j < 4; ++j) { r1[j] = __shfl(gv[j], src1); r2[j] = __shfl(gv[j], src2); }
;                     f32x4 p1, p2;
; #pragma unroll
;                     for (int j = 0; j < 4; ++j) { p1[j] = fr >= 1 ? r1[j] : q1[n][j]; p2[j] = fr >= 2 ? r2[j] : q2[n][j]; }
;                     q1[n] = r1; q2[n] = r2;
;                     const f32x4 cv = bb[n] + w0[n] * p2 + w1[n] * p1 + w2[n] * gv;
;                     o[n] = gelu4(cv) * vv;
;                     if (m == 0 && fr < 2) { const size_t so = ((size_t)blk * 2 + fr) * FF + f0 + 4 * n; *(f32x4*)(headg + so) = gv; *(f32x4*)(headv + so) = vv; }
;                     if (m == 3 && fr >= 14) { const size_t so = ((size_t)blk * 2 + (fr - 14)) * FF + f0 + 4 * n; *(f32x4*)(tailg + so) = gv; }
;                 }
;                 if (!(m == 0 && fr < 2)) {
;                     u32x4 w; w.x = cvt_pk_bf16(o[0][0], o[0][1]); w.y = cvt_pk_bf16(o[0][2], o[0][3]); w.z = cvt_pk_bf16(o[1][0], o[1][1]); w.w = cvt_pk_bf16(o[1][2], o[1][3]);
;                     *(u32x4*)(act + (size_t)row * FF + f0) = w;
	v_mov_b32_dpp v35, v37 row_ror:2 row_mask:0xf bank_mask:0xf
	v_mov_b32_dpp v32, v38 row_ror:2 row_mask:0xf bank_mask:0xf
	v_mov_b32_dpp v33, v39 row_ror:2 row_mask:0xf bank_mask:0xf
	v_mov_b32_dpp v30, v36 row_ror:1 row_mask:0xf bank_mask:0xf
	v_mov_b32_dpp v31, v37 row_ror:1 row_mask:0xf bank_mask:0xf
	v_mov_b32_dpp v29, v39 row_ror:1 row_mask:0xf bank_mask:0xf
	v_cndmask_b32_e32 v40, v53, v28, vcc
	v_cndmask_b32_e64 v52, v104, v34, s[0:1]
	v_cndmask_b32_e64 v53, v106, v35, s[0:1]
	v_cndmask_b32_e64 v46, v60, v32, s[0:1]
	v_cndmask_b32_e64 v47, v62, v33, s[0:1]
	v_cndmask_b32_e32 v50, v63, v30, vcc
	v_cndmask_b32_e32 v51, v105, v31, vcc
	v_pk_fma_f32 v[52:53], v[74:75], v[52:53], v[78:79]
	v_cndmask_b32_e32 v41, v61, v29, vcc
	v_pk_fma_f32 v[46:47], v[72:73], v[46:47], v[76:77]
	v_pk_fma_f32 v[50:51], v[66:67], v[50:51], v[52:53]
	v_pk_fma_f32 v[40:41], v[64:65], v[40:41], v[46:47]
	v_pk_fma_f32 v[36:37], v[70:71], v[36:37], v[50:51]
	v_pk_fma_f32 v[38:39], v[68:69], v[38:39], v[40:41]
	v_pk_mul_f32 v[40:41], v[36:37], v[36:37]
	v_pk_mul_f32 v[46:47], v[38:39], v[38:39]
	v_fmamk_f32 v40, v40, 0xbdd2d3e8, v216
	v_fmamk_f32 v45, v46, 0xbdd2d3e8, v216
	v_mul_f32_e32 v40, v36, v40
	v_mul_f32_e32 v45, v38, v45
	v_fmamk_f32 v46, v47, 0xbdd2d3e8, v216
	v_exp_f32_e32 v47, v40
	v_fmamk_f32 v40, v41, 0xbdd2d3e8, v216
	v_exp_f32_e32 v45, v45
	v_mul_f32_e32 v46, v39, v46
	v_mul_f32_e32 v40, v37, v40
	v_exp_f32_e32 v46, v46
	v_exp_f32_e32 v50, v40
	v_add_f32_e32 v40, 1.0, v45
	v_add_f32_e32 v45, 1.0, v47
	v_add_f32_e32 v41, 1.0, v46
	v_rcp_f32_e32 v46, v45
	v_add_f32_e32 v45, 1.0, v50
	v_rcp_f32_e32 v47, v45
	v_rcp_f32_e32 v40, v40
	v_rcp_f32_e32 v41, v41
	v_pk_mul_f32 v[22:23], v[22:23], v[44:45] op_sel_hi:[1,0]
	v_pk_mul_f32 v[36:37], v[36:37], v[46:47]
	v_pk_mul_f32 v[52:53], v[24:25], v[44:45] op_sel_hi:[1,0]
	v_pk_mul_f32 v[46:47], v[22:23], v[36:37]
	v_pk_mul_f32 v[50:51], v[26:27], v[44:45] op_sel_hi:[1,0]
	s_nop 1
	v_mov_b32_dpp v22, v52 row_ror:1 row_mask:0xf bank_mask:0xf
	v_mov_b32_dpp v26, v52 row_ror:2 row_mask:0xf bank_mask:0xf
	v_mov_b32_dpp v36, v53 row_ror:2 row_mask:0xf bank_mask:0xf
	v_pk_mul_f32 v[20:21], v[20:21], v[44:45] op_sel_hi:[1,0]
	v_pk_mul_f32 v[38:39], v[38:39], v[40:41]
	s_nop 1
	v_mov_b32_dpp v23, v53 row_ror:1 row_mask:0xf bank_mask:0xf
	v_pk_mul_f32 v[20:21], v[20:21], v[38:39]
	s_nop 1
	v_mov_b32_dpp v38, v50 row_ror:2 row_mask:0xf bank_mask:0xf
	v_mov_b32_dpp v40, v51 row_ror:2 row_mask:0xf bank_mask:0xf
	v_mov_b32_dpp v24, v50 row_ror:1 row_mask:0xf bank_mask:0xf
	v_mov_b32_dpp v25, v51 row_ror:1 row_mask:0xf bank_mask:0xf
	v_cndmask_b32_e32 v54, v56, v22, vcc
	v_cndmask_b32_e64 v56, v57, v26, s[0:1]
	v_cndmask_b32_e64 v57, v59, v36, s[0:1]
	v_cndmask_b32_e32 v55, v58, v23, vcc
	v_pk_fma_f32 v[56:57], v[92:93], v[56:57], v[96:97]
	v_cndmask_b32_e64 v60, v108, v38, s[0:1]
	v_cndmask_b32_e64 v61, v110, v40, s[0:1]
	v_pk_fma_f32 v[54:55], v[84:85], v[54:55], v[56:57]
	v_cndmask_b32_e32 v58, v107, v24, vcc
	v_cndmask_b32_e32 v59, v109, v25, vcc
	v_pk_fma_f32 v[60:61], v[94:95], v[60:61], v[98:99]
	v_pk_fma_f32 v[52:53], v[88:89], v[52:53], v[54:55]
	v_pk_fma_f32 v[58:59], v[86:87], v[58:59], v[60:61]
	v_pk_mul_f32 v[56:57], v[52:53], v[52:53]
	v_pk_fma_f32 v[50:51], v[90:91], v[50:51], v[58:59]
	v_fmamk_f32 v27, v56, 0xbdd2d3e8, v216
	v_pk_mul_f32 v[54:55], v[50:51], v[50:51]
	v_mul_f32_e32 v27, v52, v27
	v_fmamk_f32 v37, v57, 0xbdd2d3e8, v216
	v_exp_f32_e32 v27, v27
	v_mul_f32_e32 v37, v53, v37
	v_fmamk_f32 v39, v54, 0xbdd2d3e8, v216
	v_exp_f32_e32 v37, v37
	v_mul_f32_e32 v39, v50, v39
	v_fmamk_f32 v41, v55, 0xbdd2d3e8, v216
	v_exp_f32_e32 v39, v39
	v_mul_f32_e32 v41, v51, v41
	v_exp_f32_e32 v41, v41
	v_add_f32_e32 v27, 1.0, v27
	v_rcp_f32_e32 v54, v27
	v_add_f32_e32 v27, 1.0, v37
	v_rcp_f32_e32 v55, v27
	v_add_f32_e32 v27, 1.0, v39
	v_rcp_f32_e32 v56, v27
	v_add_f32_e32 v27, 1.0, v41
	v_rcp_f32_e32 v57, v27
	v_pk_mul_f32 v[16:17], v[16:17], v[44:45] op_sel_hi:[1,0]
	v_pk_mul_f32 v[18:19], v[18:19], v[44:45] op_sel_hi:[1,0]
	v_pk_mul_f32 v[44:45], v[52:53], v[54:55]
	v_pk_mul_f32 v[50:51], v[50:51], v[56:57]
	v_pk_mul_f32 v[16:17], v[16:17], v[44:45]
	v_pk_mul_f32 v[50:51], v[18:19], v[50:51]
	v_cvt_pk_bf16_f32 v18, v20, v21
	v_cvt_pk_bf16_f32 v19, v46, v47
	v_cvt_pk_bf16_f32 v20, v16, v17
	v_fmamk_f32 v16, v181, 0x3a000000, v215
	v_rsq_f32_e32 v16, v16
	v_mad_i64_i32 v[46:47], s[6:7], v178, s66, v[42:43]
	v_lshl_add_u64 v[46:47], v[46:47], 0, v[128:129]
	v_pk_mul_f32 v[14:15], v[14:15], v[16:17] op_sel_hi:[1,0]
	v_pk_mul_f32 v[12:13], v[12:13], v[16:17] op_sel_hi:[1,0]
	s_nop 1
	v_mov_b32_dpp v27, v12 row_ror:1 row_mask:0xf bank_mask:0xf
	v_mov_b32_dpp v42, v12 row_ror:2 row_mask:0xf bank_mask:0xf
	v_mov_b32_dpp v37, v13 row_ror:1 row_mask:0xf bank_mask:0xf
	v_mov_b32_dpp v43, v13 row_ror:2 row_mask:0xf bank_mask:0xf
	v_mov_b32_dpp v39, v14 row_ror:1 row_mask:0xf bank_mask:0xf
	v_mov_b32_dpp v44, v14 row_ror:2 row_mask:0xf bank_mask:0xf
	v_mov_b32_dpp v41, v15 row_ror:1 row_mask:0xf bank_mask:0xf
	v_mov_b32_dpp v45, v15 row_ror:2 row_mask:0xf bank_mask:0xf
	v_cvt_pk_bf16_f32 v21, v50, v51
	global_store_dwordx4 v[46:47], v[18:21], off
	s_nop 1
	v_lshl_add_u64 v[18:19], s[40:41], 0, v[48:49]
	v_lshl_add_u64 v[20:21], v[174:175], 2, v[18:19]
	s_and_saveexec_b64 s[6:7], s[4:5]
	s_cbranch_execz .LBB0_944
	global_store_dwordx4 v[20:21], v[12:15], off

; __device__ __forceinline__ unsigned cvt_pk_bf16(float lo, float hi) { unsigned r; asm volatile("v_cvt_pk_bf16_f32 %0, %1, %2" : "=v"(r) : "v"(lo), "v"(hi)); return r; }
;     __device__ __forceinline__ void operator()(EPI_ARGS) const {
;     ...
;             for (int m = 0; m < 4; ++m) {
;                 const int row = ROW_OF(ai, m);
;                 const float rs = __builtin_amdgcn_rsqf(rsv[ai][m] * (1.0f / D) + EPS);
;                 f32x4 o[2];
; #pragma unroll
;                 for (int n = 0; n < 2; ++n) {
;                     const f32x4 gv = acc[ai][0][m][n] * rs, vv = acc[ai][1][m][n] * rs;
;                     f32x4 r1, r2;
; #pragma unroll
;                     for (int j = 0; j < 4; ++j) { r1[j] = __shfl(gv[j], src1); r2[j] = __shfl(gv[j], src2); }
;                     f32x4 p1, p2;
; #pragma unroll
;                     for (int j = 0; j < 4; ++j) { p1[j] = fr >= 1 ? r1[j] : q1[n][j]; p2[j] = fr >= 2 ? r2[j] : q2[n][j]; }
;                     q1[n] = r1; q2[n] = r2;
;                     const f32x4 cv = bb[n] + w0[n] * p2 + w1[n] * p1 + w2[n] * gv;
;                     o[n] = gelu4(cv) * vv;
;                     if (m == 0 && fr < 2) { const size_t so = ((size_t)blk * 2 + fr) * FF + f0 + 4 * n; *(f32x4*)(headg + so) = gv; *(f32x4*)(headv + so) = vv; }
;                     if (m == 3 && fr >= 14) { const size_t so = ((size_t)blk * 2 + (fr - 14)) * FF + f0 + 4 * n; *(f32x4*)(tailg + so) = gv; }
;                 }
;                 if (!(m == 0 && fr < 2)) {
;                     u32x4 w; w.x = cvt_pk_bf16(o[0][0], o[0][1]); w.y = cvt_pk_bf16(o[0][2], o[0][3]); w.z = cvt_pk_bf16(o[1][0], o[1][1]); w.w = cvt_pk_bf16(o[1][2], o[1][3]);
;                     *(u32x4*)(act + (size_t)row * FF + f0) = w;
.LBB0_946:
	s_or_b64 exec, exec, s[6:7]
	v_cndmask_b32_e64 v20, v26, v50, s[0:1]
	v_cndmask_b32_e64 v21, v36, v51, s[0:1]
	v_cndmask_b32_e64 v50, v38, v52, s[0:1]
	v_cndmask_b32_e64 v51, v40, v53, s[0:1]
	v_pk_fma_f32 v[50:51], v[94:95], v[50:51], v[98:99]
	v_pk_fma_f32 v[20:21], v[92:93], v[20:21], v[96:97]
	v_cndmask_b32_e32 v22, v22, v46, vcc
	v_cndmask_b32_e32 v23, v23, v47, vcc
	v_cndmask_b32_e32 v24, v24, v48, vcc
	v_cndmask_b32_e32 v25, v25, v49, vcc
	v_pk_fma_f32 v[20:21], v[84:85], v[22:23], v[20:21]
	v_pk_fma_f32 v[22:23], v[86:87], v[24:25], v[50:51]
	v_pk_fma_f32 v[8:9], v[88:89], v[8:9], v[20:21]
	v_pk_fma_f32 v[10:11], v[90:91], v[10:11], v[22:23]
	v_pk_mul_f32 v[20:21], v[8:9], v[8:9]
	v_pk_mul_f32 v[22:23], v[10:11], v[10:11]
	v_fmamk_f32 v20, v20, 0xbdd2d3e8, v216
	v_fmamk_f32 v21, v21, 0xbdd2d3e8, v216
	v_fmamk_f32 v22, v22, 0xbdd2d3e8, v216
	v_fmamk_f32 v23, v23, 0xbdd2d3e8, v216
	v_mul_f32_e32 v20, v8, v20
	v_mul_f32_e32 v21, v9, v21
	v_mul_f32_e32 v22, v10, v22
	v_mul_f32_e32 v23, v11, v23
	v_exp_f32_e32 v20, v20
	v_exp_f32_e32 v21, v21
	v_exp_f32_e32 v22, v22
	v_exp_f32_e32 v23, v23
	v_add_f32_e32 v20, 1.0, v20
	v_add_f32_e32 v21, 1.0, v21
	v_add_f32_e32 v22, 1.0, v22
	v_add_f32_e32 v23, 1.0, v23
	v_rcp_f32_e32 v20, v20
	v_rcp_f32_e32 v22, v22
	v_rcp_f32_e32 v23, v23
	v_rcp_f32_e32 v21, v21
	v_pk_mul_f32 v[6:7], v[6:7], v[18:19]
	v_pk_mul_f32 v[4:5], v[4:5], v[16:17]
	v_pk_mul_f32 v[10:11], v[10:11], v[22:23]
	v_pk_mul_f32 v[8:9], v[8:9], v[20:21]
	v_pk_mul_f32 v[6:7], v[6:7], v[10:11]
	v_pk_mul_f32 v[4:5], v[4:5], v[8:9]
	v_cndmask_b32_e64 v8, v32, v42, s[0:1]
	v_cndmask_b32_e64 v9, v33, v43, s[0:1]
	v_cndmask_b32_e64 v10, v34, v44, s[0:1]
	v_cndmask_b32_e64 v11, v35, v45, s[0:1]
	v_pk_fma_f32 v[10:11], v[74:75], v[10:11], v[78:79]
	v_pk_fma_f32 v[8:9], v[72:73], v[8:9], v[76:77]
	v_cndmask_b32_e32 v20, v28, v27, vcc
	v_cndmask_b32_e32 v21, v29, v37, vcc
	v_cndmask_b32_e32 v22, v30, v39, vcc
	v_cndmask_b32_e32 v23, v31, v41, vcc
	v_pk_fma_f32 v[8:9], v[64:65], v[20:21], v[8:9]
	v_pk_fma_f32 v[10:11], v[66:67], v[22:23], v[10:11]
	v_pk_fma_f32 v[8:9], v[68:69], v[12:13], v[8:9]
	v_pk_fma_f32 v[10:11], v[70:71], v[14:15], v[10:11]
	v_pk_mul_f32 v[12:13], v[8:9], v[8:9]
	v_pk_mul_f32 v[14:15], v[10:11], v[10:11]
	v_fmamk_f32 v12, v12, 0xbdd2d3e8, v216
	v_fmamk_f32 v13, v13, 0xbdd2d3e8, v216
	v_fmamk_f32 v14, v14, 0xbdd2d3e8, v216
	v_fmamk_f32 v15, v15, 0xbdd2d3e8, v216
	v_mul_f32_e32 v12, v8, v12
	v_mul_f32_e32 v13, v9, v13
	v_mul_f32_e32 v14, v10, v14
	v_mul_f32_e32 v15, v11, v15
	v_exp_f32_e32 v12, v12
	v_exp_f32_e32 v13, v13
	v_exp_f32_e32 v14, v14
	v_exp_f32_e32 v15, v15
	v_add_f32_e32 v12, 1.0, v12
	v_add_f32_e32 v13, 1.0, v13
	v_add_f32_e32 v14, 1.0, v14
	v_add_f32_e32 v15, 1.0, v15
	v_rcp_f32_e32 v12, v12
	v_rcp_f32_e32 v14, v14
	v_rcp_f32_e32 v15, v15
	v_rcp_f32_e32 v13, v13
	v_pk_mul_f32 v[2:3], v[2:3], v[18:19]
	v_pk_mul_f32 v[0:1], v[0:1], v[16:17]
	v_pk_mul_f32 v[10:11], v[10:11], v[14:15]
	v_pk_mul_f32 v[8:9], v[8:9], v[12:13]
	v_pk_mul_f32 v[2:3], v[2:3], v[10:11]
	v_pk_mul_f32 v[0:1], v[0:1], v[8:9]
	s_cmp_eq_u32 s31, 11
	v_cvt_pk_bf16_f32 v0, v0, v1
	v_cvt_pk_bf16_f32 v1, v2, v3
	v_cvt_pk_bf16_f32 v2, v4, v5
	v_mov_b64_e32 v[4:5], s[10:11]
	v_mad_i64_i32 v[4:5], s[0:1], v176, s66, v[4:5]
	v_lshl_add_u64 v[4:5], v[174:175], 1, v[4:5]
	s_mov_b64 s[0:1], -1
	v_cvt_pk_bf16_f32 v3, v6, v7
	global_store_dwordx4 v[4:5], v[0:3], off
	s_cbranch_scc1 .LBB0_919
	s_andn2_b64 vcc, exec, s[42:43]
	s_cbranch_vccnz .LBB0_918
	s_barrier
	s_branch .LBB0_918
